# instruction selection: 96 f32->bf16 RNE bit-trick sequences (v_bfe+v_add3+d16_hi store) in vgt_tile and G3 replaced by v_cvt_pk_bf16_f32 + plain 16-bit store
# baseline (speedup 1.0000x reference)
; DI bf16 f2bf(float f) { unsigned u = __float_as_uint(f); u += 0x7fffu + ((u >> 16) & 1u); return (bf16)(u >> 16); }
;   DI bf16* P() const { return (bf16*)(p.ws + WS_P); }
; DI float erf_as(float x) {
;   const float ax = fabsf(x);
;   const float t = __builtin_amdgcn_rcpf(1.f + 0.3275911f * ax);
;   const float poly = t * (0.254829592f + t * (-0.284496736f + t * (1.421413741f + t * (-1.453152027f + t * 1.061405429f))));
;   const float y = 1.f - poly * __builtin_amdgcn_exp2f(-1.4426950408889634f * ax * ax);
;   return copysignf(y, x);
; }
; DI float gelu(float x) { return 0.5f * x * (1.f + erf_as(x * 0.70710678118654752f)); }
; DI void vgt_tile(const Ctx& c, int ti, bf16* lds) {
;     ...
;   for (int rr = 0; rr < 32; ++rr) {
;     const int t = wave * 32 + rr;
;     const unsigned u = *(const unsigned*)(c.P() + (size_t)(row0 + t) * LDP + C_V + g * 128 + 2 * lane);
;     const float a = gelu(__uint_as_float(u << 16)), b = gelu(__uint_as_float(u & 0xffff0000u));
;     const float mean = wave_sum(a + b) * (1.f / 128.f);
;     const float da = a - mean, db = b - mean;
;     const float rstd = rsqrtf(wave_sum(da * da + db * db) * (1.f / 128.f) + LN_EPS);
;     lds[(2 * lane) * LDT + t] = f2bf(da * rstd);
;     lds[(2 * lane + 1) * LDT + t] = f2bf(db * rstd);
;   }
.LBB0_321:
	s_mov_b64 s[6:7], 0x1400
	global_load_dword v20, v[4:5], off
	v_lshl_add_u64 v[4:5], v[4:5], 0, s[6:7]
	global_load_dword v21, v[4:5], off
	v_lshl_add_u64 v[4:5], v[4:5], 0, s[6:7]
	global_load_dword v22, v[4:5], off
	v_lshl_add_u64 v[4:5], v[4:5], 0, s[6:7]
	global_load_dword v23, v[4:5], off
	v_lshl_add_u64 v[4:5], v[4:5], 0, s[6:7]
	global_load_dword v24, v[4:5], off
	v_lshl_add_u64 v[4:5], v[4:5], 0, s[6:7]
	global_load_dword v25, v[4:5], off
	v_lshl_add_u64 v[4:5], v[4:5], 0, s[6:7]
	global_load_dword v26, v[4:5], off
	v_lshl_add_u64 v[4:5], v[4:5], 0, s[6:7]
	global_load_dword v27, v[4:5], off
	v_lshl_add_u64 v[4:5], v[4:5], 0, s[6:7]
	global_load_dword v28, v[4:5], off
	v_lshl_add_u64 v[4:5], v[4:5], 0, s[6:7]
	global_load_dword v29, v[4:5], off
	v_lshl_add_u64 v[4:5], v[4:5], 0, s[6:7]
	global_load_dword v30, v[4:5], off
	v_lshl_add_u64 v[4:5], v[4:5], 0, s[6:7]
	global_load_dword v31, v[4:5], off
	v_lshl_add_u64 v[4:5], v[4:5], 0, s[6:7]
	global_load_dword v32, v[4:5], off
	v_lshl_add_u64 v[4:5], v[4:5], 0, s[6:7]
	global_load_dword v33, v[4:5], off
	v_lshl_add_u64 v[4:5], v[4:5], 0, s[6:7]
	global_load_dword v34, v[4:5], off
	v_lshl_add_u64 v[4:5], v[4:5], 0, s[6:7]
	global_load_dword v35, v[4:5], off
	v_lshl_add_u64 v[4:5], v[4:5], 0, s[6:7]
	global_load_dword v36, v[4:5], off
	v_lshl_add_u64 v[4:5], v[4:5], 0, s[6:7]
	global_load_dword v37, v[4:5], off
	v_lshl_add_u64 v[4:5], v[4:5], 0, s[6:7]
	global_load_dword v38, v[4:5], off
	v_lshl_add_u64 v[4:5], v[4:5], 0, s[6:7]
	global_load_dword v39, v[4:5], off
	v_lshl_add_u64 v[4:5], v[4:5], 0, s[6:7]
	global_load_dword v40, v[4:5], off
	v_lshl_add_u64 v[4:5], v[4:5], 0, s[6:7]
	global_load_dword v41, v[4:5], off
	v_lshl_add_u64 v[4:5], v[4:5], 0, s[6:7]
	global_load_dword v42, v[4:5], off
	v_lshl_add_u64 v[4:5], v[4:5], 0, s[6:7]
	global_load_dword v43, v[4:5], off
	v_lshl_add_u64 v[4:5], v[4:5], 0, s[6:7]
	global_load_dword v44, v[4:5], off
	v_lshl_add_u64 v[4:5], v[4:5], 0, s[6:7]
	global_load_dword v45, v[4:5], off
	v_lshl_add_u64 v[4:5], v[4:5], 0, s[6:7]
	global_load_dword v46, v[4:5], off
	v_lshl_add_u64 v[4:5], v[4:5], 0, s[6:7]
	global_load_dword v47, v[4:5], off
	v_lshl_add_u64 v[4:5], v[4:5], 0, s[6:7]
	global_load_dword v48, v[4:5], off
	v_lshl_add_u64 v[4:5], v[4:5], 0, s[6:7]
	global_load_dword v49, v[4:5], off
	v_lshl_add_u64 v[4:5], v[4:5], 0, s[6:7]
	global_load_dword v50, v[4:5], off
	v_lshl_add_u64 v[4:5], v[4:5], 0, s[6:7]
	global_load_dword v51, v[4:5], off
	v_lshl_add_u64 v[4:5], v[4:5], 0, s[6:7]
	s_waitcnt vmcnt(31)
	v_lshlrev_b32_e32 v8, 16, v20
	v_mul_f32_e32 v9, 0.5, v8
	v_mul_f32_e32 v8, 0x3f3504f3, v8
	v_fma_f32 v10, |v8|, s2, 1.0
	v_rcp_f32_e32 v10, v10
	v_and_b32_e32 v7, 0xffff0000, v20
	v_fmamk_f32 v11, v10, 0x3f87dc22, v176
	v_fmaak_f32 v11, v10, v11, 0x3fb5f0e3
	v_fmaak_f32 v11, v10, v11, 0xbe91a98e
	v_fmaak_f32 v11, v10, v11, 0x3e827906
	v_mul_f32_e32 v10, v10, v11
	v_mul_f32_e64 v11, |v8|, s3
	v_mul_f32_e64 v11, |v8|, v11
	v_exp_f32_e32 v11, v11
	s_nop 0
	v_fma_f32 v10, -v11, v10, 1.0
	v_bfi_b32 v8, s13, v10, v8
	v_mul_f32_e32 v10, 0.5, v7
	v_mul_f32_e32 v7, 0x3f3504f3, v7
	v_fma_f32 v11, |v7|, s2, 1.0
	v_rcp_f32_e32 v11, v11
	v_add_f32_e32 v8, 1.0, v8
	v_fmamk_f32 v12, v11, 0x3f87dc22, v176
	v_fmaak_f32 v12, v11, v12, 0x3fb5f0e3
	v_fmaak_f32 v12, v11, v12, 0xbe91a98e
	v_fmaak_f32 v12, v11, v12, 0x3e827906
	v_mul_f32_e32 v11, v11, v12
	v_mul_f32_e64 v12, |v7|, s3
	v_mul_f32_e64 v12, |v7|, v12
	v_exp_f32_e32 v12, v12
	s_nop 0
	v_fma_f32 v11, -v12, v11, 1.0
	v_bfi_b32 v7, s13, v11, v7
	v_add_f32_e32 v7, 1.0, v7
	v_mul_f32_e32 v11, v10, v7
	v_fmac_f32_e32 v11, v9, v8
	s_nop 1
	v_add_f32_dpp v11, v11, v11 row_ror:8 row_mask:0xf bank_mask:0xf bound_ctrl:1
	s_nop 1
	v_add_f32_dpp v11, v11, v11 row_ror:4 row_mask:0xf bank_mask:0xf bound_ctrl:1
	s_nop 1
	v_add_f32_dpp v11, v11, v11 row_ror:2 row_mask:0xf bank_mask:0xf bound_ctrl:1
	s_nop 1
	v_add_f32_dpp v11, v11, v11 row_ror:1 row_mask:0xf bank_mask:0xf bound_ctrl:1
	ds_bpermute_b32 v12, v3, v11
	s_waitcnt lgkmcnt(0)
	v_add_f32_e32 v11, v11, v12
	v_mov_b32_e32 v12, v11
	s_nop 1
	v_permlane32_swap_b32_e32 v11, v12
	v_add_f32_e32 v11, v11, v12
	v_mul_f32_e32 v11, 0x3c000000, v11
	v_fma_f32 v7, v10, v7, -v11
	v_fma_f32 v8, v9, v8, -v11
	v_mul_f32_e32 v9, v7, v7
	v_fmac_f32_e32 v9, v8, v8
	s_nop 1
	v_add_f32_dpp v9, v9, v9 row_ror:8 row_mask:0xf bank_mask:0xf bound_ctrl:1
	s_nop 1
	v_add_f32_dpp v9, v9, v9 row_ror:4 row_mask:0xf bank_mask:0xf bound_ctrl:1
	s_nop 1
	v_add_f32_dpp v9, v9, v9 row_ror:2 row_mask:0xf bank_mask:0xf bound_ctrl:1
	s_nop 1
	v_add_f32_dpp v9, v9, v9 row_ror:1 row_mask:0xf bank_mask:0xf bound_ctrl:1
	ds_bpermute_b32 v10, v3, v9
	s_waitcnt lgkmcnt(0)
	v_add_f32_e32 v9, v9, v10
	v_mov_b32_e32 v10, v9
	s_nop 1
	v_permlane32_swap_b32_e32 v9, v10
	v_add_f32_e32 v9, v9, v10
	v_fmamk_f32 v9, v9, 0x3c000000, v177
	v_cmp_gt_f32_e32 vcc, s16, v9
	v_mul_f32_e32 v10, 0x4b800000, v9
	s_nop 0
	v_cndmask_b32_e32 v9, v9, v10, vcc
	v_rsq_f32_e32 v9, v9
	s_nop 0
	v_mul_f32_e32 v10, 0x45800000, v9
	v_cndmask_b32_e32 v9, v9, v10, vcc
	v_mul_f32_e32 v8, v8, v9
	v_cvt_pk_bf16_f32 v8, v8, v8
	v_add_u32_e32 v10, s5, v6
	v_mul_f32_e32 v7, v7, v9
	ds_write_b16 v10, v8
	s_add_i32 s5, s5, 2
	v_cvt_pk_bf16_f32 v7, v7, v7
	ds_write_b16 v10, v7 offset:272
	s_waitcnt vmcnt(30)
; DI bf16 f2bf(float f) { unsigned u = __float_as_uint(f); u += 0x7fffu + ((u >> 16) & 1u); return (bf16)(u >> 16); }
;   DI bf16* P() const { return (bf16*)(p.ws + WS_P); }
; DI float erf_as(float x) {
;   const float ax = fabsf(x);
;   const float t = __builtin_amdgcn_rcpf(1.f + 0.3275911f * ax);
;   const float poly = t * (0.254829592f + t * (-0.284496736f + t * (1.421413741f + t * (-1.453152027f + t * 1.061405429f))));
;   const float y = 1.f - poly * __builtin_amdgcn_exp2f(-1.4426950408889634f * ax * ax);
;   return copysignf(y, x);
; }
; DI float gelu(float x) { return 0.5f * x * (1.f + erf_as(x * 0.70710678118654752f)); }
; DI void vgt_tile(const Ctx& c, int ti, bf16* lds) {
;     ...
;   for (int rr = 0; rr < 32; ++rr) {
;     const int t = wave * 32 + rr;
;     const unsigned u = *(const unsigned*)(c.P() + (size_t)(row0 + t) * LDP + C_V + g * 128 + 2 * lane);
;     const float a = gelu(__uint_as_float(u << 16)), b = gelu(__uint_as_float(u & 0xffff0000u));
;     const float mean = wave_sum(a + b) * (1.f / 128.f);
;     const float da = a - mean, db = b - mean;
;     const float rstd = rsqrtf(wave_sum(da * da + db * db) * (1.f / 128.f) + LN_EPS);
;     lds[(2 * lane) * LDT + t] = f2bf(da * rstd);
;     lds[(2 * lane + 1) * LDT + t] = f2bf(db * rstd);
;   }
	v_lshlrev_b32_e32 v8, 16, v21
	v_mul_f32_e32 v9, 0.5, v8
	v_mul_f32_e32 v8, 0x3f3504f3, v8
	v_fma_f32 v10, |v8|, s2, 1.0
	v_rcp_f32_e32 v10, v10
	v_and_b32_e32 v7, 0xffff0000, v21
	v_fmamk_f32 v11, v10, 0x3f87dc22, v176
	v_fmaak_f32 v11, v10, v11, 0x3fb5f0e3
	v_fmaak_f32 v11, v10, v11, 0xbe91a98e
	v_fmaak_f32 v11, v10, v11, 0x3e827906
	v_mul_f32_e32 v10, v10, v11
	v_mul_f32_e64 v11, |v8|, s3
	v_mul_f32_e64 v11, |v8|, v11
	v_exp_f32_e32 v11, v11
	s_nop 0
	v_fma_f32 v10, -v11, v10, 1.0
	v_bfi_b32 v8, s13, v10, v8
	v_mul_f32_e32 v10, 0.5, v7
	v_mul_f32_e32 v7, 0x3f3504f3, v7
	v_fma_f32 v11, |v7|, s2, 1.0
	v_rcp_f32_e32 v11, v11
	v_add_f32_e32 v8, 1.0, v8
	v_fmamk_f32 v12, v11, 0x3f87dc22, v176
	v_fmaak_f32 v12, v11, v12, 0x3fb5f0e3
	v_fmaak_f32 v12, v11, v12, 0xbe91a98e
	v_fmaak_f32 v12, v11, v12, 0x3e827906
	v_mul_f32_e32 v11, v11, v12
	v_mul_f32_e64 v12, |v7|, s3
	v_mul_f32_e64 v12, |v7|, v12
	v_exp_f32_e32 v12, v12
	s_nop 0
	v_fma_f32 v11, -v12, v11, 1.0
	v_bfi_b32 v7, s13, v11, v7
	v_add_f32_e32 v7, 1.0, v7
	v_mul_f32_e32 v11, v10, v7
	v_fmac_f32_e32 v11, v9, v8
	s_nop 1
	v_add_f32_dpp v11, v11, v11 row_ror:8 row_mask:0xf bank_mask:0xf bound_ctrl:1
	s_nop 1
	v_add_f32_dpp v11, v11, v11 row_ror:4 row_mask:0xf bank_mask:0xf bound_ctrl:1
	s_nop 1
	v_add_f32_dpp v11, v11, v11 row_ror:2 row_mask:0xf bank_mask:0xf bound_ctrl:1
	s_nop 1
	v_add_f32_dpp v11, v11, v11 row_ror:1 row_mask:0xf bank_mask:0xf bound_ctrl:1
	ds_bpermute_b32 v12, v3, v11
	s_waitcnt lgkmcnt(0)
	v_add_f32_e32 v11, v11, v12
	v_mov_b32_e32 v12, v11
	s_nop 1
	v_permlane32_swap_b32_e32 v11, v12
	v_add_f32_e32 v11, v11, v12
	v_mul_f32_e32 v11, 0x3c000000, v11
	v_fma_f32 v7, v10, v7, -v11
	v_fma_f32 v8, v9, v8, -v11
	v_mul_f32_e32 v9, v7, v7
	v_fmac_f32_e32 v9, v8, v8
	s_nop 1
	v_add_f32_dpp v9, v9, v9 row_ror:8 row_mask:0xf bank_mask:0xf bound_ctrl:1
	s_nop 1
	v_add_f32_dpp v9, v9, v9 row_ror:4 row_mask:0xf bank_mask:0xf bound_ctrl:1
	s_nop 1
	v_add_f32_dpp v9, v9, v9 row_ror:2 row_mask:0xf bank_mask:0xf bound_ctrl:1
	s_nop 1
	v_add_f32_dpp v9, v9, v9 row_ror:1 row_mask:0xf bank_mask:0xf bound_ctrl:1
	ds_bpermute_b32 v10, v3, v9
	s_waitcnt lgkmcnt(0)
	v_add_f32_e32 v9, v9, v10
	v_mov_b32_e32 v10, v9
	s_nop 1
	v_permlane32_swap_b32_e32 v9, v10
	v_add_f32_e32 v9, v9, v10
	v_fmamk_f32 v9, v9, 0x3c000000, v177
	v_cmp_gt_f32_e32 vcc, s16, v9
	v_mul_f32_e32 v10, 0x4b800000, v9
	s_nop 0
	v_cndmask_b32_e32 v9, v9, v10, vcc
	v_rsq_f32_e32 v9, v9
	s_nop 0
	v_mul_f32_e32 v10, 0x45800000, v9
	v_cndmask_b32_e32 v9, v9, v10, vcc
	v_mul_f32_e32 v8, v8, v9
	v_cvt_pk_bf16_f32 v8, v8, v8
	v_add_u32_e32 v10, s5, v6
	v_mul_f32_e32 v7, v7, v9
	ds_write_b16 v10, v8
	s_add_i32 s5, s5, 2
	v_cvt_pk_bf16_f32 v7, v7, v7
	ds_write_b16 v10, v7 offset:272
	s_waitcnt vmcnt(29)
	v_lshlrev_b32_e32 v8, 16, v22
	v_mul_f32_e32 v9, 0.5, v8
	v_mul_f32_e32 v8, 0x3f3504f3, v8
	v_fma_f32 v10, |v8|, s2, 1.0
	v_rcp_f32_e32 v10, v10
	v_and_b32_e32 v7, 0xffff0000, v22
	v_fmamk_f32 v11, v10, 0x3f87dc22, v176
	v_fmaak_f32 v11, v10, v11, 0x3fb5f0e3
	v_fmaak_f32 v11, v10, v11, 0xbe91a98e
	v_fmaak_f32 v11, v10, v11, 0x3e827906
	v_mul_f32_e32 v10, v10, v11
	v_mul_f32_e64 v11, |v8|, s3
	v_mul_f32_e64 v11, |v8|, v11
	v_exp_f32_e32 v11, v11
	s_nop 0
	v_fma_f32 v10, -v11, v10, 1.0
	v_bfi_b32 v8, s13, v10, v8
	v_mul_f32_e32 v10, 0.5, v7
	v_mul_f32_e32 v7, 0x3f3504f3, v7
	v_fma_f32 v11, |v7|, s2, 1.0
	v_rcp_f32_e32 v11, v11
	v_add_f32_e32 v8, 1.0, v8
	v_fmamk_f32 v12, v11, 0x3f87dc22, v176
	v_fmaak_f32 v12, v11, v12, 0x3fb5f0e3
	v_fmaak_f32 v12, v11, v12, 0xbe91a98e
	v_fmaak_f32 v12, v11, v12, 0x3e827906
	v_mul_f32_e32 v11, v11, v12
	v_mul_f32_e64 v12, |v7|, s3
	v_mul_f32_e64 v12, |v7|, v12
	v_exp_f32_e32 v12, v12
	s_nop 0
	v_fma_f32 v11, -v12, v11, 1.0
	v_bfi_b32 v7, s13, v11, v7
	v_add_f32_e32 v7, 1.0, v7
	v_mul_f32_e32 v11, v10, v7
	v_fmac_f32_e32 v11, v9, v8
	s_nop 1
	v_add_f32_dpp v11, v11, v11 row_ror:8 row_mask:0xf bank_mask:0xf bound_ctrl:1
	s_nop 1
	v_add_f32_dpp v11, v11, v11 row_ror:4 row_mask:0xf bank_mask:0xf bound_ctrl:1
	s_nop 1
	v_add_f32_dpp v11, v11, v11 row_ror:2 row_mask:0xf bank_mask:0xf bound_ctrl:1
	s_nop 1
	v_add_f32_dpp v11, v11, v11 row_ror:1 row_mask:0xf bank_mask:0xf bound_ctrl:1
	ds_bpermute_b32 v12, v3, v11
	s_waitcnt lgkmcnt(0)
	v_add_f32_e32 v11, v11, v12
	v_mov_b32_e32 v12, v11
	s_nop 1
	v_permlane32_swap_b32_e32 v11, v12
	v_add_f32_e32 v11, v11, v12
	v_mul_f32_e32 v11, 0x3c000000, v11
	v_fma_f32 v7, v10, v7, -v11
	v_fma_f32 v8, v9, v8, -v11
	v_mul_f32_e32 v9, v7, v7
	v_fmac_f32_e32 v9, v8, v8
	s_nop 1
	v_add_f32_dpp v9, v9, v9 row_ror:8 row_mask:0xf bank_mask:0xf bound_ctrl:1
	s_nop 1
	v_add_f32_dpp v9, v9, v9 row_ror:4 row_mask:0xf bank_mask:0xf bound_ctrl:1
	s_nop 1
	v_add_f32_dpp v9, v9, v9 row_ror:2 row_mask:0xf bank_mask:0xf bound_ctrl:1
	s_nop 1
	v_add_f32_dpp v9, v9, v9 row_ror:1 row_mask:0xf bank_mask:0xf bound_ctrl:1
	ds_bpermute_b32 v10, v3, v9
	s_waitcnt lgkmcnt(0)
	v_add_f32_e32 v9, v9, v10
	v_mov_b32_e32 v10, v9
	s_nop 1
	v_permlane32_swap_b32_e32 v9, v10
	v_add_f32_e32 v9, v9, v10
	v_fmamk_f32 v9, v9, 0x3c000000, v177
	v_cmp_gt_f32_e32 vcc, s16, v9
	v_mul_f32_e32 v10, 0x4b800000, v9
	s_nop 0
	v_cndmask_b32_e32 v9, v9, v10, vcc
	v_rsq_f32_e32 v9, v9
	s_nop 0
	v_mul_f32_e32 v10, 0x45800000, v9
	v_cndmask_b32_e32 v9, v9, v10, vcc
	v_mul_f32_e32 v8, v8, v9
	v_cvt_pk_bf16_f32 v8, v8, v8
	v_add_u32_e32 v10, s5, v6
	v_mul_f32_e32 v7, v7, v9
	ds_write_b16 v10, v8
	s_add_i32 s5, s5, 2
	v_cvt_pk_bf16_f32 v7, v7, v7
	ds_write_b16 v10, v7 offset:272
	s_waitcnt vmcnt(28)
; DI bf16 f2bf(float f) { unsigned u = __float_as_uint(f); u += 0x7fffu + ((u >> 16) & 1u); return (bf16)(u >> 16); }
;   DI bf16* P() const { return (bf16*)(p.ws + WS_P); }
; DI float erf_as(float x) {
;   const float ax = fabsf(x);
;   const float t = __builtin_amdgcn_rcpf(1.f + 0.3275911f * ax);
;   const float poly = t * (0.254829592f + t * (-0.284496736f + t * (1.421413741f + t * (-1.453152027f + t * 1.061405429f))));
;   const float y = 1.f - poly * __builtin_amdgcn_exp2f(-1.4426950408889634f * ax * ax);
;   return copysignf(y, x);
; }
; DI float gelu(float x) { return 0.5f * x * (1.f + erf_as(x * 0.70710678118654752f)); }
; DI void vgt_tile(const Ctx& c, int ti, bf16* lds) {
;     ...
;   for (int rr = 0; rr < 32; ++rr) {
;     const int t = wave * 32 + rr;
;     const unsigned u = *(const unsigned*)(c.P() + (size_t)(row0 + t) * LDP + C_V + g * 128 + 2 * lane);
;     const float a = gelu(__uint_as_float(u << 16)), b = gelu(__uint_as_float(u & 0xffff0000u));
;     const float mean = wave_sum(a + b) * (1.f / 128.f);
;     const float da = a - mean, db = b - mean;
;     const float rstd = rsqrtf(wave_sum(da * da + db * db) * (1.f / 128.f) + LN_EPS);
;     lds[(2 * lane) * LDT + t] = f2bf(da * rstd);
;     lds[(2 * lane + 1) * LDT + t] = f2bf(db * rstd);
;   }
	v_lshlrev_b32_e32 v8, 16, v23
	v_mul_f32_e32 v9, 0.5, v8
	v_mul_f32_e32 v8, 0x3f3504f3, v8
	v_fma_f32 v10, |v8|, s2, 1.0
	v_rcp_f32_e32 v10, v10
	v_and_b32_e32 v7, 0xffff0000, v23
	v_fmamk_f32 v11, v10, 0x3f87dc22, v176
	v_fmaak_f32 v11, v10, v11, 0x3fb5f0e3
	v_fmaak_f32 v11, v10, v11, 0xbe91a98e
	v_fmaak_f32 v11, v10, v11, 0x3e827906
	v_mul_f32_e32 v10, v10, v11
	v_mul_f32_e64 v11, |v8|, s3
	v_mul_f32_e64 v11, |v8|, v11
	v_exp_f32_e32 v11, v11
	s_nop 0
	v_fma_f32 v10, -v11, v10, 1.0
	v_bfi_b32 v8, s13, v10, v8
	v_mul_f32_e32 v10, 0.5, v7
	v_mul_f32_e32 v7, 0x3f3504f3, v7
	v_fma_f32 v11, |v7|, s2, 1.0
	v_rcp_f32_e32 v11, v11
	v_add_f32_e32 v8, 1.0, v8
	v_fmamk_f32 v12, v11, 0x3f87dc22, v176
	v_fmaak_f32 v12, v11, v12, 0x3fb5f0e3
	v_fmaak_f32 v12, v11, v12, 0xbe91a98e
	v_fmaak_f32 v12, v11, v12, 0x3e827906
	v_mul_f32_e32 v11, v11, v12
	v_mul_f32_e64 v12, |v7|, s3
	v_mul_f32_e64 v12, |v7|, v12
	v_exp_f32_e32 v12, v12
	s_nop 0
	v_fma_f32 v11, -v12, v11, 1.0
	v_bfi_b32 v7, s13, v11, v7
	v_add_f32_e32 v7, 1.0, v7
	v_mul_f32_e32 v11, v10, v7
	v_fmac_f32_e32 v11, v9, v8
	s_nop 1
	v_add_f32_dpp v11, v11, v11 row_ror:8 row_mask:0xf bank_mask:0xf bound_ctrl:1
	s_nop 1
	v_add_f32_dpp v11, v11, v11 row_ror:4 row_mask:0xf bank_mask:0xf bound_ctrl:1
	s_nop 1
	v_add_f32_dpp v11, v11, v11 row_ror:2 row_mask:0xf bank_mask:0xf bound_ctrl:1
	s_nop 1
	v_add_f32_dpp v11, v11, v11 row_ror:1 row_mask:0xf bank_mask:0xf bound_ctrl:1
	ds_bpermute_b32 v12, v3, v11
	s_waitcnt lgkmcnt(0)
	v_add_f32_e32 v11, v11, v12
	v_mov_b32_e32 v12, v11
	s_nop 1
	v_permlane32_swap_b32_e32 v11, v12
	v_add_f32_e32 v11, v11, v12
	v_mul_f32_e32 v11, 0x3c000000, v11
	v_fma_f32 v7, v10, v7, -v11
	v_fma_f32 v8, v9, v8, -v11
	v_mul_f32_e32 v9, v7, v7
	v_fmac_f32_e32 v9, v8, v8
	s_nop 1
	v_add_f32_dpp v9, v9, v9 row_ror:8 row_mask:0xf bank_mask:0xf bound_ctrl:1
	s_nop 1
	v_add_f32_dpp v9, v9, v9 row_ror:4 row_mask:0xf bank_mask:0xf bound_ctrl:1
	s_nop 1
	v_add_f32_dpp v9, v9, v9 row_ror:2 row_mask:0xf bank_mask:0xf bound_ctrl:1
	s_nop 1
	v_add_f32_dpp v9, v9, v9 row_ror:1 row_mask:0xf bank_mask:0xf bound_ctrl:1
	ds_bpermute_b32 v10, v3, v9
	s_waitcnt lgkmcnt(0)
	v_add_f32_e32 v9, v9, v10
	v_mov_b32_e32 v10, v9
	s_nop 1
	v_permlane32_swap_b32_e32 v9, v10
	v_add_f32_e32 v9, v9, v10
	v_fmamk_f32 v9, v9, 0x3c000000, v177
	v_cmp_gt_f32_e32 vcc, s16, v9
	v_mul_f32_e32 v10, 0x4b800000, v9
	s_nop 0
	v_cndmask_b32_e32 v9, v9, v10, vcc
	v_rsq_f32_e32 v9, v9
	s_nop 0
	v_mul_f32_e32 v10, 0x45800000, v9
	v_cndmask_b32_e32 v9, v9, v10, vcc
	v_mul_f32_e32 v8, v8, v9
	v_cvt_pk_bf16_f32 v8, v8, v8
	v_add_u32_e32 v10, s5, v6
	v_mul_f32_e32 v7, v7, v9
	ds_write_b16 v10, v8
	s_add_i32 s5, s5, 2
	v_cvt_pk_bf16_f32 v7, v7, v7
	ds_write_b16 v10, v7 offset:272
	s_waitcnt vmcnt(27)
	v_lshlrev_b32_e32 v8, 16, v24
	v_mul_f32_e32 v9, 0.5, v8
	v_mul_f32_e32 v8, 0x3f3504f3, v8
	v_fma_f32 v10, |v8|, s2, 1.0
	v_rcp_f32_e32 v10, v10
	v_and_b32_e32 v7, 0xffff0000, v24
	v_fmamk_f32 v11, v10, 0x3f87dc22, v176
	v_fmaak_f32 v11, v10, v11, 0x3fb5f0e3
	v_fmaak_f32 v11, v10, v11, 0xbe91a98e
	v_fmaak_f32 v11, v10, v11, 0x3e827906
	v_mul_f32_e32 v10, v10, v11
	v_mul_f32_e64 v11, |v8|, s3
	v_mul_f32_e64 v11, |v8|, v11
	v_exp_f32_e32 v11, v11
	s_nop 0
	v_fma_f32 v10, -v11, v10, 1.0
	v_bfi_b32 v8, s13, v10, v8
	v_mul_f32_e32 v10, 0.5, v7
	v_mul_f32_e32 v7, 0x3f3504f3, v7
	v_fma_f32 v11, |v7|, s2, 1.0
	v_rcp_f32_e32 v11, v11
	v_add_f32_e32 v8, 1.0, v8
	v_fmamk_f32 v12, v11, 0x3f87dc22, v176
	v_fmaak_f32 v12, v11, v12, 0x3fb5f0e3
	v_fmaak_f32 v12, v11, v12, 0xbe91a98e
	v_fmaak_f32 v12, v11, v12, 0x3e827906
	v_mul_f32_e32 v11, v11, v12
	v_mul_f32_e64 v12, |v7|, s3
	v_mul_f32_e64 v12, |v7|, v12
	v_exp_f32_e32 v12, v12
	s_nop 0
	v_fma_f32 v11, -v12, v11, 1.0
	v_bfi_b32 v7, s13, v11, v7
	v_add_f32_e32 v7, 1.0, v7
	v_mul_f32_e32 v11, v10, v7
	v_fmac_f32_e32 v11, v9, v8
	s_nop 1
	v_add_f32_dpp v11, v11, v11 row_ror:8 row_mask:0xf bank_mask:0xf bound_ctrl:1
	s_nop 1
	v_add_f32_dpp v11, v11, v11 row_ror:4 row_mask:0xf bank_mask:0xf bound_ctrl:1
	s_nop 1
	v_add_f32_dpp v11, v11, v11 row_ror:2 row_mask:0xf bank_mask:0xf bound_ctrl:1
	s_nop 1
	v_add_f32_dpp v11, v11, v11 row_ror:1 row_mask:0xf bank_mask:0xf bound_ctrl:1
	ds_bpermute_b32 v12, v3, v11
	s_waitcnt lgkmcnt(0)
	v_add_f32_e32 v11, v11, v12
	v_mov_b32_e32 v12, v11
	s_nop 1
	v_permlane32_swap_b32_e32 v11, v12
	v_add_f32_e32 v11, v11, v12
	v_mul_f32_e32 v11, 0x3c000000, v11
	v_fma_f32 v7, v10, v7, -v11
	v_fma_f32 v8, v9, v8, -v11
	v_mul_f32_e32 v9, v7, v7
	v_fmac_f32_e32 v9, v8, v8
	s_nop 1
	v_add_f32_dpp v9, v9, v9 row_ror:8 row_mask:0xf bank_mask:0xf bound_ctrl:1
	s_nop 1
	v_add_f32_dpp v9, v9, v9 row_ror:4 row_mask:0xf bank_mask:0xf bound_ctrl:1
	s_nop 1
	v_add_f32_dpp v9, v9, v9 row_ror:2 row_mask:0xf bank_mask:0xf bound_ctrl:1
	s_nop 1
	v_add_f32_dpp v9, v9, v9 row_ror:1 row_mask:0xf bank_mask:0xf bound_ctrl:1
	ds_bpermute_b32 v10, v3, v9
	s_waitcnt lgkmcnt(0)
	v_add_f32_e32 v9, v9, v10
	v_mov_b32_e32 v10, v9
	s_nop 1
	v_permlane32_swap_b32_e32 v9, v10
	v_add_f32_e32 v9, v9, v10
	v_fmamk_f32 v9, v9, 0x3c000000, v177
	v_cmp_gt_f32_e32 vcc, s16, v9
	v_mul_f32_e32 v10, 0x4b800000, v9
	s_nop 0
	v_cndmask_b32_e32 v9, v9, v10, vcc
	v_rsq_f32_e32 v9, v9
	s_nop 0
	v_mul_f32_e32 v10, 0x45800000, v9
	v_cndmask_b32_e32 v9, v9, v10, vcc
	v_mul_f32_e32 v8, v8, v9
	v_cvt_pk_bf16_f32 v8, v8, v8
	v_add_u32_e32 v10, s5, v6
	v_mul_f32_e32 v7, v7, v9
	ds_write_b16 v10, v8
	s_add_i32 s5, s5, 2
	v_cvt_pk_bf16_f32 v7, v7, v7
	ds_write_b16 v10, v7 offset:272
	s_waitcnt vmcnt(26)
; DI bf16 f2bf(float f) { unsigned u = __float_as_uint(f); u += 0x7fffu + ((u >> 16) & 1u); return (bf16)(u >> 16); }
;   DI bf16* P() const { return (bf16*)(p.ws + WS_P); }
; DI float erf_as(float x) {
;   const float ax = fabsf(x);
;   const float t = __builtin_amdgcn_rcpf(1.f + 0.3275911f * ax);
;   const float poly = t * (0.254829592f + t * (-0.284496736f + t * (1.421413741f + t * (-1.453152027f + t * 1.061405429f))));
;   const float y = 1.f - poly * __builtin_amdgcn_exp2f(-1.4426950408889634f * ax * ax);
;   return copysignf(y, x);
; }
; DI float gelu(float x) { return 0.5f * x * (1.f + erf_as(x * 0.70710678118654752f)); }
; DI float logsigmoid(float z) { return fminf(z, 0.f) - log1pf(__expf(-fabsf(z))); }
; DI float logsigmoid_fast(float z) { return -0.6931471805599453f * __builtin_amdgcn_logf(1.f + __builtin_amdgcn_exp2f(-1.4426950408889634f * fmaxf(z, -80.f))); }
; template <int CTRL> DI float dpp_add(float v) { return v + __builtin_bit_cast(float, __builtin_amdgcn_update_dpp(0, __builtin_bit_cast(int, v), CTRL, 0xf, 0xf, false)); }
; DI float wave_sum(float v) {
;   v = dpp_add<0x128>(v); v = dpp_add<0x124>(v); v = dpp_add<0x122>(v); v = dpp_add<0x121>(v);
;   v += __shfl_xor(v, 16);
;   const unsigned u = __float_as_uint(v);
;   auto r = __builtin_amdgcn_permlane32_swap(u, u, false, false);
;   return __uint_as_float(r[0]) + __uint_as_float(r[1]);
; }
; DI void vgt_tile(const Ctx& c, int ti, bf16* lds) {
;     ...
;   for (int rr = 0; rr < 32; ++rr) {
;     const int t = wave * 32 + rr;
;     const unsigned u = *(const unsigned*)(c.P() + (size_t)(row0 + t) * LDP + C_V + g * 128 + 2 * lane);
;     const float a = gelu(__uint_as_float(u << 16)), b = gelu(__uint_as_float(u & 0xffff0000u));
;     const float mean = wave_sum(a + b) * (1.f / 128.f);
;     const float da = a - mean, db = b - mean;
;     const float rstd = rsqrtf(wave_sum(da * da + db * db) * (1.f / 128.f) + LN_EPS);
;     lds[(2 * lane) * LDT + t] = f2bf(da * rstd);
;     lds[(2 * lane + 1) * LDT + t] = f2bf(db * rstd);
;   }
	v_lshlrev_b32_e32 v8, 16, v25
	v_mul_f32_e32 v9, 0.5, v8
	v_mul_f32_e32 v8, 0x3f3504f3, v8
	v_fma_f32 v10, |v8|, s2, 1.0
	v_rcp_f32_e32 v10, v10
	v_and_b32_e32 v7, 0xffff0000, v25
	v_fmamk_f32 v11, v10, 0x3f87dc22, v176
	v_fmaak_f32 v11, v10, v11, 0x3fb5f0e3
	v_fmaak_f32 v11, v10, v11, 0xbe91a98e
	v_fmaak_f32 v11, v10, v11, 0x3e827906
	v_mul_f32_e32 v10, v10, v11
	v_mul_f32_e64 v11, |v8|, s3
	v_mul_f32_e64 v11, |v8|, v11
	v_exp_f32_e32 v11, v11
	s_nop 0
	v_fma_f32 v10, -v11, v10, 1.0
	v_bfi_b32 v8, s13, v10, v8
	v_mul_f32_e32 v10, 0.5, v7
	v_mul_f32_e32 v7, 0x3f3504f3, v7
	v_fma_f32 v11, |v7|, s2, 1.0
	v_rcp_f32_e32 v11, v11
	v_add_f32_e32 v8, 1.0, v8
	v_fmamk_f32 v12, v11, 0x3f87dc22, v176
	v_fmaak_f32 v12, v11, v12, 0x3fb5f0e3
	v_fmaak_f32 v12, v11, v12, 0xbe91a98e
	v_fmaak_f32 v12, v11, v12, 0x3e827906
	v_mul_f32_e32 v11, v11, v12
	v_mul_f32_e64 v12, |v7|, s3
	v_mul_f32_e64 v12, |v7|, v12
	v_exp_f32_e32 v12, v12
	s_nop 0
	v_fma_f32 v11, -v12, v11, 1.0
	v_bfi_b32 v7, s13, v11, v7
	v_add_f32_e32 v7, 1.0, v7
	v_mul_f32_e32 v11, v10, v7
	v_fmac_f32_e32 v11, v9, v8
	s_nop 1
	v_add_f32_dpp v11, v11, v11 row_ror:8 row_mask:0xf bank_mask:0xf bound_ctrl:1
	s_nop 1
	v_add_f32_dpp v11, v11, v11 row_ror:4 row_mask:0xf bank_mask:0xf bound_ctrl:1
	s_nop 1
	v_add_f32_dpp v11, v11, v11 row_ror:2 row_mask:0xf bank_mask:0xf bound_ctrl:1
	s_nop 1
	v_add_f32_dpp v11, v11, v11 row_ror:1 row_mask:0xf bank_mask:0xf bound_ctrl:1
	ds_bpermute_b32 v12, v3, v11
	s_waitcnt lgkmcnt(0)
	v_add_f32_e32 v11, v11, v12
	v_mov_b32_e32 v12, v11
	s_nop 1
	v_permlane32_swap_b32_e32 v11, v12
	v_add_f32_e32 v11, v11, v12
	v_mul_f32_e32 v11, 0x3c000000, v11
	v_fma_f32 v7, v10, v7, -v11
	v_fma_f32 v8, v9, v8, -v11
	v_mul_f32_e32 v9, v7, v7
	v_fmac_f32_e32 v9, v8, v8
	s_nop 1
	v_add_f32_dpp v9, v9, v9 row_ror:8 row_mask:0xf bank_mask:0xf bound_ctrl:1
	s_nop 1
	v_add_f32_dpp v9, v9, v9 row_ror:4 row_mask:0xf bank_mask:0xf bound_ctrl:1
	s_nop 1
	v_add_f32_dpp v9, v9, v9 row_ror:2 row_mask:0xf bank_mask:0xf bound_ctrl:1
	s_nop 1
	v_add_f32_dpp v9, v9, v9 row_ror:1 row_mask:0xf bank_mask:0xf bound_ctrl:1
	ds_bpermute_b32 v10, v3, v9
	s_waitcnt lgkmcnt(0)
	v_add_f32_e32 v9, v9, v10
	v_mov_b32_e32 v10, v9
	s_nop 1
	v_permlane32_swap_b32_e32 v9, v10
	v_add_f32_e32 v9, v9, v10
	v_fmamk_f32 v9, v9, 0x3c000000, v177
	v_cmp_gt_f32_e32 vcc, s16, v9
	v_mul_f32_e32 v10, 0x4b800000, v9
	s_nop 0
	v_cndmask_b32_e32 v9, v9, v10, vcc
	v_rsq_f32_e32 v9, v9
	s_nop 0
	v_mul_f32_e32 v10, 0x45800000, v9
	v_cndmask_b32_e32 v9, v9, v10, vcc
	v_mul_f32_e32 v8, v8, v9
	v_cvt_pk_bf16_f32 v8, v8, v8
	v_add_u32_e32 v10, s5, v6
	v_mul_f32_e32 v7, v7, v9
	ds_write_b16 v10, v8
	s_add_i32 s5, s5, 2
	v_cvt_pk_bf16_f32 v7, v7, v7
	ds_write_b16 v10, v7 offset:272
	s_waitcnt vmcnt(25)
	v_lshlrev_b32_e32 v8, 16, v26
	v_mul_f32_e32 v9, 0.5, v8
	v_mul_f32_e32 v8, 0x3f3504f3, v8
	v_fma_f32 v10, |v8|, s2, 1.0
	v_rcp_f32_e32 v10, v10
	v_and_b32_e32 v7, 0xffff0000, v26
	v_fmamk_f32 v11, v10, 0x3f87dc22, v176
	v_fmaak_f32 v11, v10, v11, 0x3fb5f0e3
	v_fmaak_f32 v11, v10, v11, 0xbe91a98e
	v_fmaak_f32 v11, v10, v11, 0x3e827906
	v_mul_f32_e32 v10, v10, v11
	v_mul_f32_e64 v11, |v8|, s3
	v_mul_f32_e64 v11, |v8|, v11
	v_exp_f32_e32 v11, v11
	s_nop 0
	v_fma_f32 v10, -v11, v10, 1.0
	v_bfi_b32 v8, s13, v10, v8
	v_mul_f32_e32 v10, 0.5, v7
	v_mul_f32_e32 v7, 0x3f3504f3, v7
	v_fma_f32 v11, |v7|, s2, 1.0
	v_rcp_f32_e32 v11, v11
	v_add_f32_e32 v8, 1.0, v8
	v_fmamk_f32 v12, v11, 0x3f87dc22, v176
	v_fmaak_f32 v12, v11, v12, 0x3fb5f0e3
	v_fmaak_f32 v12, v11, v12, 0xbe91a98e
	v_fmaak_f32 v12, v11, v12, 0x3e827906
	v_mul_f32_e32 v11, v11, v12
	v_mul_f32_e64 v12, |v7|, s3
	v_mul_f32_e64 v12, |v7|, v12
	v_exp_f32_e32 v12, v12
	s_nop 0
	v_fma_f32 v11, -v12, v11, 1.0
	v_bfi_b32 v7, s13, v11, v7
	v_add_f32_e32 v7, 1.0, v7
	v_mul_f32_e32 v11, v10, v7
	v_fmac_f32_e32 v11, v9, v8
	s_nop 1
	v_add_f32_dpp v11, v11, v11 row_ror:8 row_mask:0xf bank_mask:0xf bound_ctrl:1
	s_nop 1
	v_add_f32_dpp v11, v11, v11 row_ror:4 row_mask:0xf bank_mask:0xf bound_ctrl:1
	s_nop 1
	v_add_f32_dpp v11, v11, v11 row_ror:2 row_mask:0xf bank_mask:0xf bound_ctrl:1
	s_nop 1
	v_add_f32_dpp v11, v11, v11 row_ror:1 row_mask:0xf bank_mask:0xf bound_ctrl:1
	ds_bpermute_b32 v12, v3, v11
	s_waitcnt lgkmcnt(0)
	v_add_f32_e32 v11, v11, v12
	v_mov_b32_e32 v12, v11
	s_nop 1
	v_permlane32_swap_b32_e32 v11, v12
	v_add_f32_e32 v11, v11, v12
	v_mul_f32_e32 v11, 0x3c000000, v11
	v_fma_f32 v7, v10, v7, -v11
	v_fma_f32 v8, v9, v8, -v11
	v_mul_f32_e32 v9, v7, v7
	v_fmac_f32_e32 v9, v8, v8
	s_nop 1
	v_add_f32_dpp v9, v9, v9 row_ror:8 row_mask:0xf bank_mask:0xf bound_ctrl:1
	s_nop 1
	v_add_f32_dpp v9, v9, v9 row_ror:4 row_mask:0xf bank_mask:0xf bound_ctrl:1
	s_nop 1
	v_add_f32_dpp v9, v9, v9 row_ror:2 row_mask:0xf bank_mask:0xf bound_ctrl:1
	s_nop 1
	v_add_f32_dpp v9, v9, v9 row_ror:1 row_mask:0xf bank_mask:0xf bound_ctrl:1
	ds_bpermute_b32 v10, v3, v9
	s_waitcnt lgkmcnt(0)
	v_add_f32_e32 v9, v9, v10
	v_mov_b32_e32 v10, v9
	s_nop 1
	v_permlane32_swap_b32_e32 v9, v10
	v_add_f32_e32 v9, v9, v10
	v_fmamk_f32 v9, v9, 0x3c000000, v177
	v_cmp_gt_f32_e32 vcc, s16, v9
	v_mul_f32_e32 v10, 0x4b800000, v9
	s_nop 0
	v_cndmask_b32_e32 v9, v9, v10, vcc
	v_rsq_f32_e32 v9, v9
	s_nop 0
	v_mul_f32_e32 v10, 0x45800000, v9
	v_cndmask_b32_e32 v9, v9, v10, vcc
	v_mul_f32_e32 v8, v8, v9
	v_cvt_pk_bf16_f32 v8, v8, v8
	v_add_u32_e32 v10, s5, v6
	v_mul_f32_e32 v7, v7, v9
	ds_write_b16 v10, v8
	s_add_i32 s5, s5, 2
	v_cvt_pk_bf16_f32 v7, v7, v7
	ds_write_b16 v10, v7 offset:272
	s_waitcnt vmcnt(24)
; DI bf16 f2bf(float f) { unsigned u = __float_as_uint(f); u += 0x7fffu + ((u >> 16) & 1u); return (bf16)(u >> 16); }
;   DI bf16* P() const { return (bf16*)(p.ws + WS_P); }
; DI float erf_as(float x) {
;   const float ax = fabsf(x);
;   const float t = __builtin_amdgcn_rcpf(1.f + 0.3275911f * ax);
;   const float poly = t * (0.254829592f + t * (-0.284496736f + t * (1.421413741f + t * (-1.453152027f + t * 1.061405429f))));
;   const float y = 1.f - poly * __builtin_amdgcn_exp2f(-1.4426950408889634f * ax * ax);
;   return copysignf(y, x);
; }
; DI float gelu(float x) { return 0.5f * x * (1.f + erf_as(x * 0.70710678118654752f)); }
; DI float logsigmoid(float z) { return fminf(z, 0.f) - log1pf(__expf(-fabsf(z))); }
; DI float logsigmoid_fast(float z) { return -0.6931471805599453f * __builtin_amdgcn_logf(1.f + __builtin_amdgcn_exp2f(-1.4426950408889634f * fmaxf(z, -80.f))); }
; template <int CTRL> DI float dpp_add(float v) { return v + __builtin_bit_cast(float, __builtin_amdgcn_update_dpp(0, __builtin_bit_cast(int, v), CTRL, 0xf, 0xf, false)); }
; DI float wave_sum(float v) {
;   v = dpp_add<0x128>(v); v = dpp_add<0x124>(v); v = dpp_add<0x122>(v); v = dpp_add<0x121>(v);
;   v += __shfl_xor(v, 16);
;   const unsigned u = __float_as_uint(v);
;   auto r = __builtin_amdgcn_permlane32_swap(u, u, false, false);
;   return __uint_as_float(r[0]) + __uint_as_float(r[1]);
; }
; DI void vgt_tile(const Ctx& c, int ti, bf16* lds) {
;     ...
;   for (int rr = 0; rr < 32; ++rr) {
;     const int t = wave * 32 + rr;
;     const unsigned u = *(const unsigned*)(c.P() + (size_t)(row0 + t) * LDP + C_V + g * 128 + 2 * lane);
;     const float a = gelu(__uint_as_float(u << 16)), b = gelu(__uint_as_float(u & 0xffff0000u));
;     const float mean = wave_sum(a + b) * (1.f / 128.f);
;     const float da = a - mean, db = b - mean;
;     const float rstd = rsqrtf(wave_sum(da * da + db * db) * (1.f / 128.f) + LN_EPS);
;     lds[(2 * lane) * LDT + t] = f2bf(da * rstd);
;     lds[(2 * lane + 1) * LDT + t] = f2bf(db * rstd);
;   }
	v_lshlrev_b32_e32 v8, 16, v27
	v_mul_f32_e32 v9, 0.5, v8
	v_mul_f32_e32 v8, 0x3f3504f3, v8
	v_fma_f32 v10, |v8|, s2, 1.0
	v_rcp_f32_e32 v10, v10
	v_and_b32_e32 v7, 0xffff0000, v27
	v_fmamk_f32 v11, v10, 0x3f87dc22, v176
	v_fmaak_f32 v11, v10, v11, 0x3fb5f0e3
	v_fmaak_f32 v11, v10, v11, 0xbe91a98e
	v_fmaak_f32 v11, v10, v11, 0x3e827906
	v_mul_f32_e32 v10, v10, v11
	v_mul_f32_e64 v11, |v8|, s3
	v_mul_f32_e64 v11, |v8|, v11
	v_exp_f32_e32 v11, v11
	s_nop 0
	v_fma_f32 v10, -v11, v10, 1.0
	v_bfi_b32 v8, s13, v10, v8
	v_mul_f32_e32 v10, 0.5, v7
	v_mul_f32_e32 v7, 0x3f3504f3, v7
	v_fma_f32 v11, |v7|, s2, 1.0
	v_rcp_f32_e32 v11, v11
	v_add_f32_e32 v8, 1.0, v8
	v_fmamk_f32 v12, v11, 0x3f87dc22, v176
	v_fmaak_f32 v12, v11, v12, 0x3fb5f0e3
	v_fmaak_f32 v12, v11, v12, 0xbe91a98e
	v_fmaak_f32 v12, v11, v12, 0x3e827906
	v_mul_f32_e32 v11, v11, v12
	v_mul_f32_e64 v12, |v7|, s3
	v_mul_f32_e64 v12, |v7|, v12
	v_exp_f32_e32 v12, v12
	s_nop 0
	v_fma_f32 v11, -v12, v11, 1.0
	v_bfi_b32 v7, s13, v11, v7
	v_add_f32_e32 v7, 1.0, v7
	v_mul_f32_e32 v11, v10, v7
	v_fmac_f32_e32 v11, v9, v8
	s_nop 1
	v_add_f32_dpp v11, v11, v11 row_ror:8 row_mask:0xf bank_mask:0xf bound_ctrl:1
	s_nop 1
	v_add_f32_dpp v11, v11, v11 row_ror:4 row_mask:0xf bank_mask:0xf bound_ctrl:1
	s_nop 1
	v_add_f32_dpp v11, v11, v11 row_ror:2 row_mask:0xf bank_mask:0xf bound_ctrl:1
	s_nop 1
	v_add_f32_dpp v11, v11, v11 row_ror:1 row_mask:0xf bank_mask:0xf bound_ctrl:1
	ds_bpermute_b32 v12, v3, v11
	s_waitcnt lgkmcnt(0)
	v_add_f32_e32 v11, v11, v12
	v_mov_b32_e32 v12, v11
	s_nop 1
	v_permlane32_swap_b32_e32 v11, v12
	v_add_f32_e32 v11, v11, v12
	v_mul_f32_e32 v11, 0x3c000000, v11
	v_fma_f32 v7, v10, v7, -v11
	v_fma_f32 v8, v9, v8, -v11
	v_mul_f32_e32 v9, v7, v7
	v_fmac_f32_e32 v9, v8, v8
	s_nop 1
	v_add_f32_dpp v9, v9, v9 row_ror:8 row_mask:0xf bank_mask:0xf bound_ctrl:1
	s_nop 1
	v_add_f32_dpp v9, v9, v9 row_ror:4 row_mask:0xf bank_mask:0xf bound_ctrl:1
	s_nop 1
	v_add_f32_dpp v9, v9, v9 row_ror:2 row_mask:0xf bank_mask:0xf bound_ctrl:1
	s_nop 1
	v_add_f32_dpp v9, v9, v9 row_ror:1 row_mask:0xf bank_mask:0xf bound_ctrl:1
	ds_bpermute_b32 v10, v3, v9
	s_waitcnt lgkmcnt(0)
	v_add_f32_e32 v9, v9, v10
	v_mov_b32_e32 v10, v9
	s_nop 1
	v_permlane32_swap_b32_e32 v9, v10
	v_add_f32_e32 v9, v9, v10
	v_fmamk_f32 v9, v9, 0x3c000000, v177
	v_cmp_gt_f32_e32 vcc, s16, v9
	v_mul_f32_e32 v10, 0x4b800000, v9
	s_nop 0
	v_cndmask_b32_e32 v9, v9, v10, vcc
	v_rsq_f32_e32 v9, v9
	s_nop 0
	v_mul_f32_e32 v10, 0x45800000, v9
	v_cndmask_b32_e32 v9, v9, v10, vcc
	v_mul_f32_e32 v8, v8, v9
	v_cvt_pk_bf16_f32 v8, v8, v8
	v_add_u32_e32 v10, s5, v6
	v_mul_f32_e32 v7, v7, v9
	ds_write_b16 v10, v8
	s_add_i32 s5, s5, 2
	v_cvt_pk_bf16_f32 v7, v7, v7
	ds_write_b16 v10, v7 offset:272
	s_waitcnt vmcnt(23)
	v_lshlrev_b32_e32 v8, 16, v28
	v_mul_f32_e32 v9, 0.5, v8
	v_mul_f32_e32 v8, 0x3f3504f3, v8
	v_fma_f32 v10, |v8|, s2, 1.0
	v_rcp_f32_e32 v10, v10
	v_and_b32_e32 v7, 0xffff0000, v28
	v_fmamk_f32 v11, v10, 0x3f87dc22, v176
	v_fmaak_f32 v11, v10, v11, 0x3fb5f0e3
	v_fmaak_f32 v11, v10, v11, 0xbe91a98e
	v_fmaak_f32 v11, v10, v11, 0x3e827906
	v_mul_f32_e32 v10, v10, v11
	v_mul_f32_e64 v11, |v8|, s3
	v_mul_f32_e64 v11, |v8|, v11
	v_exp_f32_e32 v11, v11
	s_nop 0
	v_fma_f32 v10, -v11, v10, 1.0
	v_bfi_b32 v8, s13, v10, v8
	v_mul_f32_e32 v10, 0.5, v7
	v_mul_f32_e32 v7, 0x3f3504f3, v7
	v_fma_f32 v11, |v7|, s2, 1.0
	v_rcp_f32_e32 v11, v11
	v_add_f32_e32 v8, 1.0, v8
	v_fmamk_f32 v12, v11, 0x3f87dc22, v176
	v_fmaak_f32 v12, v11, v12, 0x3fb5f0e3
	v_fmaak_f32 v12, v11, v12, 0xbe91a98e
	v_fmaak_f32 v12, v11, v12, 0x3e827906
	v_mul_f32_e32 v11, v11, v12
	v_mul_f32_e64 v12, |v7|, s3
	v_mul_f32_e64 v12, |v7|, v12
	v_exp_f32_e32 v12, v12
	s_nop 0
	v_fma_f32 v11, -v12, v11, 1.0
	v_bfi_b32 v7, s13, v11, v7
	v_add_f32_e32 v7, 1.0, v7
	v_mul_f32_e32 v11, v10, v7
	v_fmac_f32_e32 v11, v9, v8
	s_nop 1
	v_add_f32_dpp v11, v11, v11 row_ror:8 row_mask:0xf bank_mask:0xf bound_ctrl:1
	s_nop 1
	v_add_f32_dpp v11, v11, v11 row_ror:4 row_mask:0xf bank_mask:0xf bound_ctrl:1
	s_nop 1
	v_add_f32_dpp v11, v11, v11 row_ror:2 row_mask:0xf bank_mask:0xf bound_ctrl:1
	s_nop 1
	v_add_f32_dpp v11, v11, v11 row_ror:1 row_mask:0xf bank_mask:0xf bound_ctrl:1
	ds_bpermute_b32 v12, v3, v11
	s_waitcnt lgkmcnt(0)
	v_add_f32_e32 v11, v11, v12
	v_mov_b32_e32 v12, v11
	s_nop 1
	v_permlane32_swap_b32_e32 v11, v12
	v_add_f32_e32 v11, v11, v12
	v_mul_f32_e32 v11, 0x3c000000, v11
	v_fma_f32 v7, v10, v7, -v11
	v_fma_f32 v8, v9, v8, -v11
	v_mul_f32_e32 v9, v7, v7
	v_fmac_f32_e32 v9, v8, v8
	s_nop 1
	v_add_f32_dpp v9, v9, v9 row_ror:8 row_mask:0xf bank_mask:0xf bound_ctrl:1
	s_nop 1
	v_add_f32_dpp v9, v9, v9 row_ror:4 row_mask:0xf bank_mask:0xf bound_ctrl:1
	s_nop 1
	v_add_f32_dpp v9, v9, v9 row_ror:2 row_mask:0xf bank_mask:0xf bound_ctrl:1
	s_nop 1
	v_add_f32_dpp v9, v9, v9 row_ror:1 row_mask:0xf bank_mask:0xf bound_ctrl:1
	ds_bpermute_b32 v10, v3, v9
	s_waitcnt lgkmcnt(0)
	v_add_f32_e32 v9, v9, v10
	v_mov_b32_e32 v10, v9
	s_nop 1
	v_permlane32_swap_b32_e32 v9, v10
	v_add_f32_e32 v9, v9, v10
	v_fmamk_f32 v9, v9, 0x3c000000, v177
	v_cmp_gt_f32_e32 vcc, s16, v9
	v_mul_f32_e32 v10, 0x4b800000, v9
	s_nop 0
	v_cndmask_b32_e32 v9, v9, v10, vcc
	v_rsq_f32_e32 v9, v9
	s_nop 0
	v_mul_f32_e32 v10, 0x45800000, v9
	v_cndmask_b32_e32 v9, v9, v10, vcc
	v_mul_f32_e32 v8, v8, v9
	v_cvt_pk_bf16_f32 v8, v8, v8
	v_add_u32_e32 v10, s5, v6
	v_mul_f32_e32 v7, v7, v9
	ds_write_b16 v10, v8
	s_add_i32 s5, s5, 2
	v_cvt_pk_bf16_f32 v7, v7, v7
	ds_write_b16 v10, v7 offset:272
	s_waitcnt vmcnt(22)
; DI bf16 f2bf(float f) { unsigned u = __float_as_uint(f); u += 0x7fffu + ((u >> 16) & 1u); return (bf16)(u >> 16); }
;   DI bf16* P() const { return (bf16*)(p.ws + WS_P); }
; DI float erf_as(float x) {
;   const float ax = fabsf(x);
;   const float t = __builtin_amdgcn_rcpf(1.f + 0.3275911f * ax);
;   const float poly = t * (0.254829592f + t * (-0.284496736f + t * (1.421413741f + t * (-1.453152027f + t * 1.061405429f))));
;   const float y = 1.f - poly * __builtin_amdgcn_exp2f(-1.4426950408889634f * ax * ax);
;   return copysignf(y, x);
; }
; DI float gelu(float x) { return 0.5f * x * (1.f + erf_as(x * 0.70710678118654752f)); }
; DI float logsigmoid(float z) { return fminf(z, 0.f) - log1pf(__expf(-fabsf(z))); }
; DI float logsigmoid_fast(float z) { return -0.6931471805599453f * __builtin_amdgcn_logf(1.f + __builtin_amdgcn_exp2f(-1.4426950408889634f * fmaxf(z, -80.f))); }
; template <int CTRL> DI float dpp_add(float v) { return v + __builtin_bit_cast(float, __builtin_amdgcn_update_dpp(0, __builtin_bit_cast(int, v), CTRL, 0xf, 0xf, false)); }
; DI float wave_sum(float v) {
;   v = dpp_add<0x128>(v); v = dpp_add<0x124>(v); v = dpp_add<0x122>(v); v = dpp_add<0x121>(v);
;   v += __shfl_xor(v, 16);
;   const unsigned u = __float_as_uint(v);
;   auto r = __builtin_amdgcn_permlane32_swap(u, u, false, false);
;   return __uint_as_float(r[0]) + __uint_as_float(r[1]);
; }
; DI void vgt_tile(const Ctx& c, int ti, bf16* lds) {
;     ...
;   for (int rr = 0; rr < 32; ++rr) {
;     const int t = wave * 32 + rr;
;     const unsigned u = *(const unsigned*)(c.P() + (size_t)(row0 + t) * LDP + C_V + g * 128 + 2 * lane);
;     const float a = gelu(__uint_as_float(u << 16)), b = gelu(__uint_as_float(u & 0xffff0000u));
;     const float mean = wave_sum(a + b) * (1.f / 128.f);
;     const float da = a - mean, db = b - mean;
;     const float rstd = rsqrtf(wave_sum(da * da + db * db) * (1.f / 128.f) + LN_EPS);
;     lds[(2 * lane) * LDT + t] = f2bf(da * rstd);
;     lds[(2 * lane + 1) * LDT + t] = f2bf(db * rstd);
;   }
	v_lshlrev_b32_e32 v8, 16, v29
	v_mul_f32_e32 v9, 0.5, v8
	v_mul_f32_e32 v8, 0x3f3504f3, v8
	v_fma_f32 v10, |v8|, s2, 1.0
	v_rcp_f32_e32 v10, v10
	v_and_b32_e32 v7, 0xffff0000, v29
	v_fmamk_f32 v11, v10, 0x3f87dc22, v176
	v_fmaak_f32 v11, v10, v11, 0x3fb5f0e3
	v_fmaak_f32 v11, v10, v11, 0xbe91a98e
	v_fmaak_f32 v11, v10, v11, 0x3e827906
	v_mul_f32_e32 v10, v10, v11
	v_mul_f32_e64 v11, |v8|, s3
	v_mul_f32_e64 v11, |v8|, v11
	v_exp_f32_e32 v11, v11
	s_nop 0
	v_fma_f32 v10, -v11, v10, 1.0
	v_bfi_b32 v8, s13, v10, v8
	v_mul_f32_e32 v10, 0.5, v7
	v_mul_f32_e32 v7, 0x3f3504f3, v7
	v_fma_f32 v11, |v7|, s2, 1.0
	v_rcp_f32_e32 v11, v11
	v_add_f32_e32 v8, 1.0, v8
	v_fmamk_f32 v12, v11, 0x3f87dc22, v176
	v_fmaak_f32 v12, v11, v12, 0x3fb5f0e3
	v_fmaak_f32 v12, v11, v12, 0xbe91a98e
	v_fmaak_f32 v12, v11, v12, 0x3e827906
	v_mul_f32_e32 v11, v11, v12
	v_mul_f32_e64 v12, |v7|, s3
	v_mul_f32_e64 v12, |v7|, v12
	v_exp_f32_e32 v12, v12
	s_nop 0
	v_fma_f32 v11, -v12, v11, 1.0
	v_bfi_b32 v7, s13, v11, v7
	v_add_f32_e32 v7, 1.0, v7
	v_mul_f32_e32 v11, v10, v7
	v_fmac_f32_e32 v11, v9, v8
	s_nop 1
	v_add_f32_dpp v11, v11, v11 row_ror:8 row_mask:0xf bank_mask:0xf bound_ctrl:1
	s_nop 1
	v_add_f32_dpp v11, v11, v11 row_ror:4 row_mask:0xf bank_mask:0xf bound_ctrl:1
	s_nop 1
	v_add_f32_dpp v11, v11, v11 row_ror:2 row_mask:0xf bank_mask:0xf bound_ctrl:1
	s_nop 1
	v_add_f32_dpp v11, v11, v11 row_ror:1 row_mask:0xf bank_mask:0xf bound_ctrl:1
	ds_bpermute_b32 v12, v3, v11
	s_waitcnt lgkmcnt(0)
	v_add_f32_e32 v11, v11, v12
	v_mov_b32_e32 v12, v11
	s_nop 1
	v_permlane32_swap_b32_e32 v11, v12
	v_add_f32_e32 v11, v11, v12
	v_mul_f32_e32 v11, 0x3c000000, v11
	v_fma_f32 v7, v10, v7, -v11
	v_fma_f32 v8, v9, v8, -v11
	v_mul_f32_e32 v9, v7, v7
	v_fmac_f32_e32 v9, v8, v8
	s_nop 1
	v_add_f32_dpp v9, v9, v9 row_ror:8 row_mask:0xf bank_mask:0xf bound_ctrl:1
	s_nop 1
	v_add_f32_dpp v9, v9, v9 row_ror:4 row_mask:0xf bank_mask:0xf bound_ctrl:1
	s_nop 1
	v_add_f32_dpp v9, v9, v9 row_ror:2 row_mask:0xf bank_mask:0xf bound_ctrl:1
	s_nop 1
	v_add_f32_dpp v9, v9, v9 row_ror:1 row_mask:0xf bank_mask:0xf bound_ctrl:1
	ds_bpermute_b32 v10, v3, v9
	s_waitcnt lgkmcnt(0)
	v_add_f32_e32 v9, v9, v10
	v_mov_b32_e32 v10, v9
	s_nop 1
	v_permlane32_swap_b32_e32 v9, v10
	v_add_f32_e32 v9, v9, v10
	v_fmamk_f32 v9, v9, 0x3c000000, v177
	v_cmp_gt_f32_e32 vcc, s16, v9
	v_mul_f32_e32 v10, 0x4b800000, v9
	s_nop 0
	v_cndmask_b32_e32 v9, v9, v10, vcc
	v_rsq_f32_e32 v9, v9
	s_nop 0
	v_mul_f32_e32 v10, 0x45800000, v9
	v_cndmask_b32_e32 v9, v9, v10, vcc
	v_mul_f32_e32 v8, v8, v9
	v_cvt_pk_bf16_f32 v8, v8, v8
	v_add_u32_e32 v10, s5, v6
	v_mul_f32_e32 v7, v7, v9
	ds_write_b16 v10, v8
	s_add_i32 s5, s5, 2
	v_cvt_pk_bf16_f32 v7, v7, v7
	ds_write_b16 v10, v7 offset:272
	s_waitcnt vmcnt(21)
	v_lshlrev_b32_e32 v8, 16, v30
	v_mul_f32_e32 v9, 0.5, v8
	v_mul_f32_e32 v8, 0x3f3504f3, v8
	v_fma_f32 v10, |v8|, s2, 1.0
	v_rcp_f32_e32 v10, v10
	v_and_b32_e32 v7, 0xffff0000, v30
	v_fmamk_f32 v11, v10, 0x3f87dc22, v176
	v_fmaak_f32 v11, v10, v11, 0x3fb5f0e3
	v_fmaak_f32 v11, v10, v11, 0xbe91a98e
	v_fmaak_f32 v11, v10, v11, 0x3e827906
	v_mul_f32_e32 v10, v10, v11
	v_mul_f32_e64 v11, |v8|, s3
	v_mul_f32_e64 v11, |v8|, v11
	v_exp_f32_e32 v11, v11
	s_nop 0
	v_fma_f32 v10, -v11, v10, 1.0
	v_bfi_b32 v8, s13, v10, v8
	v_mul_f32_e32 v10, 0.5, v7
	v_mul_f32_e32 v7, 0x3f3504f3, v7
	v_fma_f32 v11, |v7|, s2, 1.0
	v_rcp_f32_e32 v11, v11
	v_add_f32_e32 v8, 1.0, v8
	v_fmamk_f32 v12, v11, 0x3f87dc22, v176
	v_fmaak_f32 v12, v11, v12, 0x3fb5f0e3
	v_fmaak_f32 v12, v11, v12, 0xbe91a98e
	v_fmaak_f32 v12, v11, v12, 0x3e827906
	v_mul_f32_e32 v11, v11, v12
	v_mul_f32_e64 v12, |v7|, s3
	v_mul_f32_e64 v12, |v7|, v12
	v_exp_f32_e32 v12, v12
	s_nop 0
	v_fma_f32 v11, -v12, v11, 1.0
	v_bfi_b32 v7, s13, v11, v7
	v_add_f32_e32 v7, 1.0, v7
	v_mul_f32_e32 v11, v10, v7
	v_fmac_f32_e32 v11, v9, v8
	s_nop 1
	v_add_f32_dpp v11, v11, v11 row_ror:8 row_mask:0xf bank_mask:0xf bound_ctrl:1
	s_nop 1
	v_add_f32_dpp v11, v11, v11 row_ror:4 row_mask:0xf bank_mask:0xf bound_ctrl:1
	s_nop 1
	v_add_f32_dpp v11, v11, v11 row_ror:2 row_mask:0xf bank_mask:0xf bound_ctrl:1
	s_nop 1
	v_add_f32_dpp v11, v11, v11 row_ror:1 row_mask:0xf bank_mask:0xf bound_ctrl:1
	ds_bpermute_b32 v12, v3, v11
	s_waitcnt lgkmcnt(0)
	v_add_f32_e32 v11, v11, v12
	v_mov_b32_e32 v12, v11
	s_nop 1
	v_permlane32_swap_b32_e32 v11, v12
	v_add_f32_e32 v11, v11, v12
	v_mul_f32_e32 v11, 0x3c000000, v11
	v_fma_f32 v7, v10, v7, -v11
	v_fma_f32 v8, v9, v8, -v11
	v_mul_f32_e32 v9, v7, v7
	v_fmac_f32_e32 v9, v8, v8
	s_nop 1
	v_add_f32_dpp v9, v9, v9 row_ror:8 row_mask:0xf bank_mask:0xf bound_ctrl:1
	s_nop 1
	v_add_f32_dpp v9, v9, v9 row_ror:4 row_mask:0xf bank_mask:0xf bound_ctrl:1
	s_nop 1
	v_add_f32_dpp v9, v9, v9 row_ror:2 row_mask:0xf bank_mask:0xf bound_ctrl:1
	s_nop 1
	v_add_f32_dpp v9, v9, v9 row_ror:1 row_mask:0xf bank_mask:0xf bound_ctrl:1
	ds_bpermute_b32 v10, v3, v9
	s_waitcnt lgkmcnt(0)
	v_add_f32_e32 v9, v9, v10
	v_mov_b32_e32 v10, v9
	s_nop 1
	v_permlane32_swap_b32_e32 v9, v10
	v_add_f32_e32 v9, v9, v10
	v_fmamk_f32 v9, v9, 0x3c000000, v177
	v_cmp_gt_f32_e32 vcc, s16, v9
	v_mul_f32_e32 v10, 0x4b800000, v9
	s_nop 0
	v_cndmask_b32_e32 v9, v9, v10, vcc
	v_rsq_f32_e32 v9, v9
	s_nop 0
	v_mul_f32_e32 v10, 0x45800000, v9
	v_cndmask_b32_e32 v9, v9, v10, vcc
	v_mul_f32_e32 v8, v8, v9
	v_cvt_pk_bf16_f32 v8, v8, v8
	v_add_u32_e32 v10, s5, v6
	v_mul_f32_e32 v7, v7, v9
	ds_write_b16 v10, v8
	s_add_i32 s5, s5, 2
	v_cvt_pk_bf16_f32 v7, v7, v7
	ds_write_b16 v10, v7 offset:272
	s_waitcnt vmcnt(20)
; DI bf16 f2bf(float f) { unsigned u = __float_as_uint(f); u += 0x7fffu + ((u >> 16) & 1u); return (bf16)(u >> 16); }
;   DI bf16* P() const { return (bf16*)(p.ws + WS_P); }
; DI float erf_as(float x) {
;   const float ax = fabsf(x);
;   const float t = __builtin_amdgcn_rcpf(1.f + 0.3275911f * ax);
;   const float poly = t * (0.254829592f + t * (-0.284496736f + t * (1.421413741f + t * (-1.453152027f + t * 1.061405429f))));
;   const float y = 1.f - poly * __builtin_amdgcn_exp2f(-1.4426950408889634f * ax * ax);
;   return copysignf(y, x);
; }
; DI float gelu(float x) { return 0.5f * x * (1.f + erf_as(x * 0.70710678118654752f)); }
; DI float logsigmoid(float z) { return fminf(z, 0.f) - log1pf(__expf(-fabsf(z))); }
; DI float logsigmoid_fast(float z) { return -0.6931471805599453f * __builtin_amdgcn_logf(1.f + __builtin_amdgcn_exp2f(-1.4426950408889634f * fmaxf(z, -80.f))); }
; template <int CTRL> DI float dpp_add(float v) { return v + __builtin_bit_cast(float, __builtin_amdgcn_update_dpp(0, __builtin_bit_cast(int, v), CTRL, 0xf, 0xf, false)); }
; DI float wave_sum(float v) {
;   v = dpp_add<0x128>(v); v = dpp_add<0x124>(v); v = dpp_add<0x122>(v); v = dpp_add<0x121>(v);
;   v += __shfl_xor(v, 16);
;   const unsigned u = __float_as_uint(v);
;   auto r = __builtin_amdgcn_permlane32_swap(u, u, false, false);
;   return __uint_as_float(r[0]) + __uint_as_float(r[1]);
; }
; DI void vgt_tile(const Ctx& c, int ti, bf16* lds) {
;     ...
;   for (int rr = 0; rr < 32; ++rr) {
;     const int t = wave * 32 + rr;
;     const unsigned u = *(const unsigned*)(c.P() + (size_t)(row0 + t) * LDP + C_V + g * 128 + 2 * lane);
;     const float a = gelu(__uint_as_float(u << 16)), b = gelu(__uint_as_float(u & 0xffff0000u));
;     const float mean = wave_sum(a + b) * (1.f / 128.f);
;     const float da = a - mean, db = b - mean;
;     const float rstd = rsqrtf(wave_sum(da * da + db * db) * (1.f / 128.f) + LN_EPS);
;     lds[(2 * lane) * LDT + t] = f2bf(da * rstd);
;     lds[(2 * lane + 1) * LDT + t] = f2bf(db * rstd);
;   }
	v_lshlrev_b32_e32 v8, 16, v31
	v_mul_f32_e32 v9, 0.5, v8
	v_mul_f32_e32 v8, 0x3f3504f3, v8
	v_fma_f32 v10, |v8|, s2, 1.0
	v_rcp_f32_e32 v10, v10
	v_and_b32_e32 v7, 0xffff0000, v31
	v_fmamk_f32 v11, v10, 0x3f87dc22, v176
	v_fmaak_f32 v11, v10, v11, 0x3fb5f0e3
	v_fmaak_f32 v11, v10, v11, 0xbe91a98e
	v_fmaak_f32 v11, v10, v11, 0x3e827906
	v_mul_f32_e32 v10, v10, v11
	v_mul_f32_e64 v11, |v8|, s3
	v_mul_f32_e64 v11, |v8|, v11
	v_exp_f32_e32 v11, v11
	s_nop 0
	v_fma_f32 v10, -v11, v10, 1.0
	v_bfi_b32 v8, s13, v10, v8
	v_mul_f32_e32 v10, 0.5, v7
	v_mul_f32_e32 v7, 0x3f3504f3, v7
	v_fma_f32 v11, |v7|, s2, 1.0
	v_rcp_f32_e32 v11, v11
	v_add_f32_e32 v8, 1.0, v8
	v_fmamk_f32 v12, v11, 0x3f87dc22, v176
	v_fmaak_f32 v12, v11, v12, 0x3fb5f0e3
	v_fmaak_f32 v12, v11, v12, 0xbe91a98e
	v_fmaak_f32 v12, v11, v12, 0x3e827906
	v_mul_f32_e32 v11, v11, v12
	v_mul_f32_e64 v12, |v7|, s3
	v_mul_f32_e64 v12, |v7|, v12
	v_exp_f32_e32 v12, v12
	s_nop 0
	v_fma_f32 v11, -v12, v11, 1.0
	v_bfi_b32 v7, s13, v11, v7
	v_add_f32_e32 v7, 1.0, v7
	v_mul_f32_e32 v11, v10, v7
	v_fmac_f32_e32 v11, v9, v8
	s_nop 1
	v_add_f32_dpp v11, v11, v11 row_ror:8 row_mask:0xf bank_mask:0xf bound_ctrl:1
	s_nop 1
	v_add_f32_dpp v11, v11, v11 row_ror:4 row_mask:0xf bank_mask:0xf bound_ctrl:1
	s_nop 1
	v_add_f32_dpp v11, v11, v11 row_ror:2 row_mask:0xf bank_mask:0xf bound_ctrl:1
	s_nop 1
	v_add_f32_dpp v11, v11, v11 row_ror:1 row_mask:0xf bank_mask:0xf bound_ctrl:1
	ds_bpermute_b32 v12, v3, v11
	s_waitcnt lgkmcnt(0)
	v_add_f32_e32 v11, v11, v12
	v_mov_b32_e32 v12, v11
	s_nop 1
	v_permlane32_swap_b32_e32 v11, v12
	v_add_f32_e32 v11, v11, v12
	v_mul_f32_e32 v11, 0x3c000000, v11
	v_fma_f32 v7, v10, v7, -v11
	v_fma_f32 v8, v9, v8, -v11
	v_mul_f32_e32 v9, v7, v7
	v_fmac_f32_e32 v9, v8, v8
	s_nop 1
	v_add_f32_dpp v9, v9, v9 row_ror:8 row_mask:0xf bank_mask:0xf bound_ctrl:1
	s_nop 1
	v_add_f32_dpp v9, v9, v9 row_ror:4 row_mask:0xf bank_mask:0xf bound_ctrl:1
	s_nop 1
	v_add_f32_dpp v9, v9, v9 row_ror:2 row_mask:0xf bank_mask:0xf bound_ctrl:1
	s_nop 1
	v_add_f32_dpp v9, v9, v9 row_ror:1 row_mask:0xf bank_mask:0xf bound_ctrl:1
	ds_bpermute_b32 v10, v3, v9
	s_waitcnt lgkmcnt(0)
	v_add_f32_e32 v9, v9, v10
	v_mov_b32_e32 v10, v9
	s_nop 1
	v_permlane32_swap_b32_e32 v9, v10
	v_add_f32_e32 v9, v9, v10
	v_fmamk_f32 v9, v9, 0x3c000000, v177
	v_cmp_gt_f32_e32 vcc, s16, v9
	v_mul_f32_e32 v10, 0x4b800000, v9
	s_nop 0
	v_cndmask_b32_e32 v9, v9, v10, vcc
	v_rsq_f32_e32 v9, v9
	s_nop 0
	v_mul_f32_e32 v10, 0x45800000, v9
	v_cndmask_b32_e32 v9, v9, v10, vcc
	v_mul_f32_e32 v8, v8, v9
	v_cvt_pk_bf16_f32 v8, v8, v8
	v_add_u32_e32 v10, s5, v6
	v_mul_f32_e32 v7, v7, v9
	ds_write_b16 v10, v8
	s_add_i32 s5, s5, 2
	v_cvt_pk_bf16_f32 v7, v7, v7
	ds_write_b16 v10, v7 offset:272
	s_waitcnt vmcnt(19)
	v_lshlrev_b32_e32 v8, 16, v32
	v_mul_f32_e32 v9, 0.5, v8
	v_mul_f32_e32 v8, 0x3f3504f3, v8
	v_fma_f32 v10, |v8|, s2, 1.0
	v_rcp_f32_e32 v10, v10
	v_and_b32_e32 v7, 0xffff0000, v32
	v_fmamk_f32 v11, v10, 0x3f87dc22, v176
	v_fmaak_f32 v11, v10, v11, 0x3fb5f0e3
	v_fmaak_f32 v11, v10, v11, 0xbe91a98e
	v_fmaak_f32 v11, v10, v11, 0x3e827906
	v_mul_f32_e32 v10, v10, v11
	v_mul_f32_e64 v11, |v8|, s3
	v_mul_f32_e64 v11, |v8|, v11
	v_exp_f32_e32 v11, v11
	s_nop 0
	v_fma_f32 v10, -v11, v10, 1.0
	v_bfi_b32 v8, s13, v10, v8
	v_mul_f32_e32 v10, 0.5, v7
	v_mul_f32_e32 v7, 0x3f3504f3, v7
	v_fma_f32 v11, |v7|, s2, 1.0
	v_rcp_f32_e32 v11, v11
	v_add_f32_e32 v8, 1.0, v8
	v_fmamk_f32 v12, v11, 0x3f87dc22, v176
	v_fmaak_f32 v12, v11, v12, 0x3fb5f0e3
	v_fmaak_f32 v12, v11, v12, 0xbe91a98e
	v_fmaak_f32 v12, v11, v12, 0x3e827906
	v_mul_f32_e32 v11, v11, v12
	v_mul_f32_e64 v12, |v7|, s3
	v_mul_f32_e64 v12, |v7|, v12
	v_exp_f32_e32 v12, v12
	s_nop 0
	v_fma_f32 v11, -v12, v11, 1.0
	v_bfi_b32 v7, s13, v11, v7
	v_add_f32_e32 v7, 1.0, v7
	v_mul_f32_e32 v11, v10, v7
	v_fmac_f32_e32 v11, v9, v8
	s_nop 1
	v_add_f32_dpp v11, v11, v11 row_ror:8 row_mask:0xf bank_mask:0xf bound_ctrl:1
	s_nop 1
	v_add_f32_dpp v11, v11, v11 row_ror:4 row_mask:0xf bank_mask:0xf bound_ctrl:1
	s_nop 1
	v_add_f32_dpp v11, v11, v11 row_ror:2 row_mask:0xf bank_mask:0xf bound_ctrl:1
	s_nop 1
	v_add_f32_dpp v11, v11, v11 row_ror:1 row_mask:0xf bank_mask:0xf bound_ctrl:1
	ds_bpermute_b32 v12, v3, v11
	s_waitcnt lgkmcnt(0)
	v_add_f32_e32 v11, v11, v12
	v_mov_b32_e32 v12, v11
	s_nop 1
	v_permlane32_swap_b32_e32 v11, v12
	v_add_f32_e32 v11, v11, v12
	v_mul_f32_e32 v11, 0x3c000000, v11
	v_fma_f32 v7, v10, v7, -v11
	v_fma_f32 v8, v9, v8, -v11
	v_mul_f32_e32 v9, v7, v7
	v_fmac_f32_e32 v9, v8, v8
	s_nop 1
	v_add_f32_dpp v9, v9, v9 row_ror:8 row_mask:0xf bank_mask:0xf bound_ctrl:1
	s_nop 1
	v_add_f32_dpp v9, v9, v9 row_ror:4 row_mask:0xf bank_mask:0xf bound_ctrl:1
	s_nop 1
	v_add_f32_dpp v9, v9, v9 row_ror:2 row_mask:0xf bank_mask:0xf bound_ctrl:1
	s_nop 1
	v_add_f32_dpp v9, v9, v9 row_ror:1 row_mask:0xf bank_mask:0xf bound_ctrl:1
	ds_bpermute_b32 v10, v3, v9
	s_waitcnt lgkmcnt(0)
	v_add_f32_e32 v9, v9, v10
	v_mov_b32_e32 v10, v9
	s_nop 1
	v_permlane32_swap_b32_e32 v9, v10
	v_add_f32_e32 v9, v9, v10
	v_fmamk_f32 v9, v9, 0x3c000000, v177
	v_cmp_gt_f32_e32 vcc, s16, v9
	v_mul_f32_e32 v10, 0x4b800000, v9
	s_nop 0
	v_cndmask_b32_e32 v9, v9, v10, vcc
	v_rsq_f32_e32 v9, v9
	s_nop 0
	v_mul_f32_e32 v10, 0x45800000, v9
	v_cndmask_b32_e32 v9, v9, v10, vcc
	v_mul_f32_e32 v8, v8, v9
	v_cvt_pk_bf16_f32 v8, v8, v8
	v_add_u32_e32 v10, s5, v6
	v_mul_f32_e32 v7, v7, v9
	ds_write_b16 v10, v8
	s_add_i32 s5, s5, 2
	v_cvt_pk_bf16_f32 v7, v7, v7
	ds_write_b16 v10, v7 offset:272
	s_waitcnt vmcnt(18)
; DI bf16 f2bf(float f) { unsigned u = __float_as_uint(f); u += 0x7fffu + ((u >> 16) & 1u); return (bf16)(u >> 16); }
;   DI bf16* P() const { return (bf16*)(p.ws + WS_P); }
; DI float erf_as(float x) {
;   const float ax = fabsf(x);
;   const float t = __builtin_amdgcn_rcpf(1.f + 0.3275911f * ax);
;   const float poly = t * (0.254829592f + t * (-0.284496736f + t * (1.421413741f + t * (-1.453152027f + t * 1.061405429f))));
;   const float y = 1.f - poly * __builtin_amdgcn_exp2f(-1.4426950408889634f * ax * ax);
;   return copysignf(y, x);
; }
; DI float gelu(float x) { return 0.5f * x * (1.f + erf_as(x * 0.70710678118654752f)); }
; DI float logsigmoid(float z) { return fminf(z, 0.f) - log1pf(__expf(-fabsf(z))); }
; DI float logsigmoid_fast(float z) { return -0.6931471805599453f * __builtin_amdgcn_logf(1.f + __builtin_amdgcn_exp2f(-1.4426950408889634f * fmaxf(z, -80.f))); }
; template <int CTRL> DI float dpp_add(float v) { return v + __builtin_bit_cast(float, __builtin_amdgcn_update_dpp(0, __builtin_bit_cast(int, v), CTRL, 0xf, 0xf, false)); }
; DI float wave_sum(float v) {
;   v = dpp_add<0x128>(v); v = dpp_add<0x124>(v); v = dpp_add<0x122>(v); v = dpp_add<0x121>(v);
;   v += __shfl_xor(v, 16);
;   const unsigned u = __float_as_uint(v);
;   auto r = __builtin_amdgcn_permlane32_swap(u, u, false, false);
;   return __uint_as_float(r[0]) + __uint_as_float(r[1]);
; }
; DI void vgt_tile(const Ctx& c, int ti, bf16* lds) {
;     ...
;   for (int rr = 0; rr < 32; ++rr) {
;     const int t = wave * 32 + rr;
;     const unsigned u = *(const unsigned*)(c.P() + (size_t)(row0 + t) * LDP + C_V + g * 128 + 2 * lane);
;     const float a = gelu(__uint_as_float(u << 16)), b = gelu(__uint_as_float(u & 0xffff0000u));
;     const float mean = wave_sum(a + b) * (1.f / 128.f);
;     const float da = a - mean, db = b - mean;
;     const float rstd = rsqrtf(wave_sum(da * da + db * db) * (1.f / 128.f) + LN_EPS);
;     lds[(2 * lane) * LDT + t] = f2bf(da * rstd);
;     lds[(2 * lane + 1) * LDT + t] = f2bf(db * rstd);
;   }
	v_lshlrev_b32_e32 v8, 16, v33
	v_mul_f32_e32 v9, 0.5, v8
	v_mul_f32_e32 v8, 0x3f3504f3, v8
	v_fma_f32 v10, |v8|, s2, 1.0
	v_rcp_f32_e32 v10, v10
	v_and_b32_e32 v7, 0xffff0000, v33
	v_fmamk_f32 v11, v10, 0x3f87dc22, v176
	v_fmaak_f32 v11, v10, v11, 0x3fb5f0e3
	v_fmaak_f32 v11, v10, v11, 0xbe91a98e
	v_fmaak_f32 v11, v10, v11, 0x3e827906
	v_mul_f32_e32 v10, v10, v11
	v_mul_f32_e64 v11, |v8|, s3
	v_mul_f32_e64 v11, |v8|, v11
	v_exp_f32_e32 v11, v11
	s_nop 0
	v_fma_f32 v10, -v11, v10, 1.0
	v_bfi_b32 v8, s13, v10, v8
	v_mul_f32_e32 v10, 0.5, v7
	v_mul_f32_e32 v7, 0x3f3504f3, v7
	v_fma_f32 v11, |v7|, s2, 1.0
	v_rcp_f32_e32 v11, v11
	v_add_f32_e32 v8, 1.0, v8
	v_fmamk_f32 v12, v11, 0x3f87dc22, v176
	v_fmaak_f32 v12, v11, v12, 0x3fb5f0e3
	v_fmaak_f32 v12, v11, v12, 0xbe91a98e
	v_fmaak_f32 v12, v11, v12, 0x3e827906
	v_mul_f32_e32 v11, v11, v12
	v_mul_f32_e64 v12, |v7|, s3
	v_mul_f32_e64 v12, |v7|, v12
	v_exp_f32_e32 v12, v12
	s_nop 0
	v_fma_f32 v11, -v12, v11, 1.0
	v_bfi_b32 v7, s13, v11, v7
	v_add_f32_e32 v7, 1.0, v7
	v_mul_f32_e32 v11, v10, v7
	v_fmac_f32_e32 v11, v9, v8
	s_nop 1
	v_add_f32_dpp v11, v11, v11 row_ror:8 row_mask:0xf bank_mask:0xf bound_ctrl:1
	s_nop 1
	v_add_f32_dpp v11, v11, v11 row_ror:4 row_mask:0xf bank_mask:0xf bound_ctrl:1
	s_nop 1
	v_add_f32_dpp v11, v11, v11 row_ror:2 row_mask:0xf bank_mask:0xf bound_ctrl:1
	s_nop 1
	v_add_f32_dpp v11, v11, v11 row_ror:1 row_mask:0xf bank_mask:0xf bound_ctrl:1
	ds_bpermute_b32 v12, v3, v11
	s_waitcnt lgkmcnt(0)
	v_add_f32_e32 v11, v11, v12
	v_mov_b32_e32 v12, v11
	s_nop 1
	v_permlane32_swap_b32_e32 v11, v12
	v_add_f32_e32 v11, v11, v12
	v_mul_f32_e32 v11, 0x3c000000, v11
	v_fma_f32 v7, v10, v7, -v11
	v_fma_f32 v8, v9, v8, -v11
	v_mul_f32_e32 v9, v7, v7
	v_fmac_f32_e32 v9, v8, v8
	s_nop 1
	v_add_f32_dpp v9, v9, v9 row_ror:8 row_mask:0xf bank_mask:0xf bound_ctrl:1
	s_nop 1
	v_add_f32_dpp v9, v9, v9 row_ror:4 row_mask:0xf bank_mask:0xf bound_ctrl:1
	s_nop 1
	v_add_f32_dpp v9, v9, v9 row_ror:2 row_mask:0xf bank_mask:0xf bound_ctrl:1
	s_nop 1
	v_add_f32_dpp v9, v9, v9 row_ror:1 row_mask:0xf bank_mask:0xf bound_ctrl:1
	ds_bpermute_b32 v10, v3, v9
	s_waitcnt lgkmcnt(0)
	v_add_f32_e32 v9, v9, v10
	v_mov_b32_e32 v10, v9
	s_nop 1
	v_permlane32_swap_b32_e32 v9, v10
	v_add_f32_e32 v9, v9, v10
	v_fmamk_f32 v9, v9, 0x3c000000, v177
	v_cmp_gt_f32_e32 vcc, s16, v9
	v_mul_f32_e32 v10, 0x4b800000, v9
	s_nop 0
	v_cndmask_b32_e32 v9, v9, v10, vcc
	v_rsq_f32_e32 v9, v9
	s_nop 0
	v_mul_f32_e32 v10, 0x45800000, v9
	v_cndmask_b32_e32 v9, v9, v10, vcc
	v_mul_f32_e32 v8, v8, v9
	v_cvt_pk_bf16_f32 v8, v8, v8
	v_add_u32_e32 v10, s5, v6
	v_mul_f32_e32 v7, v7, v9
	ds_write_b16 v10, v8
	s_add_i32 s5, s5, 2
	v_cvt_pk_bf16_f32 v7, v7, v7
	ds_write_b16 v10, v7 offset:272
	s_waitcnt vmcnt(17)
	v_lshlrev_b32_e32 v8, 16, v34
	v_mul_f32_e32 v9, 0.5, v8
	v_mul_f32_e32 v8, 0x3f3504f3, v8
	v_fma_f32 v10, |v8|, s2, 1.0
	v_rcp_f32_e32 v10, v10
	v_and_b32_e32 v7, 0xffff0000, v34
	v_fmamk_f32 v11, v10, 0x3f87dc22, v176
	v_fmaak_f32 v11, v10, v11, 0x3fb5f0e3
	v_fmaak_f32 v11, v10, v11, 0xbe91a98e
	v_fmaak_f32 v11, v10, v11, 0x3e827906
	v_mul_f32_e32 v10, v10, v11
	v_mul_f32_e64 v11, |v8|, s3
	v_mul_f32_e64 v11, |v8|, v11
	v_exp_f32_e32 v11, v11
	s_nop 0
	v_fma_f32 v10, -v11, v10, 1.0
	v_bfi_b32 v8, s13, v10, v8
	v_mul_f32_e32 v10, 0.5, v7
	v_mul_f32_e32 v7, 0x3f3504f3, v7
	v_fma_f32 v11, |v7|, s2, 1.0
	v_rcp_f32_e32 v11, v11
	v_add_f32_e32 v8, 1.0, v8
	v_fmamk_f32 v12, v11, 0x3f87dc22, v176
	v_fmaak_f32 v12, v11, v12, 0x3fb5f0e3
	v_fmaak_f32 v12, v11, v12, 0xbe91a98e
	v_fmaak_f32 v12, v11, v12, 0x3e827906
	v_mul_f32_e32 v11, v11, v12
	v_mul_f32_e64 v12, |v7|, s3
	v_mul_f32_e64 v12, |v7|, v12
	v_exp_f32_e32 v12, v12
	s_nop 0
	v_fma_f32 v11, -v12, v11, 1.0
	v_bfi_b32 v7, s13, v11, v7
	v_add_f32_e32 v7, 1.0, v7
	v_mul_f32_e32 v11, v10, v7
	v_fmac_f32_e32 v11, v9, v8
	s_nop 1
	v_add_f32_dpp v11, v11, v11 row_ror:8 row_mask:0xf bank_mask:0xf bound_ctrl:1
	s_nop 1
	v_add_f32_dpp v11, v11, v11 row_ror:4 row_mask:0xf bank_mask:0xf bound_ctrl:1
	s_nop 1
	v_add_f32_dpp v11, v11, v11 row_ror:2 row_mask:0xf bank_mask:0xf bound_ctrl:1
	s_nop 1
	v_add_f32_dpp v11, v11, v11 row_ror:1 row_mask:0xf bank_mask:0xf bound_ctrl:1
	ds_bpermute_b32 v12, v3, v11
	s_waitcnt lgkmcnt(0)
	v_add_f32_e32 v11, v11, v12
	v_mov_b32_e32 v12, v11
	s_nop 1
	v_permlane32_swap_b32_e32 v11, v12
	v_add_f32_e32 v11, v11, v12
	v_mul_f32_e32 v11, 0x3c000000, v11
	v_fma_f32 v7, v10, v7, -v11
	v_fma_f32 v8, v9, v8, -v11
	v_mul_f32_e32 v9, v7, v7
	v_fmac_f32_e32 v9, v8, v8
	s_nop 1
	v_add_f32_dpp v9, v9, v9 row_ror:8 row_mask:0xf bank_mask:0xf bound_ctrl:1
	s_nop 1
	v_add_f32_dpp v9, v9, v9 row_ror:4 row_mask:0xf bank_mask:0xf bound_ctrl:1
	s_nop 1
	v_add_f32_dpp v9, v9, v9 row_ror:2 row_mask:0xf bank_mask:0xf bound_ctrl:1
	s_nop 1
	v_add_f32_dpp v9, v9, v9 row_ror:1 row_mask:0xf bank_mask:0xf bound_ctrl:1
	ds_bpermute_b32 v10, v3, v9
	s_waitcnt lgkmcnt(0)
	v_add_f32_e32 v9, v9, v10
	v_mov_b32_e32 v10, v9
	s_nop 1
	v_permlane32_swap_b32_e32 v9, v10
	v_add_f32_e32 v9, v9, v10
	v_fmamk_f32 v9, v9, 0x3c000000, v177
	v_cmp_gt_f32_e32 vcc, s16, v9
	v_mul_f32_e32 v10, 0x4b800000, v9
	s_nop 0
	v_cndmask_b32_e32 v9, v9, v10, vcc
	v_rsq_f32_e32 v9, v9
	s_nop 0
	v_mul_f32_e32 v10, 0x45800000, v9
	v_cndmask_b32_e32 v9, v9, v10, vcc
	v_mul_f32_e32 v8, v8, v9
	v_cvt_pk_bf16_f32 v8, v8, v8
	v_add_u32_e32 v10, s5, v6
	v_mul_f32_e32 v7, v7, v9
	ds_write_b16 v10, v8
	s_add_i32 s5, s5, 2
	v_cvt_pk_bf16_f32 v7, v7, v7
	ds_write_b16 v10, v7 offset:272
	s_waitcnt vmcnt(16)
; DI bf16 f2bf(float f) { unsigned u = __float_as_uint(f); u += 0x7fffu + ((u >> 16) & 1u); return (bf16)(u >> 16); }
;   DI bf16* P() const { return (bf16*)(p.ws + WS_P); }
; DI float erf_as(float x) {
;   const float ax = fabsf(x);
;   const float t = __builtin_amdgcn_rcpf(1.f + 0.3275911f * ax);
;   const float poly = t * (0.254829592f + t * (-0.284496736f + t * (1.421413741f + t * (-1.453152027f + t * 1.061405429f))));
;   const float y = 1.f - poly * __builtin_amdgcn_exp2f(-1.4426950408889634f * ax * ax);
;   return copysignf(y, x);
; }
; DI float gelu(float x) { return 0.5f * x * (1.f + erf_as(x * 0.70710678118654752f)); }
; DI float logsigmoid(float z) { return fminf(z, 0.f) - log1pf(__expf(-fabsf(z))); }
; DI float logsigmoid_fast(float z) { return -0.6931471805599453f * __builtin_amdgcn_logf(1.f + __builtin_amdgcn_exp2f(-1.4426950408889634f * fmaxf(z, -80.f))); }
; template <int CTRL> DI float dpp_add(float v) { return v + __builtin_bit_cast(float, __builtin_amdgcn_update_dpp(0, __builtin_bit_cast(int, v), CTRL, 0xf, 0xf, false)); }
; DI float wave_sum(float v) {
;   v = dpp_add<0x128>(v); v = dpp_add<0x124>(v); v = dpp_add<0x122>(v); v = dpp_add<0x121>(v);
;   v += __shfl_xor(v, 16);
;   const unsigned u = __float_as_uint(v);
;   auto r = __builtin_amdgcn_permlane32_swap(u, u, false, false);
;   return __uint_as_float(r[0]) + __uint_as_float(r[1]);
; }
; DI void vgt_tile(const Ctx& c, int ti, bf16* lds) {
;     ...
;   for (int rr = 0; rr < 32; ++rr) {
;     const int t = wave * 32 + rr;
;     const unsigned u = *(const unsigned*)(c.P() + (size_t)(row0 + t) * LDP + C_V + g * 128 + 2 * lane);
;     const float a = gelu(__uint_as_float(u << 16)), b = gelu(__uint_as_float(u & 0xffff0000u));
;     const float mean = wave_sum(a + b) * (1.f / 128.f);
;     const float da = a - mean, db = b - mean;
;     const float rstd = rsqrtf(wave_sum(da * da + db * db) * (1.f / 128.f) + LN_EPS);
;     lds[(2 * lane) * LDT + t] = f2bf(da * rstd);
;     lds[(2 * lane + 1) * LDT + t] = f2bf(db * rstd);
;   }
	v_lshlrev_b32_e32 v8, 16, v35
	v_mul_f32_e32 v9, 0.5, v8
	v_mul_f32_e32 v8, 0x3f3504f3, v8
	v_fma_f32 v10, |v8|, s2, 1.0
	v_rcp_f32_e32 v10, v10
	v_and_b32_e32 v7, 0xffff0000, v35
	v_fmamk_f32 v11, v10, 0x3f87dc22, v176
	v_fmaak_f32 v11, v10, v11, 0x3fb5f0e3
	v_fmaak_f32 v11, v10, v11, 0xbe91a98e
	v_fmaak_f32 v11, v10, v11, 0x3e827906
	v_mul_f32_e32 v10, v10, v11
	v_mul_f32_e64 v11, |v8|, s3
	v_mul_f32_e64 v11, |v8|, v11
	v_exp_f32_e32 v11, v11
	s_nop 0
	v_fma_f32 v10, -v11, v10, 1.0
	v_bfi_b32 v8, s13, v10, v8
	v_mul_f32_e32 v10, 0.5, v7
	v_mul_f32_e32 v7, 0x3f3504f3, v7
	v_fma_f32 v11, |v7|, s2, 1.0
	v_rcp_f32_e32 v11, v11
	v_add_f32_e32 v8, 1.0, v8
	v_fmamk_f32 v12, v11, 0x3f87dc22, v176
	v_fmaak_f32 v12, v11, v12, 0x3fb5f0e3
	v_fmaak_f32 v12, v11, v12, 0xbe91a98e
	v_fmaak_f32 v12, v11, v12, 0x3e827906
	v_mul_f32_e32 v11, v11, v12
	v_mul_f32_e64 v12, |v7|, s3
	v_mul_f32_e64 v12, |v7|, v12
	v_exp_f32_e32 v12, v12
	s_nop 0
	v_fma_f32 v11, -v12, v11, 1.0
	v_bfi_b32 v7, s13, v11, v7
	v_add_f32_e32 v7, 1.0, v7
	v_mul_f32_e32 v11, v10, v7
	v_fmac_f32_e32 v11, v9, v8
	s_nop 1
	v_add_f32_dpp v11, v11, v11 row_ror:8 row_mask:0xf bank_mask:0xf bound_ctrl:1
	s_nop 1
	v_add_f32_dpp v11, v11, v11 row_ror:4 row_mask:0xf bank_mask:0xf bound_ctrl:1
	s_nop 1
	v_add_f32_dpp v11, v11, v11 row_ror:2 row_mask:0xf bank_mask:0xf bound_ctrl:1
	s_nop 1
	v_add_f32_dpp v11, v11, v11 row_ror:1 row_mask:0xf bank_mask:0xf bound_ctrl:1
	ds_bpermute_b32 v12, v3, v11
	s_waitcnt lgkmcnt(0)
	v_add_f32_e32 v11, v11, v12
	v_mov_b32_e32 v12, v11
	s_nop 1
	v_permlane32_swap_b32_e32 v11, v12
	v_add_f32_e32 v11, v11, v12
	v_mul_f32_e32 v11, 0x3c000000, v11
	v_fma_f32 v7, v10, v7, -v11
	v_fma_f32 v8, v9, v8, -v11
	v_mul_f32_e32 v9, v7, v7
	v_fmac_f32_e32 v9, v8, v8
	s_nop 1
	v_add_f32_dpp v9, v9, v9 row_ror:8 row_mask:0xf bank_mask:0xf bound_ctrl:1
	s_nop 1
	v_add_f32_dpp v9, v9, v9 row_ror:4 row_mask:0xf bank_mask:0xf bound_ctrl:1
	s_nop 1
	v_add_f32_dpp v9, v9, v9 row_ror:2 row_mask:0xf bank_mask:0xf bound_ctrl:1
	s_nop 1
	v_add_f32_dpp v9, v9, v9 row_ror:1 row_mask:0xf bank_mask:0xf bound_ctrl:1
	ds_bpermute_b32 v10, v3, v9
	s_waitcnt lgkmcnt(0)
	v_add_f32_e32 v9, v9, v10
	v_mov_b32_e32 v10, v9
	s_nop 1
	v_permlane32_swap_b32_e32 v9, v10
	v_add_f32_e32 v9, v9, v10
	v_fmamk_f32 v9, v9, 0x3c000000, v177
	v_cmp_gt_f32_e32 vcc, s16, v9
	v_mul_f32_e32 v10, 0x4b800000, v9
	s_nop 0
	v_cndmask_b32_e32 v9, v9, v10, vcc
	v_rsq_f32_e32 v9, v9
	s_nop 0
	v_mul_f32_e32 v10, 0x45800000, v9
	v_cndmask_b32_e32 v9, v9, v10, vcc
	v_mul_f32_e32 v8, v8, v9
	v_cvt_pk_bf16_f32 v8, v8, v8
	v_add_u32_e32 v10, s5, v6
	v_mul_f32_e32 v7, v7, v9
	ds_write_b16 v10, v8
	s_add_i32 s5, s5, 2
	v_cvt_pk_bf16_f32 v7, v7, v7
	ds_write_b16 v10, v7 offset:272
	s_waitcnt vmcnt(15)
	v_lshlrev_b32_e32 v8, 16, v36
	v_mul_f32_e32 v9, 0.5, v8
	v_mul_f32_e32 v8, 0x3f3504f3, v8
	v_fma_f32 v10, |v8|, s2, 1.0
	v_rcp_f32_e32 v10, v10
	v_and_b32_e32 v7, 0xffff0000, v36
	v_fmamk_f32 v11, v10, 0x3f87dc22, v176
	v_fmaak_f32 v11, v10, v11, 0x3fb5f0e3
	v_fmaak_f32 v11, v10, v11, 0xbe91a98e
	v_fmaak_f32 v11, v10, v11, 0x3e827906
	v_mul_f32_e32 v10, v10, v11
	v_mul_f32_e64 v11, |v8|, s3
	v_mul_f32_e64 v11, |v8|, v11
	v_exp_f32_e32 v11, v11
	s_nop 0
	v_fma_f32 v10, -v11, v10, 1.0
	v_bfi_b32 v8, s13, v10, v8
	v_mul_f32_e32 v10, 0.5, v7
	v_mul_f32_e32 v7, 0x3f3504f3, v7
	v_fma_f32 v11, |v7|, s2, 1.0
	v_rcp_f32_e32 v11, v11
	v_add_f32_e32 v8, 1.0, v8
	v_fmamk_f32 v12, v11, 0x3f87dc22, v176
	v_fmaak_f32 v12, v11, v12, 0x3fb5f0e3
	v_fmaak_f32 v12, v11, v12, 0xbe91a98e
	v_fmaak_f32 v12, v11, v12, 0x3e827906
	v_mul_f32_e32 v11, v11, v12
	v_mul_f32_e64 v12, |v7|, s3
	v_mul_f32_e64 v12, |v7|, v12
	v_exp_f32_e32 v12, v12
	s_nop 0
	v_fma_f32 v11, -v12, v11, 1.0
	v_bfi_b32 v7, s13, v11, v7
	v_add_f32_e32 v7, 1.0, v7
	v_mul_f32_e32 v11, v10, v7
	v_fmac_f32_e32 v11, v9, v8
	s_nop 1
	v_add_f32_dpp v11, v11, v11 row_ror:8 row_mask:0xf bank_mask:0xf bound_ctrl:1
	s_nop 1
	v_add_f32_dpp v11, v11, v11 row_ror:4 row_mask:0xf bank_mask:0xf bound_ctrl:1
	s_nop 1
	v_add_f32_dpp v11, v11, v11 row_ror:2 row_mask:0xf bank_mask:0xf bound_ctrl:1
	s_nop 1
	v_add_f32_dpp v11, v11, v11 row_ror:1 row_mask:0xf bank_mask:0xf bound_ctrl:1
	ds_bpermute_b32 v12, v3, v11
	s_waitcnt lgkmcnt(0)
	v_add_f32_e32 v11, v11, v12
	v_mov_b32_e32 v12, v11
	s_nop 1
	v_permlane32_swap_b32_e32 v11, v12
	v_add_f32_e32 v11, v11, v12
	v_mul_f32_e32 v11, 0x3c000000, v11
	v_fma_f32 v7, v10, v7, -v11
	v_fma_f32 v8, v9, v8, -v11
	v_mul_f32_e32 v9, v7, v7
	v_fmac_f32_e32 v9, v8, v8
	s_nop 1
	v_add_f32_dpp v9, v9, v9 row_ror:8 row_mask:0xf bank_mask:0xf bound_ctrl:1
	s_nop 1
	v_add_f32_dpp v9, v9, v9 row_ror:4 row_mask:0xf bank_mask:0xf bound_ctrl:1
	s_nop 1
	v_add_f32_dpp v9, v9, v9 row_ror:2 row_mask:0xf bank_mask:0xf bound_ctrl:1
	s_nop 1
	v_add_f32_dpp v9, v9, v9 row_ror:1 row_mask:0xf bank_mask:0xf bound_ctrl:1
	ds_bpermute_b32 v10, v3, v9
	s_waitcnt lgkmcnt(0)
	v_add_f32_e32 v9, v9, v10
	v_mov_b32_e32 v10, v9
	s_nop 1
	v_permlane32_swap_b32_e32 v9, v10
	v_add_f32_e32 v9, v9, v10
	v_fmamk_f32 v9, v9, 0x3c000000, v177
	v_cmp_gt_f32_e32 vcc, s16, v9
	v_mul_f32_e32 v10, 0x4b800000, v9
	s_nop 0
	v_cndmask_b32_e32 v9, v9, v10, vcc
	v_rsq_f32_e32 v9, v9
	s_nop 0
	v_mul_f32_e32 v10, 0x45800000, v9
	v_cndmask_b32_e32 v9, v9, v10, vcc
	v_mul_f32_e32 v8, v8, v9
	v_cvt_pk_bf16_f32 v8, v8, v8
	v_add_u32_e32 v10, s5, v6
	v_mul_f32_e32 v7, v7, v9
	ds_write_b16 v10, v8
	s_add_i32 s5, s5, 2
	v_cvt_pk_bf16_f32 v7, v7, v7
	ds_write_b16 v10, v7 offset:272
	s_waitcnt vmcnt(14)
; DI bf16 f2bf(float f) { unsigned u = __float_as_uint(f); u += 0x7fffu + ((u >> 16) & 1u); return (bf16)(u >> 16); }
;   DI bf16* P() const { return (bf16*)(p.ws + WS_P); }
; DI float erf_as(float x) {
;   const float ax = fabsf(x);
;   const float t = __builtin_amdgcn_rcpf(1.f + 0.3275911f * ax);
;   const float poly = t * (0.254829592f + t * (-0.284496736f + t * (1.421413741f + t * (-1.453152027f + t * 1.061405429f))));
;   const float y = 1.f - poly * __builtin_amdgcn_exp2f(-1.4426950408889634f * ax * ax);
;   return copysignf(y, x);
; }
; DI float gelu(float x) { return 0.5f * x * (1.f + erf_as(x * 0.70710678118654752f)); }
; DI float logsigmoid(float z) { return fminf(z, 0.f) - log1pf(__expf(-fabsf(z))); }
; DI float logsigmoid_fast(float z) { return -0.6931471805599453f * __builtin_amdgcn_logf(1.f + __builtin_amdgcn_exp2f(-1.4426950408889634f * fmaxf(z, -80.f))); }
; template <int CTRL> DI float dpp_add(float v) { return v + __builtin_bit_cast(float, __builtin_amdgcn_update_dpp(0, __builtin_bit_cast(int, v), CTRL, 0xf, 0xf, false)); }
; DI float wave_sum(float v) {
;   v = dpp_add<0x128>(v); v = dpp_add<0x124>(v); v = dpp_add<0x122>(v); v = dpp_add<0x121>(v);
;   v += __shfl_xor(v, 16);
;   const unsigned u = __float_as_uint(v);
;   auto r = __builtin_amdgcn_permlane32_swap(u, u, false, false);
;   return __uint_as_float(r[0]) + __uint_as_float(r[1]);
; }
; DI void vgt_tile(const Ctx& c, int ti, bf16* lds) {
;     ...
;   for (int rr = 0; rr < 32; ++rr) {
;     const int t = wave * 32 + rr;
;     const unsigned u = *(const unsigned*)(c.P() + (size_t)(row0 + t) * LDP + C_V + g * 128 + 2 * lane);
;     const float a = gelu(__uint_as_float(u << 16)), b = gelu(__uint_as_float(u & 0xffff0000u));
;     const float mean = wave_sum(a + b) * (1.f / 128.f);
;     const float da = a - mean, db = b - mean;
;     const float rstd = rsqrtf(wave_sum(da * da + db * db) * (1.f / 128.f) + LN_EPS);
;     lds[(2 * lane) * LDT + t] = f2bf(da * rstd);
;     lds[(2 * lane + 1) * LDT + t] = f2bf(db * rstd);
;   }
	v_lshlrev_b32_e32 v8, 16, v37
	v_mul_f32_e32 v9, 0.5, v8
	v_mul_f32_e32 v8, 0x3f3504f3, v8
	v_fma_f32 v10, |v8|, s2, 1.0
	v_rcp_f32_e32 v10, v10
	v_and_b32_e32 v7, 0xffff0000, v37
	v_fmamk_f32 v11, v10, 0x3f87dc22, v176
	v_fmaak_f32 v11, v10, v11, 0x3fb5f0e3
	v_fmaak_f32 v11, v10, v11, 0xbe91a98e
	v_fmaak_f32 v11, v10, v11, 0x3e827906
	v_mul_f32_e32 v10, v10, v11
	v_mul_f32_e64 v11, |v8|, s3
	v_mul_f32_e64 v11, |v8|, v11
	v_exp_f32_e32 v11, v11
	s_nop 0
	v_fma_f32 v10, -v11, v10, 1.0
	v_bfi_b32 v8, s13, v10, v8
	v_mul_f32_e32 v10, 0.5, v7
	v_mul_f32_e32 v7, 0x3f3504f3, v7
	v_fma_f32 v11, |v7|, s2, 1.0
	v_rcp_f32_e32 v11, v11
	v_add_f32_e32 v8, 1.0, v8
	v_fmamk_f32 v12, v11, 0x3f87dc22, v176
	v_fmaak_f32 v12, v11, v12, 0x3fb5f0e3
	v_fmaak_f32 v12, v11, v12, 0xbe91a98e
	v_fmaak_f32 v12, v11, v12, 0x3e827906
	v_mul_f32_e32 v11, v11, v12
	v_mul_f32_e64 v12, |v7|, s3
	v_mul_f32_e64 v12, |v7|, v12
	v_exp_f32_e32 v12, v12
	s_nop 0
	v_fma_f32 v11, -v12, v11, 1.0
	v_bfi_b32 v7, s13, v11, v7
	v_add_f32_e32 v7, 1.0, v7
	v_mul_f32_e32 v11, v10, v7
	v_fmac_f32_e32 v11, v9, v8
	s_nop 1
	v_add_f32_dpp v11, v11, v11 row_ror:8 row_mask:0xf bank_mask:0xf bound_ctrl:1
	s_nop 1
	v_add_f32_dpp v11, v11, v11 row_ror:4 row_mask:0xf bank_mask:0xf bound_ctrl:1
	s_nop 1
	v_add_f32_dpp v11, v11, v11 row_ror:2 row_mask:0xf bank_mask:0xf bound_ctrl:1
	s_nop 1
	v_add_f32_dpp v11, v11, v11 row_ror:1 row_mask:0xf bank_mask:0xf bound_ctrl:1
	ds_bpermute_b32 v12, v3, v11
	s_waitcnt lgkmcnt(0)
	v_add_f32_e32 v11, v11, v12
	v_mov_b32_e32 v12, v11
	s_nop 1
	v_permlane32_swap_b32_e32 v11, v12
	v_add_f32_e32 v11, v11, v12
	v_mul_f32_e32 v11, 0x3c000000, v11
	v_fma_f32 v7, v10, v7, -v11
	v_fma_f32 v8, v9, v8, -v11
	v_mul_f32_e32 v9, v7, v7
	v_fmac_f32_e32 v9, v8, v8
	s_nop 1
	v_add_f32_dpp v9, v9, v9 row_ror:8 row_mask:0xf bank_mask:0xf bound_ctrl:1
	s_nop 1
	v_add_f32_dpp v9, v9, v9 row_ror:4 row_mask:0xf bank_mask:0xf bound_ctrl:1
	s_nop 1
	v_add_f32_dpp v9, v9, v9 row_ror:2 row_mask:0xf bank_mask:0xf bound_ctrl:1
	s_nop 1
	v_add_f32_dpp v9, v9, v9 row_ror:1 row_mask:0xf bank_mask:0xf bound_ctrl:1
	ds_bpermute_b32 v10, v3, v9
	s_waitcnt lgkmcnt(0)
	v_add_f32_e32 v9, v9, v10
	v_mov_b32_e32 v10, v9
	s_nop 1
	v_permlane32_swap_b32_e32 v9, v10
	v_add_f32_e32 v9, v9, v10
	v_fmamk_f32 v9, v9, 0x3c000000, v177
	v_cmp_gt_f32_e32 vcc, s16, v9
	v_mul_f32_e32 v10, 0x4b800000, v9
	s_nop 0
	v_cndmask_b32_e32 v9, v9, v10, vcc
	v_rsq_f32_e32 v9, v9
	s_nop 0
	v_mul_f32_e32 v10, 0x45800000, v9
	v_cndmask_b32_e32 v9, v9, v10, vcc
	v_mul_f32_e32 v8, v8, v9
	v_cvt_pk_bf16_f32 v8, v8, v8
	v_add_u32_e32 v10, s5, v6
	v_mul_f32_e32 v7, v7, v9
	ds_write_b16 v10, v8
	s_add_i32 s5, s5, 2
	v_cvt_pk_bf16_f32 v7, v7, v7
	ds_write_b16 v10, v7 offset:272
	s_waitcnt vmcnt(13)
	v_lshlrev_b32_e32 v8, 16, v38
	v_mul_f32_e32 v9, 0.5, v8
	v_mul_f32_e32 v8, 0x3f3504f3, v8
	v_fma_f32 v10, |v8|, s2, 1.0
	v_rcp_f32_e32 v10, v10
	v_and_b32_e32 v7, 0xffff0000, v38
	v_fmamk_f32 v11, v10, 0x3f87dc22, v176
	v_fmaak_f32 v11, v10, v11, 0x3fb5f0e3
	v_fmaak_f32 v11, v10, v11, 0xbe91a98e
	v_fmaak_f32 v11, v10, v11, 0x3e827906
	v_mul_f32_e32 v10, v10, v11
	v_mul_f32_e64 v11, |v8|, s3
	v_mul_f32_e64 v11, |v8|, v11
	v_exp_f32_e32 v11, v11
	s_nop 0
	v_fma_f32 v10, -v11, v10, 1.0
	v_bfi_b32 v8, s13, v10, v8
	v_mul_f32_e32 v10, 0.5, v7
	v_mul_f32_e32 v7, 0x3f3504f3, v7
	v_fma_f32 v11, |v7|, s2, 1.0
	v_rcp_f32_e32 v11, v11
	v_add_f32_e32 v8, 1.0, v8
	v_fmamk_f32 v12, v11, 0x3f87dc22, v176
	v_fmaak_f32 v12, v11, v12, 0x3fb5f0e3
	v_fmaak_f32 v12, v11, v12, 0xbe91a98e
	v_fmaak_f32 v12, v11, v12, 0x3e827906
	v_mul_f32_e32 v11, v11, v12
	v_mul_f32_e64 v12, |v7|, s3
	v_mul_f32_e64 v12, |v7|, v12
	v_exp_f32_e32 v12, v12
	s_nop 0
	v_fma_f32 v11, -v12, v11, 1.0
	v_bfi_b32 v7, s13, v11, v7
	v_add_f32_e32 v7, 1.0, v7
	v_mul_f32_e32 v11, v10, v7
	v_fmac_f32_e32 v11, v9, v8
	s_nop 1
	v_add_f32_dpp v11, v11, v11 row_ror:8 row_mask:0xf bank_mask:0xf bound_ctrl:1
	s_nop 1
	v_add_f32_dpp v11, v11, v11 row_ror:4 row_mask:0xf bank_mask:0xf bound_ctrl:1
	s_nop 1
	v_add_f32_dpp v11, v11, v11 row_ror:2 row_mask:0xf bank_mask:0xf bound_ctrl:1
	s_nop 1
	v_add_f32_dpp v11, v11, v11 row_ror:1 row_mask:0xf bank_mask:0xf bound_ctrl:1
	ds_bpermute_b32 v12, v3, v11
	s_waitcnt lgkmcnt(0)
	v_add_f32_e32 v11, v11, v12
	v_mov_b32_e32 v12, v11
	s_nop 1
	v_permlane32_swap_b32_e32 v11, v12
	v_add_f32_e32 v11, v11, v12
	v_mul_f32_e32 v11, 0x3c000000, v11
	v_fma_f32 v7, v10, v7, -v11
	v_fma_f32 v8, v9, v8, -v11
	v_mul_f32_e32 v9, v7, v7
	v_fmac_f32_e32 v9, v8, v8
	s_nop 1
	v_add_f32_dpp v9, v9, v9 row_ror:8 row_mask:0xf bank_mask:0xf bound_ctrl:1
	s_nop 1
	v_add_f32_dpp v9, v9, v9 row_ror:4 row_mask:0xf bank_mask:0xf bound_ctrl:1
	s_nop 1
	v_add_f32_dpp v9, v9, v9 row_ror:2 row_mask:0xf bank_mask:0xf bound_ctrl:1
	s_nop 1
	v_add_f32_dpp v9, v9, v9 row_ror:1 row_mask:0xf bank_mask:0xf bound_ctrl:1
	ds_bpermute_b32 v10, v3, v9
	s_waitcnt lgkmcnt(0)
	v_add_f32_e32 v9, v9, v10
	v_mov_b32_e32 v10, v9
	s_nop 1
	v_permlane32_swap_b32_e32 v9, v10
	v_add_f32_e32 v9, v9, v10
	v_fmamk_f32 v9, v9, 0x3c000000, v177
	v_cmp_gt_f32_e32 vcc, s16, v9
	v_mul_f32_e32 v10, 0x4b800000, v9
	s_nop 0
	v_cndmask_b32_e32 v9, v9, v10, vcc
	v_rsq_f32_e32 v9, v9
	s_nop 0
	v_mul_f32_e32 v10, 0x45800000, v9
	v_cndmask_b32_e32 v9, v9, v10, vcc
	v_mul_f32_e32 v8, v8, v9
	v_cvt_pk_bf16_f32 v8, v8, v8
	v_add_u32_e32 v10, s5, v6
	v_mul_f32_e32 v7, v7, v9
	ds_write_b16 v10, v8
	s_add_i32 s5, s5, 2
	v_cvt_pk_bf16_f32 v7, v7, v7
	ds_write_b16 v10, v7 offset:272
	s_waitcnt vmcnt(12)
; DI bf16 f2bf(float f) { unsigned u = __float_as_uint(f); u += 0x7fffu + ((u >> 16) & 1u); return (bf16)(u >> 16); }
;   DI bf16* P() const { return (bf16*)(p.ws + WS_P); }
; DI float erf_as(float x) {
;   const float ax = fabsf(x);
;   const float t = __builtin_amdgcn_rcpf(1.f + 0.3275911f * ax);
;   const float poly = t * (0.254829592f + t * (-0.284496736f + t * (1.421413741f + t * (-1.453152027f + t * 1.061405429f))));
;   const float y = 1.f - poly * __builtin_amdgcn_exp2f(-1.4426950408889634f * ax * ax);
;   return copysignf(y, x);
; }
; DI float gelu(float x) { return 0.5f * x * (1.f + erf_as(x * 0.70710678118654752f)); }
; DI float logsigmoid(float z) { return fminf(z, 0.f) - log1pf(__expf(-fabsf(z))); }
; DI float logsigmoid_fast(float z) { return -0.6931471805599453f * __builtin_amdgcn_logf(1.f + __builtin_amdgcn_exp2f(-1.4426950408889634f * fmaxf(z, -80.f))); }
; template <int CTRL> DI float dpp_add(float v) { return v + __builtin_bit_cast(float, __builtin_amdgcn_update_dpp(0, __builtin_bit_cast(int, v), CTRL, 0xf, 0xf, false)); }
; DI float wave_sum(float v) {
;   v = dpp_add<0x128>(v); v = dpp_add<0x124>(v); v = dpp_add<0x122>(v); v = dpp_add<0x121>(v);
;   v += __shfl_xor(v, 16);
;   const unsigned u = __float_as_uint(v);
;   auto r = __builtin_amdgcn_permlane32_swap(u, u, false, false);
;   return __uint_as_float(r[0]) + __uint_as_float(r[1]);
; }
; DI void vgt_tile(const Ctx& c, int ti, bf16* lds) {
;     ...
;   for (int rr = 0; rr < 32; ++rr) {
;     const int t = wave * 32 + rr;
;     const unsigned u = *(const unsigned*)(c.P() + (size_t)(row0 + t) * LDP + C_V + g * 128 + 2 * lane);
;     const float a = gelu(__uint_as_float(u << 16)), b = gelu(__uint_as_float(u & 0xffff0000u));
;     const float mean = wave_sum(a + b) * (1.f / 128.f);
;     const float da = a - mean, db = b - mean;
;     const float rstd = rsqrtf(wave_sum(da * da + db * db) * (1.f / 128.f) + LN_EPS);
;     lds[(2 * lane) * LDT + t] = f2bf(da * rstd);
;     lds[(2 * lane + 1) * LDT + t] = f2bf(db * rstd);
;   }
	v_lshlrev_b32_e32 v8, 16, v39
	v_mul_f32_e32 v9, 0.5, v8
	v_mul_f32_e32 v8, 0x3f3504f3, v8
	v_fma_f32 v10, |v8|, s2, 1.0
	v_rcp_f32_e32 v10, v10
	v_and_b32_e32 v7, 0xffff0000, v39
	v_fmamk_f32 v11, v10, 0x3f87dc22, v176
	v_fmaak_f32 v11, v10, v11, 0x3fb5f0e3
	v_fmaak_f32 v11, v10, v11, 0xbe91a98e
	v_fmaak_f32 v11, v10, v11, 0x3e827906
	v_mul_f32_e32 v10, v10, v11
	v_mul_f32_e64 v11, |v8|, s3
	v_mul_f32_e64 v11, |v8|, v11
	v_exp_f32_e32 v11, v11
	s_nop 0
	v_fma_f32 v10, -v11, v10, 1.0
	v_bfi_b32 v8, s13, v10, v8
	v_mul_f32_e32 v10, 0.5, v7
	v_mul_f32_e32 v7, 0x3f3504f3, v7
	v_fma_f32 v11, |v7|, s2, 1.0
	v_rcp_f32_e32 v11, v11
	v_add_f32_e32 v8, 1.0, v8
	v_fmamk_f32 v12, v11, 0x3f87dc22, v176
	v_fmaak_f32 v12, v11, v12, 0x3fb5f0e3
	v_fmaak_f32 v12, v11, v12, 0xbe91a98e
	v_fmaak_f32 v12, v11, v12, 0x3e827906
	v_mul_f32_e32 v11, v11, v12
	v_mul_f32_e64 v12, |v7|, s3
	v_mul_f32_e64 v12, |v7|, v12
	v_exp_f32_e32 v12, v12
	s_nop 0
	v_fma_f32 v11, -v12, v11, 1.0
	v_bfi_b32 v7, s13, v11, v7
	v_add_f32_e32 v7, 1.0, v7
	v_mul_f32_e32 v11, v10, v7
	v_fmac_f32_e32 v11, v9, v8
	s_nop 1
	v_add_f32_dpp v11, v11, v11 row_ror:8 row_mask:0xf bank_mask:0xf bound_ctrl:1
	s_nop 1
	v_add_f32_dpp v11, v11, v11 row_ror:4 row_mask:0xf bank_mask:0xf bound_ctrl:1
	s_nop 1
	v_add_f32_dpp v11, v11, v11 row_ror:2 row_mask:0xf bank_mask:0xf bound_ctrl:1
	s_nop 1
	v_add_f32_dpp v11, v11, v11 row_ror:1 row_mask:0xf bank_mask:0xf bound_ctrl:1
	ds_bpermute_b32 v12, v3, v11
	s_waitcnt lgkmcnt(0)
	v_add_f32_e32 v11, v11, v12
	v_mov_b32_e32 v12, v11
	s_nop 1
	v_permlane32_swap_b32_e32 v11, v12
	v_add_f32_e32 v11, v11, v12
	v_mul_f32_e32 v11, 0x3c000000, v11
	v_fma_f32 v7, v10, v7, -v11
	v_fma_f32 v8, v9, v8, -v11
	v_mul_f32_e32 v9, v7, v7
	v_fmac_f32_e32 v9, v8, v8
	s_nop 1
	v_add_f32_dpp v9, v9, v9 row_ror:8 row_mask:0xf bank_mask:0xf bound_ctrl:1
	s_nop 1
	v_add_f32_dpp v9, v9, v9 row_ror:4 row_mask:0xf bank_mask:0xf bound_ctrl:1
	s_nop 1
	v_add_f32_dpp v9, v9, v9 row_ror:2 row_mask:0xf bank_mask:0xf bound_ctrl:1
	s_nop 1
	v_add_f32_dpp v9, v9, v9 row_ror:1 row_mask:0xf bank_mask:0xf bound_ctrl:1
	ds_bpermute_b32 v10, v3, v9
	s_waitcnt lgkmcnt(0)
	v_add_f32_e32 v9, v9, v10
	v_mov_b32_e32 v10, v9
	s_nop 1
	v_permlane32_swap_b32_e32 v9, v10
	v_add_f32_e32 v9, v9, v10
	v_fmamk_f32 v9, v9, 0x3c000000, v177
	v_cmp_gt_f32_e32 vcc, s16, v9
	v_mul_f32_e32 v10, 0x4b800000, v9
	s_nop 0
	v_cndmask_b32_e32 v9, v9, v10, vcc
	v_rsq_f32_e32 v9, v9
	s_nop 0
	v_mul_f32_e32 v10, 0x45800000, v9
	v_cndmask_b32_e32 v9, v9, v10, vcc
	v_mul_f32_e32 v8, v8, v9
	v_cvt_pk_bf16_f32 v8, v8, v8
	v_add_u32_e32 v10, s5, v6
	v_mul_f32_e32 v7, v7, v9
	ds_write_b16 v10, v8
	s_add_i32 s5, s5, 2
	v_cvt_pk_bf16_f32 v7, v7, v7
	ds_write_b16 v10, v7 offset:272
	s_waitcnt vmcnt(11)
	v_lshlrev_b32_e32 v8, 16, v40
	v_mul_f32_e32 v9, 0.5, v8
	v_mul_f32_e32 v8, 0x3f3504f3, v8
	v_fma_f32 v10, |v8|, s2, 1.0
	v_rcp_f32_e32 v10, v10
	v_and_b32_e32 v7, 0xffff0000, v40
	v_fmamk_f32 v11, v10, 0x3f87dc22, v176
	v_fmaak_f32 v11, v10, v11, 0x3fb5f0e3
	v_fmaak_f32 v11, v10, v11, 0xbe91a98e
	v_fmaak_f32 v11, v10, v11, 0x3e827906
	v_mul_f32_e32 v10, v10, v11
	v_mul_f32_e64 v11, |v8|, s3
	v_mul_f32_e64 v11, |v8|, v11
	v_exp_f32_e32 v11, v11
	s_nop 0
	v_fma_f32 v10, -v11, v10, 1.0
	v_bfi_b32 v8, s13, v10, v8
	v_mul_f32_e32 v10, 0.5, v7
	v_mul_f32_e32 v7, 0x3f3504f3, v7
	v_fma_f32 v11, |v7|, s2, 1.0
	v_rcp_f32_e32 v11, v11
	v_add_f32_e32 v8, 1.0, v8
	v_fmamk_f32 v12, v11, 0x3f87dc22, v176
	v_fmaak_f32 v12, v11, v12, 0x3fb5f0e3
	v_fmaak_f32 v12, v11, v12, 0xbe91a98e
	v_fmaak_f32 v12, v11, v12, 0x3e827906
	v_mul_f32_e32 v11, v11, v12
	v_mul_f32_e64 v12, |v7|, s3
	v_mul_f32_e64 v12, |v7|, v12
	v_exp_f32_e32 v12, v12
	s_nop 0
	v_fma_f32 v11, -v12, v11, 1.0
	v_bfi_b32 v7, s13, v11, v7
	v_add_f32_e32 v7, 1.0, v7
	v_mul_f32_e32 v11, v10, v7
	v_fmac_f32_e32 v11, v9, v8
	s_nop 1
	v_add_f32_dpp v11, v11, v11 row_ror:8 row_mask:0xf bank_mask:0xf bound_ctrl:1
	s_nop 1
	v_add_f32_dpp v11, v11, v11 row_ror:4 row_mask:0xf bank_mask:0xf bound_ctrl:1
	s_nop 1
	v_add_f32_dpp v11, v11, v11 row_ror:2 row_mask:0xf bank_mask:0xf bound_ctrl:1
	s_nop 1
	v_add_f32_dpp v11, v11, v11 row_ror:1 row_mask:0xf bank_mask:0xf bound_ctrl:1
	ds_bpermute_b32 v12, v3, v11
	s_waitcnt lgkmcnt(0)
	v_add_f32_e32 v11, v11, v12
	v_mov_b32_e32 v12, v11
	s_nop 1
	v_permlane32_swap_b32_e32 v11, v12
	v_add_f32_e32 v11, v11, v12
	v_mul_f32_e32 v11, 0x3c000000, v11
	v_fma_f32 v7, v10, v7, -v11
	v_fma_f32 v8, v9, v8, -v11
	v_mul_f32_e32 v9, v7, v7
	v_fmac_f32_e32 v9, v8, v8
	s_nop 1
	v_add_f32_dpp v9, v9, v9 row_ror:8 row_mask:0xf bank_mask:0xf bound_ctrl:1
	s_nop 1
	v_add_f32_dpp v9, v9, v9 row_ror:4 row_mask:0xf bank_mask:0xf bound_ctrl:1
	s_nop 1
	v_add_f32_dpp v9, v9, v9 row_ror:2 row_mask:0xf bank_mask:0xf bound_ctrl:1
	s_nop 1
	v_add_f32_dpp v9, v9, v9 row_ror:1 row_mask:0xf bank_mask:0xf bound_ctrl:1
	ds_bpermute_b32 v10, v3, v9
	s_waitcnt lgkmcnt(0)
	v_add_f32_e32 v9, v9, v10
	v_mov_b32_e32 v10, v9
	s_nop 1
	v_permlane32_swap_b32_e32 v9, v10
	v_add_f32_e32 v9, v9, v10
	v_fmamk_f32 v9, v9, 0x3c000000, v177
	v_cmp_gt_f32_e32 vcc, s16, v9
	v_mul_f32_e32 v10, 0x4b800000, v9
	s_nop 0
	v_cndmask_b32_e32 v9, v9, v10, vcc
	v_rsq_f32_e32 v9, v9
	s_nop 0
	v_mul_f32_e32 v10, 0x45800000, v9
	v_cndmask_b32_e32 v9, v9, v10, vcc
	v_mul_f32_e32 v8, v8, v9
	v_cvt_pk_bf16_f32 v8, v8, v8
	v_add_u32_e32 v10, s5, v6
	v_mul_f32_e32 v7, v7, v9
	ds_write_b16 v10, v8
	s_add_i32 s5, s5, 2
	v_cvt_pk_bf16_f32 v7, v7, v7
	ds_write_b16 v10, v7 offset:272
	s_waitcnt vmcnt(10)
; DI bf16 f2bf(float f) { unsigned u = __float_as_uint(f); u += 0x7fffu + ((u >> 16) & 1u); return (bf16)(u >> 16); }
;   DI bf16* P() const { return (bf16*)(p.ws + WS_P); }
; DI float erf_as(float x) {
;   const float ax = fabsf(x);
;   const float t = __builtin_amdgcn_rcpf(1.f + 0.3275911f * ax);
;   const float poly = t * (0.254829592f + t * (-0.284496736f + t * (1.421413741f + t * (-1.453152027f + t * 1.061405429f))));
;   const float y = 1.f - poly * __builtin_amdgcn_exp2f(-1.4426950408889634f * ax * ax);
;   return copysignf(y, x);
; }
; DI float gelu(float x) { return 0.5f * x * (1.f + erf_as(x * 0.70710678118654752f)); }
; DI float logsigmoid(float z) { return fminf(z, 0.f) - log1pf(__expf(-fabsf(z))); }
; DI float logsigmoid_fast(float z) { return -0.6931471805599453f * __builtin_amdgcn_logf(1.f + __builtin_amdgcn_exp2f(-1.4426950408889634f * fmaxf(z, -80.f))); }
; template <int CTRL> DI float dpp_add(float v) { return v + __builtin_bit_cast(float, __builtin_amdgcn_update_dpp(0, __builtin_bit_cast(int, v), CTRL, 0xf, 0xf, false)); }
; DI float wave_sum(float v) {
;   v = dpp_add<0x128>(v); v = dpp_add<0x124>(v); v = dpp_add<0x122>(v); v = dpp_add<0x121>(v);
;   v += __shfl_xor(v, 16);
;   const unsigned u = __float_as_uint(v);
;   auto r = __builtin_amdgcn_permlane32_swap(u, u, false, false);
;   return __uint_as_float(r[0]) + __uint_as_float(r[1]);
; }
; DI void vgt_tile(const Ctx& c, int ti, bf16* lds) {
;     ...
;   for (int rr = 0; rr < 32; ++rr) {
;     const int t = wave * 32 + rr;
;     const unsigned u = *(const unsigned*)(c.P() + (size_t)(row0 + t) * LDP + C_V + g * 128 + 2 * lane);
;     const float a = gelu(__uint_as_float(u << 16)), b = gelu(__uint_as_float(u & 0xffff0000u));
;     const float mean = wave_sum(a + b) * (1.f / 128.f);
;     const float da = a - mean, db = b - mean;
;     const float rstd = rsqrtf(wave_sum(da * da + db * db) * (1.f / 128.f) + LN_EPS);
;     lds[(2 * lane) * LDT + t] = f2bf(da * rstd);
;     lds[(2 * lane + 1) * LDT + t] = f2bf(db * rstd);
;   }
	v_lshlrev_b32_e32 v8, 16, v41
	v_mul_f32_e32 v9, 0.5, v8
	v_mul_f32_e32 v8, 0x3f3504f3, v8
	v_fma_f32 v10, |v8|, s2, 1.0
	v_rcp_f32_e32 v10, v10
	v_and_b32_e32 v7, 0xffff0000, v41
	v_fmamk_f32 v11, v10, 0x3f87dc22, v176
	v_fmaak_f32 v11, v10, v11, 0x3fb5f0e3
	v_fmaak_f32 v11, v10, v11, 0xbe91a98e
	v_fmaak_f32 v11, v10, v11, 0x3e827906
	v_mul_f32_e32 v10, v10, v11
	v_mul_f32_e64 v11, |v8|, s3
	v_mul_f32_e64 v11, |v8|, v11
	v_exp_f32_e32 v11, v11
	s_nop 0
	v_fma_f32 v10, -v11, v10, 1.0
	v_bfi_b32 v8, s13, v10, v8
	v_mul_f32_e32 v10, 0.5, v7
	v_mul_f32_e32 v7, 0x3f3504f3, v7
	v_fma_f32 v11, |v7|, s2, 1.0
	v_rcp_f32_e32 v11, v11
	v_add_f32_e32 v8, 1.0, v8
	v_fmamk_f32 v12, v11, 0x3f87dc22, v176
	v_fmaak_f32 v12, v11, v12, 0x3fb5f0e3
	v_fmaak_f32 v12, v11, v12, 0xbe91a98e
	v_fmaak_f32 v12, v11, v12, 0x3e827906
	v_mul_f32_e32 v11, v11, v12
	v_mul_f32_e64 v12, |v7|, s3
	v_mul_f32_e64 v12, |v7|, v12
	v_exp_f32_e32 v12, v12
	s_nop 0
	v_fma_f32 v11, -v12, v11, 1.0
	v_bfi_b32 v7, s13, v11, v7
	v_add_f32_e32 v7, 1.0, v7
	v_mul_f32_e32 v11, v10, v7
	v_fmac_f32_e32 v11, v9, v8
	s_nop 1
	v_add_f32_dpp v11, v11, v11 row_ror:8 row_mask:0xf bank_mask:0xf bound_ctrl:1
	s_nop 1
	v_add_f32_dpp v11, v11, v11 row_ror:4 row_mask:0xf bank_mask:0xf bound_ctrl:1
	s_nop 1
	v_add_f32_dpp v11, v11, v11 row_ror:2 row_mask:0xf bank_mask:0xf bound_ctrl:1
	s_nop 1
	v_add_f32_dpp v11, v11, v11 row_ror:1 row_mask:0xf bank_mask:0xf bound_ctrl:1
	ds_bpermute_b32 v12, v3, v11
	s_waitcnt lgkmcnt(0)
	v_add_f32_e32 v11, v11, v12
	v_mov_b32_e32 v12, v11
	s_nop 1
	v_permlane32_swap_b32_e32 v11, v12
	v_add_f32_e32 v11, v11, v12
	v_mul_f32_e32 v11, 0x3c000000, v11
	v_fma_f32 v7, v10, v7, -v11
	v_fma_f32 v8, v9, v8, -v11
	v_mul_f32_e32 v9, v7, v7
	v_fmac_f32_e32 v9, v8, v8
	s_nop 1
	v_add_f32_dpp v9, v9, v9 row_ror:8 row_mask:0xf bank_mask:0xf bound_ctrl:1
	s_nop 1
	v_add_f32_dpp v9, v9, v9 row_ror:4 row_mask:0xf bank_mask:0xf bound_ctrl:1
	s_nop 1
	v_add_f32_dpp v9, v9, v9 row_ror:2 row_mask:0xf bank_mask:0xf bound_ctrl:1
	s_nop 1
	v_add_f32_dpp v9, v9, v9 row_ror:1 row_mask:0xf bank_mask:0xf bound_ctrl:1
	ds_bpermute_b32 v10, v3, v9
	s_waitcnt lgkmcnt(0)
	v_add_f32_e32 v9, v9, v10
	v_mov_b32_e32 v10, v9
	s_nop 1
	v_permlane32_swap_b32_e32 v9, v10
	v_add_f32_e32 v9, v9, v10
	v_fmamk_f32 v9, v9, 0x3c000000, v177
	v_cmp_gt_f32_e32 vcc, s16, v9
	v_mul_f32_e32 v10, 0x4b800000, v9
	s_nop 0
	v_cndmask_b32_e32 v9, v9, v10, vcc
	v_rsq_f32_e32 v9, v9
	s_nop 0
	v_mul_f32_e32 v10, 0x45800000, v9
	v_cndmask_b32_e32 v9, v9, v10, vcc
	v_mul_f32_e32 v8, v8, v9
	v_cvt_pk_bf16_f32 v8, v8, v8
	v_add_u32_e32 v10, s5, v6
	v_mul_f32_e32 v7, v7, v9
	ds_write_b16 v10, v8
	s_add_i32 s5, s5, 2
	v_cvt_pk_bf16_f32 v7, v7, v7
	ds_write_b16 v10, v7 offset:272
	s_waitcnt vmcnt(9)
	v_lshlrev_b32_e32 v8, 16, v42
	v_mul_f32_e32 v9, 0.5, v8
	v_mul_f32_e32 v8, 0x3f3504f3, v8
	v_fma_f32 v10, |v8|, s2, 1.0
	v_rcp_f32_e32 v10, v10
	v_and_b32_e32 v7, 0xffff0000, v42
	v_fmamk_f32 v11, v10, 0x3f87dc22, v176
	v_fmaak_f32 v11, v10, v11, 0x3fb5f0e3
	v_fmaak_f32 v11, v10, v11, 0xbe91a98e
	v_fmaak_f32 v11, v10, v11, 0x3e827906
	v_mul_f32_e32 v10, v10, v11
	v_mul_f32_e64 v11, |v8|, s3
	v_mul_f32_e64 v11, |v8|, v11
	v_exp_f32_e32 v11, v11
	s_nop 0
	v_fma_f32 v10, -v11, v10, 1.0
	v_bfi_b32 v8, s13, v10, v8
	v_mul_f32_e32 v10, 0.5, v7
	v_mul_f32_e32 v7, 0x3f3504f3, v7
	v_fma_f32 v11, |v7|, s2, 1.0
	v_rcp_f32_e32 v11, v11
	v_add_f32_e32 v8, 1.0, v8
	v_fmamk_f32 v12, v11, 0x3f87dc22, v176
	v_fmaak_f32 v12, v11, v12, 0x3fb5f0e3
	v_fmaak_f32 v12, v11, v12, 0xbe91a98e
	v_fmaak_f32 v12, v11, v12, 0x3e827906
	v_mul_f32_e32 v11, v11, v12
	v_mul_f32_e64 v12, |v7|, s3
	v_mul_f32_e64 v12, |v7|, v12
	v_exp_f32_e32 v12, v12
	s_nop 0
	v_fma_f32 v11, -v12, v11, 1.0
	v_bfi_b32 v7, s13, v11, v7
	v_add_f32_e32 v7, 1.0, v7
	v_mul_f32_e32 v11, v10, v7
	v_fmac_f32_e32 v11, v9, v8
	s_nop 1
	v_add_f32_dpp v11, v11, v11 row_ror:8 row_mask:0xf bank_mask:0xf bound_ctrl:1
	s_nop 1
	v_add_f32_dpp v11, v11, v11 row_ror:4 row_mask:0xf bank_mask:0xf bound_ctrl:1
	s_nop 1
	v_add_f32_dpp v11, v11, v11 row_ror:2 row_mask:0xf bank_mask:0xf bound_ctrl:1
	s_nop 1
	v_add_f32_dpp v11, v11, v11 row_ror:1 row_mask:0xf bank_mask:0xf bound_ctrl:1
	ds_bpermute_b32 v12, v3, v11
	s_waitcnt lgkmcnt(0)
	v_add_f32_e32 v11, v11, v12
	v_mov_b32_e32 v12, v11
	s_nop 1
	v_permlane32_swap_b32_e32 v11, v12
	v_add_f32_e32 v11, v11, v12
	v_mul_f32_e32 v11, 0x3c000000, v11
	v_fma_f32 v7, v10, v7, -v11
	v_fma_f32 v8, v9, v8, -v11
	v_mul_f32_e32 v9, v7, v7
	v_fmac_f32_e32 v9, v8, v8
	s_nop 1
	v_add_f32_dpp v9, v9, v9 row_ror:8 row_mask:0xf bank_mask:0xf bound_ctrl:1
	s_nop 1
	v_add_f32_dpp v9, v9, v9 row_ror:4 row_mask:0xf bank_mask:0xf bound_ctrl:1
	s_nop 1
	v_add_f32_dpp v9, v9, v9 row_ror:2 row_mask:0xf bank_mask:0xf bound_ctrl:1
	s_nop 1
	v_add_f32_dpp v9, v9, v9 row_ror:1 row_mask:0xf bank_mask:0xf bound_ctrl:1
	ds_bpermute_b32 v10, v3, v9
	s_waitcnt lgkmcnt(0)
	v_add_f32_e32 v9, v9, v10
	v_mov_b32_e32 v10, v9
	s_nop 1
	v_permlane32_swap_b32_e32 v9, v10
	v_add_f32_e32 v9, v9, v10
	v_fmamk_f32 v9, v9, 0x3c000000, v177
	v_cmp_gt_f32_e32 vcc, s16, v9
	v_mul_f32_e32 v10, 0x4b800000, v9
	s_nop 0
	v_cndmask_b32_e32 v9, v9, v10, vcc
	v_rsq_f32_e32 v9, v9
	s_nop 0
	v_mul_f32_e32 v10, 0x45800000, v9
	v_cndmask_b32_e32 v9, v9, v10, vcc
	v_mul_f32_e32 v8, v8, v9
	v_cvt_pk_bf16_f32 v8, v8, v8
	v_add_u32_e32 v10, s5, v6
	v_mul_f32_e32 v7, v7, v9
	ds_write_b16 v10, v8
	s_add_i32 s5, s5, 2
	v_cvt_pk_bf16_f32 v7, v7, v7
	ds_write_b16 v10, v7 offset:272
	s_waitcnt vmcnt(8)
; DI bf16 f2bf(float f) { unsigned u = __float_as_uint(f); u += 0x7fffu + ((u >> 16) & 1u); return (bf16)(u >> 16); }
;   DI bf16* P() const { return (bf16*)(p.ws + WS_P); }
; DI float erf_as(float x) {
;   const float ax = fabsf(x);
;   const float t = __builtin_amdgcn_rcpf(1.f + 0.3275911f * ax);
;   const float poly = t * (0.254829592f + t * (-0.284496736f + t * (1.421413741f + t * (-1.453152027f + t * 1.061405429f))));
;   const float y = 1.f - poly * __builtin_amdgcn_exp2f(-1.4426950408889634f * ax * ax);
;   return copysignf(y, x);
; }
; DI float gelu(float x) { return 0.5f * x * (1.f + erf_as(x * 0.70710678118654752f)); }
; DI float logsigmoid(float z) { return fminf(z, 0.f) - log1pf(__expf(-fabsf(z))); }
; DI float logsigmoid_fast(float z) { return -0.6931471805599453f * __builtin_amdgcn_logf(1.f + __builtin_amdgcn_exp2f(-1.4426950408889634f * fmaxf(z, -80.f))); }
; template <int CTRL> DI float dpp_add(float v) { return v + __builtin_bit_cast(float, __builtin_amdgcn_update_dpp(0, __builtin_bit_cast(int, v), CTRL, 0xf, 0xf, false)); }
; DI float wave_sum(float v) {
;   v = dpp_add<0x128>(v); v = dpp_add<0x124>(v); v = dpp_add<0x122>(v); v = dpp_add<0x121>(v);
;   v += __shfl_xor(v, 16);
;   const unsigned u = __float_as_uint(v);
;   auto r = __builtin_amdgcn_permlane32_swap(u, u, false, false);
;   return __uint_as_float(r[0]) + __uint_as_float(r[1]);
; }
; DI void vgt_tile(const Ctx& c, int ti, bf16* lds) {
;     ...
;   for (int rr = 0; rr < 32; ++rr) {
;     const int t = wave * 32 + rr;
;     const unsigned u = *(const unsigned*)(c.P() + (size_t)(row0 + t) * LDP + C_V + g * 128 + 2 * lane);
;     const float a = gelu(__uint_as_float(u << 16)), b = gelu(__uint_as_float(u & 0xffff0000u));
;     const float mean = wave_sum(a + b) * (1.f / 128.f);
;     const float da = a - mean, db = b - mean;
;     const float rstd = rsqrtf(wave_sum(da * da + db * db) * (1.f / 128.f) + LN_EPS);
;     lds[(2 * lane) * LDT + t] = f2bf(da * rstd);
;     lds[(2 * lane + 1) * LDT + t] = f2bf(db * rstd);
;   }
	v_lshlrev_b32_e32 v8, 16, v43
	v_mul_f32_e32 v9, 0.5, v8
	v_mul_f32_e32 v8, 0x3f3504f3, v8
	v_fma_f32 v10, |v8|, s2, 1.0
	v_rcp_f32_e32 v10, v10
	v_and_b32_e32 v7, 0xffff0000, v43
	v_fmamk_f32 v11, v10, 0x3f87dc22, v176
	v_fmaak_f32 v11, v10, v11, 0x3fb5f0e3
	v_fmaak_f32 v11, v10, v11, 0xbe91a98e
	v_fmaak_f32 v11, v10, v11, 0x3e827906
	v_mul_f32_e32 v10, v10, v11
	v_mul_f32_e64 v11, |v8|, s3
	v_mul_f32_e64 v11, |v8|, v11
	v_exp_f32_e32 v11, v11
	s_nop 0
	v_fma_f32 v10, -v11, v10, 1.0
	v_bfi_b32 v8, s13, v10, v8
	v_mul_f32_e32 v10, 0.5, v7
	v_mul_f32_e32 v7, 0x3f3504f3, v7
	v_fma_f32 v11, |v7|, s2, 1.0
	v_rcp_f32_e32 v11, v11
	v_add_f32_e32 v8, 1.0, v8
	v_fmamk_f32 v12, v11, 0x3f87dc22, v176
	v_fmaak_f32 v12, v11, v12, 0x3fb5f0e3
	v_fmaak_f32 v12, v11, v12, 0xbe91a98e
	v_fmaak_f32 v12, v11, v12, 0x3e827906
	v_mul_f32_e32 v11, v11, v12
	v_mul_f32_e64 v12, |v7|, s3
	v_mul_f32_e64 v12, |v7|, v12
	v_exp_f32_e32 v12, v12
	s_nop 0
	v_fma_f32 v11, -v12, v11, 1.0
	v_bfi_b32 v7, s13, v11, v7
	v_add_f32_e32 v7, 1.0, v7
	v_mul_f32_e32 v11, v10, v7
	v_fmac_f32_e32 v11, v9, v8
	s_nop 1
	v_add_f32_dpp v11, v11, v11 row_ror:8 row_mask:0xf bank_mask:0xf bound_ctrl:1
	s_nop 1
	v_add_f32_dpp v11, v11, v11 row_ror:4 row_mask:0xf bank_mask:0xf bound_ctrl:1
	s_nop 1
	v_add_f32_dpp v11, v11, v11 row_ror:2 row_mask:0xf bank_mask:0xf bound_ctrl:1
	s_nop 1
	v_add_f32_dpp v11, v11, v11 row_ror:1 row_mask:0xf bank_mask:0xf bound_ctrl:1
	ds_bpermute_b32 v12, v3, v11
	s_waitcnt lgkmcnt(0)
	v_add_f32_e32 v11, v11, v12
	v_mov_b32_e32 v12, v11
	s_nop 1
	v_permlane32_swap_b32_e32 v11, v12
	v_add_f32_e32 v11, v11, v12
	v_mul_f32_e32 v11, 0x3c000000, v11
	v_fma_f32 v7, v10, v7, -v11
	v_fma_f32 v8, v9, v8, -v11
	v_mul_f32_e32 v9, v7, v7
	v_fmac_f32_e32 v9, v8, v8
	s_nop 1
	v_add_f32_dpp v9, v9, v9 row_ror:8 row_mask:0xf bank_mask:0xf bound_ctrl:1
	s_nop 1
	v_add_f32_dpp v9, v9, v9 row_ror:4 row_mask:0xf bank_mask:0xf bound_ctrl:1
	s_nop 1
	v_add_f32_dpp v9, v9, v9 row_ror:2 row_mask:0xf bank_mask:0xf bound_ctrl:1
	s_nop 1
	v_add_f32_dpp v9, v9, v9 row_ror:1 row_mask:0xf bank_mask:0xf bound_ctrl:1
	ds_bpermute_b32 v10, v3, v9
	s_waitcnt lgkmcnt(0)
	v_add_f32_e32 v9, v9, v10
	v_mov_b32_e32 v10, v9
	s_nop 1
	v_permlane32_swap_b32_e32 v9, v10
	v_add_f32_e32 v9, v9, v10
	v_fmamk_f32 v9, v9, 0x3c000000, v177
	v_cmp_gt_f32_e32 vcc, s16, v9
	v_mul_f32_e32 v10, 0x4b800000, v9
	s_nop 0
	v_cndmask_b32_e32 v9, v9, v10, vcc
	v_rsq_f32_e32 v9, v9
	s_nop 0
	v_mul_f32_e32 v10, 0x45800000, v9
	v_cndmask_b32_e32 v9, v9, v10, vcc
	v_mul_f32_e32 v8, v8, v9
	v_cvt_pk_bf16_f32 v8, v8, v8
	v_add_u32_e32 v10, s5, v6
	v_mul_f32_e32 v7, v7, v9
	ds_write_b16 v10, v8
	s_add_i32 s5, s5, 2
	v_cvt_pk_bf16_f32 v7, v7, v7
	ds_write_b16 v10, v7 offset:272
	s_waitcnt vmcnt(7)
	v_lshlrev_b32_e32 v8, 16, v44
	v_mul_f32_e32 v9, 0.5, v8
	v_mul_f32_e32 v8, 0x3f3504f3, v8
	v_fma_f32 v10, |v8|, s2, 1.0
	v_rcp_f32_e32 v10, v10
	v_and_b32_e32 v7, 0xffff0000, v44
	v_fmamk_f32 v11, v10, 0x3f87dc22, v176
	v_fmaak_f32 v11, v10, v11, 0x3fb5f0e3
	v_fmaak_f32 v11, v10, v11, 0xbe91a98e
	v_fmaak_f32 v11, v10, v11, 0x3e827906
	v_mul_f32_e32 v10, v10, v11
	v_mul_f32_e64 v11, |v8|, s3
	v_mul_f32_e64 v11, |v8|, v11
	v_exp_f32_e32 v11, v11
	s_nop 0
	v_fma_f32 v10, -v11, v10, 1.0
	v_bfi_b32 v8, s13, v10, v8
	v_mul_f32_e32 v10, 0.5, v7
	v_mul_f32_e32 v7, 0x3f3504f3, v7
	v_fma_f32 v11, |v7|, s2, 1.0
	v_rcp_f32_e32 v11, v11
	v_add_f32_e32 v8, 1.0, v8
	v_fmamk_f32 v12, v11, 0x3f87dc22, v176
	v_fmaak_f32 v12, v11, v12, 0x3fb5f0e3
	v_fmaak_f32 v12, v11, v12, 0xbe91a98e
	v_fmaak_f32 v12, v11, v12, 0x3e827906
	v_mul_f32_e32 v11, v11, v12
	v_mul_f32_e64 v12, |v7|, s3
	v_mul_f32_e64 v12, |v7|, v12
	v_exp_f32_e32 v12, v12
	s_nop 0
	v_fma_f32 v11, -v12, v11, 1.0
	v_bfi_b32 v7, s13, v11, v7
	v_add_f32_e32 v7, 1.0, v7
	v_mul_f32_e32 v11, v10, v7
	v_fmac_f32_e32 v11, v9, v8
	s_nop 1
	v_add_f32_dpp v11, v11, v11 row_ror:8 row_mask:0xf bank_mask:0xf bound_ctrl:1
	s_nop 1
	v_add_f32_dpp v11, v11, v11 row_ror:4 row_mask:0xf bank_mask:0xf bound_ctrl:1
	s_nop 1
	v_add_f32_dpp v11, v11, v11 row_ror:2 row_mask:0xf bank_mask:0xf bound_ctrl:1
	s_nop 1
	v_add_f32_dpp v11, v11, v11 row_ror:1 row_mask:0xf bank_mask:0xf bound_ctrl:1
	ds_bpermute_b32 v12, v3, v11
	s_waitcnt lgkmcnt(0)
	v_add_f32_e32 v11, v11, v12
	v_mov_b32_e32 v12, v11
	s_nop 1
	v_permlane32_swap_b32_e32 v11, v12
	v_add_f32_e32 v11, v11, v12
	v_mul_f32_e32 v11, 0x3c000000, v11
	v_fma_f32 v7, v10, v7, -v11
	v_fma_f32 v8, v9, v8, -v11
	v_mul_f32_e32 v9, v7, v7
	v_fmac_f32_e32 v9, v8, v8
	s_nop 1
	v_add_f32_dpp v9, v9, v9 row_ror:8 row_mask:0xf bank_mask:0xf bound_ctrl:1
	s_nop 1
	v_add_f32_dpp v9, v9, v9 row_ror:4 row_mask:0xf bank_mask:0xf bound_ctrl:1
	s_nop 1
	v_add_f32_dpp v9, v9, v9 row_ror:2 row_mask:0xf bank_mask:0xf bound_ctrl:1
	s_nop 1
	v_add_f32_dpp v9, v9, v9 row_ror:1 row_mask:0xf bank_mask:0xf bound_ctrl:1
	ds_bpermute_b32 v10, v3, v9
	s_waitcnt lgkmcnt(0)
	v_add_f32_e32 v9, v9, v10
	v_mov_b32_e32 v10, v9
	s_nop 1
	v_permlane32_swap_b32_e32 v9, v10
	v_add_f32_e32 v9, v9, v10
	v_fmamk_f32 v9, v9, 0x3c000000, v177
	v_cmp_gt_f32_e32 vcc, s16, v9
	v_mul_f32_e32 v10, 0x4b800000, v9
	s_nop 0
	v_cndmask_b32_e32 v9, v9, v10, vcc
	v_rsq_f32_e32 v9, v9
	s_nop 0
	v_mul_f32_e32 v10, 0x45800000, v9
	v_cndmask_b32_e32 v9, v9, v10, vcc
	v_mul_f32_e32 v8, v8, v9
	v_cvt_pk_bf16_f32 v8, v8, v8
	v_add_u32_e32 v10, s5, v6
	v_mul_f32_e32 v7, v7, v9
	ds_write_b16 v10, v8
	s_add_i32 s5, s5, 2
	v_cvt_pk_bf16_f32 v7, v7, v7
	ds_write_b16 v10, v7 offset:272
	s_waitcnt vmcnt(6)
; DI bf16 f2bf(float f) { unsigned u = __float_as_uint(f); u += 0x7fffu + ((u >> 16) & 1u); return (bf16)(u >> 16); }
;   DI bf16* P() const { return (bf16*)(p.ws + WS_P); }
; DI float erf_as(float x) {
;   const float ax = fabsf(x);
;   const float t = __builtin_amdgcn_rcpf(1.f + 0.3275911f * ax);
;   const float poly = t * (0.254829592f + t * (-0.284496736f + t * (1.421413741f + t * (-1.453152027f + t * 1.061405429f))));
;   const float y = 1.f - poly * __builtin_amdgcn_exp2f(-1.4426950408889634f * ax * ax);
;   return copysignf(y, x);
; }
; DI float gelu(float x) { return 0.5f * x * (1.f + erf_as(x * 0.70710678118654752f)); }
; DI float logsigmoid(float z) { return fminf(z, 0.f) - log1pf(__expf(-fabsf(z))); }
; DI float logsigmoid_fast(float z) { return -0.6931471805599453f * __builtin_amdgcn_logf(1.f + __builtin_amdgcn_exp2f(-1.4426950408889634f * fmaxf(z, -80.f))); }
; template <int CTRL> DI float dpp_add(float v) { return v + __builtin_bit_cast(float, __builtin_amdgcn_update_dpp(0, __builtin_bit_cast(int, v), CTRL, 0xf, 0xf, false)); }
; DI float wave_sum(float v) {
;   v = dpp_add<0x128>(v); v = dpp_add<0x124>(v); v = dpp_add<0x122>(v); v = dpp_add<0x121>(v);
;   v += __shfl_xor(v, 16);
;   const unsigned u = __float_as_uint(v);
;   auto r = __builtin_amdgcn_permlane32_swap(u, u, false, false);
;   return __uint_as_float(r[0]) + __uint_as_float(r[1]);
; }
; DI void vgt_tile(const Ctx& c, int ti, bf16* lds) {
;     ...
;   for (int rr = 0; rr < 32; ++rr) {
;     const int t = wave * 32 + rr;
;     const unsigned u = *(const unsigned*)(c.P() + (size_t)(row0 + t) * LDP + C_V + g * 128 + 2 * lane);
;     const float a = gelu(__uint_as_float(u << 16)), b = gelu(__uint_as_float(u & 0xffff0000u));
;     const float mean = wave_sum(a + b) * (1.f / 128.f);
;     const float da = a - mean, db = b - mean;
;     const float rstd = rsqrtf(wave_sum(da * da + db * db) * (1.f / 128.f) + LN_EPS);
;     lds[(2 * lane) * LDT + t] = f2bf(da * rstd);
;     lds[(2 * lane + 1) * LDT + t] = f2bf(db * rstd);
;   }
	v_lshlrev_b32_e32 v8, 16, v45
	v_mul_f32_e32 v9, 0.5, v8
	v_mul_f32_e32 v8, 0x3f3504f3, v8
	v_fma_f32 v10, |v8|, s2, 1.0
	v_rcp_f32_e32 v10, v10
	v_and_b32_e32 v7, 0xffff0000, v45
	v_fmamk_f32 v11, v10, 0x3f87dc22, v176
	v_fmaak_f32 v11, v10, v11, 0x3fb5f0e3
	v_fmaak_f32 v11, v10, v11, 0xbe91a98e
	v_fmaak_f32 v11, v10, v11, 0x3e827906
	v_mul_f32_e32 v10, v10, v11
	v_mul_f32_e64 v11, |v8|, s3
	v_mul_f32_e64 v11, |v8|, v11
	v_exp_f32_e32 v11, v11
	s_nop 0
	v_fma_f32 v10, -v11, v10, 1.0
	v_bfi_b32 v8, s13, v10, v8
	v_mul_f32_e32 v10, 0.5, v7
	v_mul_f32_e32 v7, 0x3f3504f3, v7
	v_fma_f32 v11, |v7|, s2, 1.0
	v_rcp_f32_e32 v11, v11
	v_add_f32_e32 v8, 1.0, v8
	v_fmamk_f32 v12, v11, 0x3f87dc22, v176
	v_fmaak_f32 v12, v11, v12, 0x3fb5f0e3
	v_fmaak_f32 v12, v11, v12, 0xbe91a98e
	v_fmaak_f32 v12, v11, v12, 0x3e827906
	v_mul_f32_e32 v11, v11, v12
	v_mul_f32_e64 v12, |v7|, s3
	v_mul_f32_e64 v12, |v7|, v12
	v_exp_f32_e32 v12, v12
	s_nop 0
	v_fma_f32 v11, -v12, v11, 1.0
	v_bfi_b32 v7, s13, v11, v7
	v_add_f32_e32 v7, 1.0, v7
	v_mul_f32_e32 v11, v10, v7
	v_fmac_f32_e32 v11, v9, v8
	s_nop 1
	v_add_f32_dpp v11, v11, v11 row_ror:8 row_mask:0xf bank_mask:0xf bound_ctrl:1
	s_nop 1
	v_add_f32_dpp v11, v11, v11 row_ror:4 row_mask:0xf bank_mask:0xf bound_ctrl:1
	s_nop 1
	v_add_f32_dpp v11, v11, v11 row_ror:2 row_mask:0xf bank_mask:0xf bound_ctrl:1
	s_nop 1
	v_add_f32_dpp v11, v11, v11 row_ror:1 row_mask:0xf bank_mask:0xf bound_ctrl:1
	ds_bpermute_b32 v12, v3, v11
	s_waitcnt lgkmcnt(0)
	v_add_f32_e32 v11, v11, v12
	v_mov_b32_e32 v12, v11
	s_nop 1
	v_permlane32_swap_b32_e32 v11, v12
	v_add_f32_e32 v11, v11, v12
	v_mul_f32_e32 v11, 0x3c000000, v11
	v_fma_f32 v7, v10, v7, -v11
	v_fma_f32 v8, v9, v8, -v11
	v_mul_f32_e32 v9, v7, v7
	v_fmac_f32_e32 v9, v8, v8
	s_nop 1
	v_add_f32_dpp v9, v9, v9 row_ror:8 row_mask:0xf bank_mask:0xf bound_ctrl:1
	s_nop 1
	v_add_f32_dpp v9, v9, v9 row_ror:4 row_mask:0xf bank_mask:0xf bound_ctrl:1
	s_nop 1
	v_add_f32_dpp v9, v9, v9 row_ror:2 row_mask:0xf bank_mask:0xf bound_ctrl:1
	s_nop 1
	v_add_f32_dpp v9, v9, v9 row_ror:1 row_mask:0xf bank_mask:0xf bound_ctrl:1
	ds_bpermute_b32 v10, v3, v9
	s_waitcnt lgkmcnt(0)
	v_add_f32_e32 v9, v9, v10
	v_mov_b32_e32 v10, v9
	s_nop 1
	v_permlane32_swap_b32_e32 v9, v10
	v_add_f32_e32 v9, v9, v10
	v_fmamk_f32 v9, v9, 0x3c000000, v177
	v_cmp_gt_f32_e32 vcc, s16, v9
	v_mul_f32_e32 v10, 0x4b800000, v9
	s_nop 0
	v_cndmask_b32_e32 v9, v9, v10, vcc
	v_rsq_f32_e32 v9, v9
	s_nop 0
	v_mul_f32_e32 v10, 0x45800000, v9
	v_cndmask_b32_e32 v9, v9, v10, vcc
	v_mul_f32_e32 v8, v8, v9
	v_cvt_pk_bf16_f32 v8, v8, v8
	v_add_u32_e32 v10, s5, v6
	v_mul_f32_e32 v7, v7, v9
	ds_write_b16 v10, v8
	s_add_i32 s5, s5, 2
	v_cvt_pk_bf16_f32 v7, v7, v7
	ds_write_b16 v10, v7 offset:272
	s_waitcnt vmcnt(5)
	v_lshlrev_b32_e32 v8, 16, v46
	v_mul_f32_e32 v9, 0.5, v8
	v_mul_f32_e32 v8, 0x3f3504f3, v8
	v_fma_f32 v10, |v8|, s2, 1.0
	v_rcp_f32_e32 v10, v10
	v_and_b32_e32 v7, 0xffff0000, v46
	v_fmamk_f32 v11, v10, 0x3f87dc22, v176
	v_fmaak_f32 v11, v10, v11, 0x3fb5f0e3
	v_fmaak_f32 v11, v10, v11, 0xbe91a98e
	v_fmaak_f32 v11, v10, v11, 0x3e827906
	v_mul_f32_e32 v10, v10, v11
	v_mul_f32_e64 v11, |v8|, s3
	v_mul_f32_e64 v11, |v8|, v11
	v_exp_f32_e32 v11, v11
	s_nop 0
	v_fma_f32 v10, -v11, v10, 1.0
	v_bfi_b32 v8, s13, v10, v8
	v_mul_f32_e32 v10, 0.5, v7
	v_mul_f32_e32 v7, 0x3f3504f3, v7
	v_fma_f32 v11, |v7|, s2, 1.0
	v_rcp_f32_e32 v11, v11
	v_add_f32_e32 v8, 1.0, v8
	v_fmamk_f32 v12, v11, 0x3f87dc22, v176
	v_fmaak_f32 v12, v11, v12, 0x3fb5f0e3
	v_fmaak_f32 v12, v11, v12, 0xbe91a98e
	v_fmaak_f32 v12, v11, v12, 0x3e827906
	v_mul_f32_e32 v11, v11, v12
	v_mul_f32_e64 v12, |v7|, s3
	v_mul_f32_e64 v12, |v7|, v12
	v_exp_f32_e32 v12, v12
	s_nop 0
	v_fma_f32 v11, -v12, v11, 1.0
	v_bfi_b32 v7, s13, v11, v7
	v_add_f32_e32 v7, 1.0, v7
	v_mul_f32_e32 v11, v10, v7
	v_fmac_f32_e32 v11, v9, v8
	s_nop 1
	v_add_f32_dpp v11, v11, v11 row_ror:8 row_mask:0xf bank_mask:0xf bound_ctrl:1
	s_nop 1
	v_add_f32_dpp v11, v11, v11 row_ror:4 row_mask:0xf bank_mask:0xf bound_ctrl:1
	s_nop 1
	v_add_f32_dpp v11, v11, v11 row_ror:2 row_mask:0xf bank_mask:0xf bound_ctrl:1
	s_nop 1
	v_add_f32_dpp v11, v11, v11 row_ror:1 row_mask:0xf bank_mask:0xf bound_ctrl:1
	ds_bpermute_b32 v12, v3, v11
	s_waitcnt lgkmcnt(0)
	v_add_f32_e32 v11, v11, v12
	v_mov_b32_e32 v12, v11
	s_nop 1
	v_permlane32_swap_b32_e32 v11, v12
	v_add_f32_e32 v11, v11, v12
	v_mul_f32_e32 v11, 0x3c000000, v11
	v_fma_f32 v7, v10, v7, -v11
	v_fma_f32 v8, v9, v8, -v11
	v_mul_f32_e32 v9, v7, v7
	v_fmac_f32_e32 v9, v8, v8
	s_nop 1
	v_add_f32_dpp v9, v9, v9 row_ror:8 row_mask:0xf bank_mask:0xf bound_ctrl:1
	s_nop 1
	v_add_f32_dpp v9, v9, v9 row_ror:4 row_mask:0xf bank_mask:0xf bound_ctrl:1
	s_nop 1
	v_add_f32_dpp v9, v9, v9 row_ror:2 row_mask:0xf bank_mask:0xf bound_ctrl:1
	s_nop 1
	v_add_f32_dpp v9, v9, v9 row_ror:1 row_mask:0xf bank_mask:0xf bound_ctrl:1
	ds_bpermute_b32 v10, v3, v9
	s_waitcnt lgkmcnt(0)
	v_add_f32_e32 v9, v9, v10
	v_mov_b32_e32 v10, v9
	s_nop 1
	v_permlane32_swap_b32_e32 v9, v10
	v_add_f32_e32 v9, v9, v10
	v_fmamk_f32 v9, v9, 0x3c000000, v177
	v_cmp_gt_f32_e32 vcc, s16, v9
	v_mul_f32_e32 v10, 0x4b800000, v9
	s_nop 0
	v_cndmask_b32_e32 v9, v9, v10, vcc
	v_rsq_f32_e32 v9, v9
	s_nop 0
	v_mul_f32_e32 v10, 0x45800000, v9
	v_cndmask_b32_e32 v9, v9, v10, vcc
	v_mul_f32_e32 v8, v8, v9
	v_cvt_pk_bf16_f32 v8, v8, v8
	v_add_u32_e32 v10, s5, v6
	v_mul_f32_e32 v7, v7, v9
	ds_write_b16 v10, v8
	s_add_i32 s5, s5, 2
	v_cvt_pk_bf16_f32 v7, v7, v7
	ds_write_b16 v10, v7 offset:272
	s_waitcnt vmcnt(4)
; DI bf16 f2bf(float f) { unsigned u = __float_as_uint(f); u += 0x7fffu + ((u >> 16) & 1u); return (bf16)(u >> 16); }
;   DI bf16* P() const { return (bf16*)(p.ws + WS_P); }
; DI float erf_as(float x) {
;   const float ax = fabsf(x);
;   const float t = __builtin_amdgcn_rcpf(1.f + 0.3275911f * ax);
;   const float poly = t * (0.254829592f + t * (-0.284496736f + t * (1.421413741f + t * (-1.453152027f + t * 1.061405429f))));
;   const float y = 1.f - poly * __builtin_amdgcn_exp2f(-1.4426950408889634f * ax * ax);
;   return copysignf(y, x);
; }
; DI float gelu(float x) { return 0.5f * x * (1.f + erf_as(x * 0.70710678118654752f)); }
; DI float logsigmoid(float z) { return fminf(z, 0.f) - log1pf(__expf(-fabsf(z))); }
; DI float logsigmoid_fast(float z) { return -0.6931471805599453f * __builtin_amdgcn_logf(1.f + __builtin_amdgcn_exp2f(-1.4426950408889634f * fmaxf(z, -80.f))); }
; template <int CTRL> DI float dpp_add(float v) { return v + __builtin_bit_cast(float, __builtin_amdgcn_update_dpp(0, __builtin_bit_cast(int, v), CTRL, 0xf, 0xf, false)); }
; DI float wave_sum(float v) {
;   v = dpp_add<0x128>(v); v = dpp_add<0x124>(v); v = dpp_add<0x122>(v); v = dpp_add<0x121>(v);
;   v += __shfl_xor(v, 16);
;   const unsigned u = __float_as_uint(v);
;   auto r = __builtin_amdgcn_permlane32_swap(u, u, false, false);
;   return __uint_as_float(r[0]) + __uint_as_float(r[1]);
; }
; DI void vgt_tile(const Ctx& c, int ti, bf16* lds) {
;     ...
;   for (int rr = 0; rr < 32; ++rr) {
;     const int t = wave * 32 + rr;
;     const unsigned u = *(const unsigned*)(c.P() + (size_t)(row0 + t) * LDP + C_V + g * 128 + 2 * lane);
;     const float a = gelu(__uint_as_float(u << 16)), b = gelu(__uint_as_float(u & 0xffff0000u));
;     const float mean = wave_sum(a + b) * (1.f / 128.f);
;     const float da = a - mean, db = b - mean;
;     const float rstd = rsqrtf(wave_sum(da * da + db * db) * (1.f / 128.f) + LN_EPS);
;     lds[(2 * lane) * LDT + t] = f2bf(da * rstd);
;     lds[(2 * lane + 1) * LDT + t] = f2bf(db * rstd);
;   }
	v_lshlrev_b32_e32 v8, 16, v47
	v_mul_f32_e32 v9, 0.5, v8
	v_mul_f32_e32 v8, 0x3f3504f3, v8
	v_fma_f32 v10, |v8|, s2, 1.0
	v_rcp_f32_e32 v10, v10
	v_and_b32_e32 v7, 0xffff0000, v47
	v_fmamk_f32 v11, v10, 0x3f87dc22, v176
	v_fmaak_f32 v11, v10, v11, 0x3fb5f0e3
	v_fmaak_f32 v11, v10, v11, 0xbe91a98e
	v_fmaak_f32 v11, v10, v11, 0x3e827906
	v_mul_f32_e32 v10, v10, v11
	v_mul_f32_e64 v11, |v8|, s3
	v_mul_f32_e64 v11, |v8|, v11
	v_exp_f32_e32 v11, v11
	s_nop 0
	v_fma_f32 v10, -v11, v10, 1.0
	v_bfi_b32 v8, s13, v10, v8
	v_mul_f32_e32 v10, 0.5, v7
	v_mul_f32_e32 v7, 0x3f3504f3, v7
	v_fma_f32 v11, |v7|, s2, 1.0
	v_rcp_f32_e32 v11, v11
	v_add_f32_e32 v8, 1.0, v8
	v_fmamk_f32 v12, v11, 0x3f87dc22, v176
	v_fmaak_f32 v12, v11, v12, 0x3fb5f0e3
	v_fmaak_f32 v12, v11, v12, 0xbe91a98e
	v_fmaak_f32 v12, v11, v12, 0x3e827906
	v_mul_f32_e32 v11, v11, v12
	v_mul_f32_e64 v12, |v7|, s3
	v_mul_f32_e64 v12, |v7|, v12
	v_exp_f32_e32 v12, v12
	s_nop 0
	v_fma_f32 v11, -v12, v11, 1.0
	v_bfi_b32 v7, s13, v11, v7
	v_add_f32_e32 v7, 1.0, v7
	v_mul_f32_e32 v11, v10, v7
	v_fmac_f32_e32 v11, v9, v8
	s_nop 1
	v_add_f32_dpp v11, v11, v11 row_ror:8 row_mask:0xf bank_mask:0xf bound_ctrl:1
	s_nop 1
	v_add_f32_dpp v11, v11, v11 row_ror:4 row_mask:0xf bank_mask:0xf bound_ctrl:1
	s_nop 1
	v_add_f32_dpp v11, v11, v11 row_ror:2 row_mask:0xf bank_mask:0xf bound_ctrl:1
	s_nop 1
	v_add_f32_dpp v11, v11, v11 row_ror:1 row_mask:0xf bank_mask:0xf bound_ctrl:1
	ds_bpermute_b32 v12, v3, v11
	s_waitcnt lgkmcnt(0)
	v_add_f32_e32 v11, v11, v12
	v_mov_b32_e32 v12, v11
	s_nop 1
	v_permlane32_swap_b32_e32 v11, v12
	v_add_f32_e32 v11, v11, v12
	v_mul_f32_e32 v11, 0x3c000000, v11
	v_fma_f32 v7, v10, v7, -v11
	v_fma_f32 v8, v9, v8, -v11
	v_mul_f32_e32 v9, v7, v7
	v_fmac_f32_e32 v9, v8, v8
	s_nop 1
	v_add_f32_dpp v9, v9, v9 row_ror:8 row_mask:0xf bank_mask:0xf bound_ctrl:1
	s_nop 1
	v_add_f32_dpp v9, v9, v9 row_ror:4 row_mask:0xf bank_mask:0xf bound_ctrl:1
	s_nop 1
	v_add_f32_dpp v9, v9, v9 row_ror:2 row_mask:0xf bank_mask:0xf bound_ctrl:1
	s_nop 1
	v_add_f32_dpp v9, v9, v9 row_ror:1 row_mask:0xf bank_mask:0xf bound_ctrl:1
	ds_bpermute_b32 v10, v3, v9
	s_waitcnt lgkmcnt(0)
	v_add_f32_e32 v9, v9, v10
	v_mov_b32_e32 v10, v9
	s_nop 1
	v_permlane32_swap_b32_e32 v9, v10
	v_add_f32_e32 v9, v9, v10
	v_fmamk_f32 v9, v9, 0x3c000000, v177
	v_cmp_gt_f32_e32 vcc, s16, v9
	v_mul_f32_e32 v10, 0x4b800000, v9
	s_nop 0
	v_cndmask_b32_e32 v9, v9, v10, vcc
	v_rsq_f32_e32 v9, v9
	s_nop 0
	v_mul_f32_e32 v10, 0x45800000, v9
	v_cndmask_b32_e32 v9, v9, v10, vcc
	v_mul_f32_e32 v8, v8, v9
	v_cvt_pk_bf16_f32 v8, v8, v8
	v_add_u32_e32 v10, s5, v6
	v_mul_f32_e32 v7, v7, v9
	ds_write_b16 v10, v8
	s_add_i32 s5, s5, 2
	v_cvt_pk_bf16_f32 v7, v7, v7
	ds_write_b16 v10, v7 offset:272
	s_waitcnt vmcnt(3)
	v_lshlrev_b32_e32 v8, 16, v48
	v_mul_f32_e32 v9, 0.5, v8
	v_mul_f32_e32 v8, 0x3f3504f3, v8
	v_fma_f32 v10, |v8|, s2, 1.0
	v_rcp_f32_e32 v10, v10
	v_and_b32_e32 v7, 0xffff0000, v48
	v_fmamk_f32 v11, v10, 0x3f87dc22, v176
	v_fmaak_f32 v11, v10, v11, 0x3fb5f0e3
	v_fmaak_f32 v11, v10, v11, 0xbe91a98e
	v_fmaak_f32 v11, v10, v11, 0x3e827906
	v_mul_f32_e32 v10, v10, v11
	v_mul_f32_e64 v11, |v8|, s3
	v_mul_f32_e64 v11, |v8|, v11
	v_exp_f32_e32 v11, v11
	s_nop 0
	v_fma_f32 v10, -v11, v10, 1.0
	v_bfi_b32 v8, s13, v10, v8
	v_mul_f32_e32 v10, 0.5, v7
	v_mul_f32_e32 v7, 0x3f3504f3, v7
	v_fma_f32 v11, |v7|, s2, 1.0
	v_rcp_f32_e32 v11, v11
	v_add_f32_e32 v8, 1.0, v8
	v_fmamk_f32 v12, v11, 0x3f87dc22, v176
	v_fmaak_f32 v12, v11, v12, 0x3fb5f0e3
	v_fmaak_f32 v12, v11, v12, 0xbe91a98e
	v_fmaak_f32 v12, v11, v12, 0x3e827906
	v_mul_f32_e32 v11, v11, v12
	v_mul_f32_e64 v12, |v7|, s3
	v_mul_f32_e64 v12, |v7|, v12
	v_exp_f32_e32 v12, v12
	s_nop 0
	v_fma_f32 v11, -v12, v11, 1.0
	v_bfi_b32 v7, s13, v11, v7
	v_add_f32_e32 v7, 1.0, v7
	v_mul_f32_e32 v11, v10, v7
	v_fmac_f32_e32 v11, v9, v8
	s_nop 1
	v_add_f32_dpp v11, v11, v11 row_ror:8 row_mask:0xf bank_mask:0xf bound_ctrl:1
	s_nop 1
	v_add_f32_dpp v11, v11, v11 row_ror:4 row_mask:0xf bank_mask:0xf bound_ctrl:1
	s_nop 1
	v_add_f32_dpp v11, v11, v11 row_ror:2 row_mask:0xf bank_mask:0xf bound_ctrl:1
	s_nop 1
	v_add_f32_dpp v11, v11, v11 row_ror:1 row_mask:0xf bank_mask:0xf bound_ctrl:1
	ds_bpermute_b32 v12, v3, v11
	s_waitcnt lgkmcnt(0)
	v_add_f32_e32 v11, v11, v12
	v_mov_b32_e32 v12, v11
	s_nop 1
	v_permlane32_swap_b32_e32 v11, v12
	v_add_f32_e32 v11, v11, v12
	v_mul_f32_e32 v11, 0x3c000000, v11
	v_fma_f32 v7, v10, v7, -v11
	v_fma_f32 v8, v9, v8, -v11
	v_mul_f32_e32 v9, v7, v7
	v_fmac_f32_e32 v9, v8, v8
	s_nop 1
	v_add_f32_dpp v9, v9, v9 row_ror:8 row_mask:0xf bank_mask:0xf bound_ctrl:1
	s_nop 1
	v_add_f32_dpp v9, v9, v9 row_ror:4 row_mask:0xf bank_mask:0xf bound_ctrl:1
	s_nop 1
	v_add_f32_dpp v9, v9, v9 row_ror:2 row_mask:0xf bank_mask:0xf bound_ctrl:1
	s_nop 1
	v_add_f32_dpp v9, v9, v9 row_ror:1 row_mask:0xf bank_mask:0xf bound_ctrl:1
	ds_bpermute_b32 v10, v3, v9
	s_waitcnt lgkmcnt(0)
	v_add_f32_e32 v9, v9, v10
	v_mov_b32_e32 v10, v9
	s_nop 1
	v_permlane32_swap_b32_e32 v9, v10
	v_add_f32_e32 v9, v9, v10
	v_fmamk_f32 v9, v9, 0x3c000000, v177
	v_cmp_gt_f32_e32 vcc, s16, v9
	v_mul_f32_e32 v10, 0x4b800000, v9
	s_nop 0
	v_cndmask_b32_e32 v9, v9, v10, vcc
	v_rsq_f32_e32 v9, v9
	s_nop 0
	v_mul_f32_e32 v10, 0x45800000, v9
	v_cndmask_b32_e32 v9, v9, v10, vcc
	v_mul_f32_e32 v8, v8, v9
	v_cvt_pk_bf16_f32 v8, v8, v8
	v_add_u32_e32 v10, s5, v6
	v_mul_f32_e32 v7, v7, v9
	ds_write_b16 v10, v8
	s_add_i32 s5, s5, 2
	v_cvt_pk_bf16_f32 v7, v7, v7
	ds_write_b16 v10, v7 offset:272
	s_waitcnt vmcnt(2)
; DI bf16 f2bf(float f) { unsigned u = __float_as_uint(f); u += 0x7fffu + ((u >> 16) & 1u); return (bf16)(u >> 16); }
;   DI bf16* P() const { return (bf16*)(p.ws + WS_P); }
; DI float erf_as(float x) {
;   const float ax = fabsf(x);
;   const float t = __builtin_amdgcn_rcpf(1.f + 0.3275911f * ax);
;   const float poly = t * (0.254829592f + t * (-0.284496736f + t * (1.421413741f + t * (-1.453152027f + t * 1.061405429f))));
;   const float y = 1.f - poly * __builtin_amdgcn_exp2f(-1.4426950408889634f * ax * ax);
;   return copysignf(y, x);
; }
; DI float gelu(float x) { return 0.5f * x * (1.f + erf_as(x * 0.70710678118654752f)); }
; DI float logsigmoid(float z) { return fminf(z, 0.f) - log1pf(__expf(-fabsf(z))); }
; DI float logsigmoid_fast(float z) { return -0.6931471805599453f * __builtin_amdgcn_logf(1.f + __builtin_amdgcn_exp2f(-1.4426950408889634f * fmaxf(z, -80.f))); }
; template <int CTRL> DI float dpp_add(float v) { return v + __builtin_bit_cast(float, __builtin_amdgcn_update_dpp(0, __builtin_bit_cast(int, v), CTRL, 0xf, 0xf, false)); }
; DI float wave_sum(float v) {
;   v = dpp_add<0x128>(v); v = dpp_add<0x124>(v); v = dpp_add<0x122>(v); v = dpp_add<0x121>(v);
;   v += __shfl_xor(v, 16);
;   const unsigned u = __float_as_uint(v);
;   auto r = __builtin_amdgcn_permlane32_swap(u, u, false, false);
;   return __uint_as_float(r[0]) + __uint_as_float(r[1]);
; }
; DI void vgt_tile(const Ctx& c, int ti, bf16* lds) {
;     ...
;   for (int rr = 0; rr < 32; ++rr) {
;     const int t = wave * 32 + rr;
;     const unsigned u = *(const unsigned*)(c.P() + (size_t)(row0 + t) * LDP + C_V + g * 128 + 2 * lane);
;     const float a = gelu(__uint_as_float(u << 16)), b = gelu(__uint_as_float(u & 0xffff0000u));
;     const float mean = wave_sum(a + b) * (1.f / 128.f);
;     const float da = a - mean, db = b - mean;
;     const float rstd = rsqrtf(wave_sum(da * da + db * db) * (1.f / 128.f) + LN_EPS);
;     lds[(2 * lane) * LDT + t] = f2bf(da * rstd);
;     lds[(2 * lane + 1) * LDT + t] = f2bf(db * rstd);
;   }
	v_lshlrev_b32_e32 v8, 16, v49
	v_mul_f32_e32 v9, 0.5, v8
	v_mul_f32_e32 v8, 0x3f3504f3, v8
	v_fma_f32 v10, |v8|, s2, 1.0
	v_rcp_f32_e32 v10, v10
	v_and_b32_e32 v7, 0xffff0000, v49
	v_fmamk_f32 v11, v10, 0x3f87dc22, v176
	v_fmaak_f32 v11, v10, v11, 0x3fb5f0e3
	v_fmaak_f32 v11, v10, v11, 0xbe91a98e
	v_fmaak_f32 v11, v10, v11, 0x3e827906
	v_mul_f32_e32 v10, v10, v11
	v_mul_f32_e64 v11, |v8|, s3
	v_mul_f32_e64 v11, |v8|, v11
	v_exp_f32_e32 v11, v11
	s_nop 0
	v_fma_f32 v10, -v11, v10, 1.0
	v_bfi_b32 v8, s13, v10, v8
	v_mul_f32_e32 v10, 0.5, v7
	v_mul_f32_e32 v7, 0x3f3504f3, v7
	v_fma_f32 v11, |v7|, s2, 1.0
	v_rcp_f32_e32 v11, v11
	v_add_f32_e32 v8, 1.0, v8
	v_fmamk_f32 v12, v11, 0x3f87dc22, v176
	v_fmaak_f32 v12, v11, v12, 0x3fb5f0e3
	v_fmaak_f32 v12, v11, v12, 0xbe91a98e
	v_fmaak_f32 v12, v11, v12, 0x3e827906
	v_mul_f32_e32 v11, v11, v12
	v_mul_f32_e64 v12, |v7|, s3
	v_mul_f32_e64 v12, |v7|, v12
	v_exp_f32_e32 v12, v12
	s_nop 0
	v_fma_f32 v11, -v12, v11, 1.0
	v_bfi_b32 v7, s13, v11, v7
	v_add_f32_e32 v7, 1.0, v7
	v_mul_f32_e32 v11, v10, v7
	v_fmac_f32_e32 v11, v9, v8
	s_nop 1
	v_add_f32_dpp v11, v11, v11 row_ror:8 row_mask:0xf bank_mask:0xf bound_ctrl:1
	s_nop 1
	v_add_f32_dpp v11, v11, v11 row_ror:4 row_mask:0xf bank_mask:0xf bound_ctrl:1
	s_nop 1
	v_add_f32_dpp v11, v11, v11 row_ror:2 row_mask:0xf bank_mask:0xf bound_ctrl:1
	s_nop 1
	v_add_f32_dpp v11, v11, v11 row_ror:1 row_mask:0xf bank_mask:0xf bound_ctrl:1
	ds_bpermute_b32 v12, v3, v11
	s_waitcnt lgkmcnt(0)
	v_add_f32_e32 v11, v11, v12
	v_mov_b32_e32 v12, v11
	s_nop 1
	v_permlane32_swap_b32_e32 v11, v12
	v_add_f32_e32 v11, v11, v12
	v_mul_f32_e32 v11, 0x3c000000, v11
	v_fma_f32 v7, v10, v7, -v11
	v_fma_f32 v8, v9, v8, -v11
	v_mul_f32_e32 v9, v7, v7
	v_fmac_f32_e32 v9, v8, v8
	s_nop 1
	v_add_f32_dpp v9, v9, v9 row_ror:8 row_mask:0xf bank_mask:0xf bound_ctrl:1
	s_nop 1
	v_add_f32_dpp v9, v9, v9 row_ror:4 row_mask:0xf bank_mask:0xf bound_ctrl:1
	s_nop 1
	v_add_f32_dpp v9, v9, v9 row_ror:2 row_mask:0xf bank_mask:0xf bound_ctrl:1
	s_nop 1
	v_add_f32_dpp v9, v9, v9 row_ror:1 row_mask:0xf bank_mask:0xf bound_ctrl:1
	ds_bpermute_b32 v10, v3, v9
	s_waitcnt lgkmcnt(0)
	v_add_f32_e32 v9, v9, v10
	v_mov_b32_e32 v10, v9
	s_nop 1
	v_permlane32_swap_b32_e32 v9, v10
	v_add_f32_e32 v9, v9, v10
	v_fmamk_f32 v9, v9, 0x3c000000, v177
	v_cmp_gt_f32_e32 vcc, s16, v9
	v_mul_f32_e32 v10, 0x4b800000, v9
	s_nop 0
	v_cndmask_b32_e32 v9, v9, v10, vcc
	v_rsq_f32_e32 v9, v9
	s_nop 0
	v_mul_f32_e32 v10, 0x45800000, v9
	v_cndmask_b32_e32 v9, v9, v10, vcc
	v_mul_f32_e32 v8, v8, v9
	v_cvt_pk_bf16_f32 v8, v8, v8
	v_add_u32_e32 v10, s5, v6
	v_mul_f32_e32 v7, v7, v9
	ds_write_b16 v10, v8
	s_add_i32 s5, s5, 2
	v_cvt_pk_bf16_f32 v7, v7, v7
	ds_write_b16 v10, v7 offset:272
	s_waitcnt vmcnt(1)
	v_lshlrev_b32_e32 v8, 16, v50
	v_mul_f32_e32 v9, 0.5, v8
	v_mul_f32_e32 v8, 0x3f3504f3, v8
	v_fma_f32 v10, |v8|, s2, 1.0
	v_rcp_f32_e32 v10, v10
	v_and_b32_e32 v7, 0xffff0000, v50
	v_fmamk_f32 v11, v10, 0x3f87dc22, v176
	v_fmaak_f32 v11, v10, v11, 0x3fb5f0e3
	v_fmaak_f32 v11, v10, v11, 0xbe91a98e
	v_fmaak_f32 v11, v10, v11, 0x3e827906
	v_mul_f32_e32 v10, v10, v11
	v_mul_f32_e64 v11, |v8|, s3
	v_mul_f32_e64 v11, |v8|, v11
	v_exp_f32_e32 v11, v11
	s_nop 0
	v_fma_f32 v10, -v11, v10, 1.0
	v_bfi_b32 v8, s13, v10, v8
	v_mul_f32_e32 v10, 0.5, v7
	v_mul_f32_e32 v7, 0x3f3504f3, v7
	v_fma_f32 v11, |v7|, s2, 1.0
	v_rcp_f32_e32 v11, v11
	v_add_f32_e32 v8, 1.0, v8
	v_fmamk_f32 v12, v11, 0x3f87dc22, v176
	v_fmaak_f32 v12, v11, v12, 0x3fb5f0e3
	v_fmaak_f32 v12, v11, v12, 0xbe91a98e
	v_fmaak_f32 v12, v11, v12, 0x3e827906
	v_mul_f32_e32 v11, v11, v12
	v_mul_f32_e64 v12, |v7|, s3
	v_mul_f32_e64 v12, |v7|, v12
	v_exp_f32_e32 v12, v12
	s_nop 0
	v_fma_f32 v11, -v12, v11, 1.0
	v_bfi_b32 v7, s13, v11, v7
	v_add_f32_e32 v7, 1.0, v7
	v_mul_f32_e32 v11, v10, v7
	v_fmac_f32_e32 v11, v9, v8
	s_nop 1
	v_add_f32_dpp v11, v11, v11 row_ror:8 row_mask:0xf bank_mask:0xf bound_ctrl:1
	s_nop 1
	v_add_f32_dpp v11, v11, v11 row_ror:4 row_mask:0xf bank_mask:0xf bound_ctrl:1
	s_nop 1
	v_add_f32_dpp v11, v11, v11 row_ror:2 row_mask:0xf bank_mask:0xf bound_ctrl:1
	s_nop 1
	v_add_f32_dpp v11, v11, v11 row_ror:1 row_mask:0xf bank_mask:0xf bound_ctrl:1
	ds_bpermute_b32 v12, v3, v11
	s_waitcnt lgkmcnt(0)
	v_add_f32_e32 v11, v11, v12
	v_mov_b32_e32 v12, v11
	s_nop 1
	v_permlane32_swap_b32_e32 v11, v12
	v_add_f32_e32 v11, v11, v12
	v_mul_f32_e32 v11, 0x3c000000, v11
	v_fma_f32 v7, v10, v7, -v11
	v_fma_f32 v8, v9, v8, -v11
	v_mul_f32_e32 v9, v7, v7
	v_fmac_f32_e32 v9, v8, v8
	s_nop 1
	v_add_f32_dpp v9, v9, v9 row_ror:8 row_mask:0xf bank_mask:0xf bound_ctrl:1
	s_nop 1
	v_add_f32_dpp v9, v9, v9 row_ror:4 row_mask:0xf bank_mask:0xf bound_ctrl:1
	s_nop 1
	v_add_f32_dpp v9, v9, v9 row_ror:2 row_mask:0xf bank_mask:0xf bound_ctrl:1
	s_nop 1
	v_add_f32_dpp v9, v9, v9 row_ror:1 row_mask:0xf bank_mask:0xf bound_ctrl:1
	ds_bpermute_b32 v10, v3, v9
	s_waitcnt lgkmcnt(0)
; DI bf16 f2bf(float f) { unsigned u = __float_as_uint(f); u += 0x7fffu + ((u >> 16) & 1u); return (bf16)(u >> 16); }
; DI float gelu(float x) { return 0.5f * x * (1.f + erf_as(x * 0.70710678118654752f)); }
;   DI bf16* P() const { return (bf16*)(p.ws + WS_P); }
;   DI bf16* VGT() const { return (bf16*)(p.ws + WS_VGT); }
; DI void vgt_tile(const Ctx& c, int ti, bf16* lds) {
;     ...
;   for (int rr = 0; rr < 32; ++rr) {
;     const int t = wave * 32 + rr;
;     const unsigned u = *(const unsigned*)(c.P() + (size_t)(row0 + t) * LDP + C_V + g * 128 + 2 * lane);
;     const float a = gelu(__uint_as_float(u << 16)), b = gelu(__uint_as_float(u & 0xffff0000u));
;     const float mean = wave_sum(a + b) * (1.f / 128.f);
;     const float da = a - mean, db = b - mean;
;     const float rstd = rsqrtf(wave_sum(da * da + db * db) * (1.f / 128.f) + LN_EPS);
;     lds[(2 * lane) * LDT + t] = f2bf(da * rstd);
;     lds[(2 * lane + 1) * LDT + t] = f2bf(db * rstd);
;   }
;   __syncthreads();
;   {
;     const int d = tid >> 1, half = tid & 1;
;     bf16* dst = c.VGT() + ((size_t)ti * 128 + d) * 128 + half * 64;
;     const bf16* src = lds + d * LDT + half * 64;
; #pragma unroll
;     for (int i = 0; i < 8; ++i) *(u32x4*)(dst + i * 8) = *(const u32x4*)(src + i * 8);
;   }
;   __syncthreads();
	v_add_f32_e32 v9, v9, v10
	v_mov_b32_e32 v10, v9
	s_nop 1
	v_permlane32_swap_b32_e32 v9, v10
	v_add_f32_e32 v9, v9, v10
	v_fmamk_f32 v9, v9, 0x3c000000, v177
	v_cmp_gt_f32_e32 vcc, s16, v9
	v_mul_f32_e32 v10, 0x4b800000, v9
	s_nop 0
	v_cndmask_b32_e32 v9, v9, v10, vcc
	v_rsq_f32_e32 v9, v9
	s_nop 0
	v_mul_f32_e32 v10, 0x45800000, v9
	v_cndmask_b32_e32 v9, v9, v10, vcc
	v_mul_f32_e32 v8, v8, v9
	v_cvt_pk_bf16_f32 v8, v8, v8
	v_add_u32_e32 v10, s5, v6
	v_mul_f32_e32 v7, v7, v9
	ds_write_b16 v10, v8
	s_add_i32 s5, s5, 2
	v_cvt_pk_bf16_f32 v7, v7, v7
	ds_write_b16 v10, v7 offset:272
	s_waitcnt vmcnt(0)
	v_lshlrev_b32_e32 v8, 16, v51
	v_mul_f32_e32 v9, 0.5, v8
	v_mul_f32_e32 v8, 0x3f3504f3, v8
	v_fma_f32 v10, |v8|, s2, 1.0
	v_rcp_f32_e32 v10, v10
	v_and_b32_e32 v7, 0xffff0000, v51
	v_fmamk_f32 v11, v10, 0x3f87dc22, v176
	v_fmaak_f32 v11, v10, v11, 0x3fb5f0e3
	v_fmaak_f32 v11, v10, v11, 0xbe91a98e
	v_fmaak_f32 v11, v10, v11, 0x3e827906
	v_mul_f32_e32 v10, v10, v11
	v_mul_f32_e64 v11, |v8|, s3
	v_mul_f32_e64 v11, |v8|, v11
	v_exp_f32_e32 v11, v11
	s_nop 0
	v_fma_f32 v10, -v11, v10, 1.0
	v_bfi_b32 v8, s13, v10, v8
	v_mul_f32_e32 v10, 0.5, v7
	v_mul_f32_e32 v7, 0x3f3504f3, v7
	v_fma_f32 v11, |v7|, s2, 1.0
	v_rcp_f32_e32 v11, v11
	v_add_f32_e32 v8, 1.0, v8
	v_fmamk_f32 v12, v11, 0x3f87dc22, v176
	v_fmaak_f32 v12, v11, v12, 0x3fb5f0e3
	v_fmaak_f32 v12, v11, v12, 0xbe91a98e
	v_fmaak_f32 v12, v11, v12, 0x3e827906
	v_mul_f32_e32 v11, v11, v12
	v_mul_f32_e64 v12, |v7|, s3
	v_mul_f32_e64 v12, |v7|, v12
	v_exp_f32_e32 v12, v12
	s_nop 0
	v_fma_f32 v11, -v12, v11, 1.0
	v_bfi_b32 v7, s13, v11, v7
	v_add_f32_e32 v7, 1.0, v7
	v_mul_f32_e32 v11, v10, v7
	v_fmac_f32_e32 v11, v9, v8
	s_nop 1
	v_add_f32_dpp v11, v11, v11 row_ror:8 row_mask:0xf bank_mask:0xf bound_ctrl:1
	s_nop 1
	v_add_f32_dpp v11, v11, v11 row_ror:4 row_mask:0xf bank_mask:0xf bound_ctrl:1
	s_nop 1
	v_add_f32_dpp v11, v11, v11 row_ror:2 row_mask:0xf bank_mask:0xf bound_ctrl:1
	s_nop 1
	v_add_f32_dpp v11, v11, v11 row_ror:1 row_mask:0xf bank_mask:0xf bound_ctrl:1
	ds_bpermute_b32 v12, v3, v11
	s_waitcnt lgkmcnt(0)
	v_add_f32_e32 v11, v11, v12
	v_mov_b32_e32 v12, v11
	s_nop 1
	v_permlane32_swap_b32_e32 v11, v12
	v_add_f32_e32 v11, v11, v12
	v_mul_f32_e32 v11, 0x3c000000, v11
	v_fma_f32 v7, v10, v7, -v11
	v_fma_f32 v8, v9, v8, -v11
	v_mul_f32_e32 v9, v7, v7
	v_fmac_f32_e32 v9, v8, v8
	s_nop 1
	v_add_f32_dpp v9, v9, v9 row_ror:8 row_mask:0xf bank_mask:0xf bound_ctrl:1
	s_nop 1
	v_add_f32_dpp v9, v9, v9 row_ror:4 row_mask:0xf bank_mask:0xf bound_ctrl:1
	s_nop 1
	v_add_f32_dpp v9, v9, v9 row_ror:2 row_mask:0xf bank_mask:0xf bound_ctrl:1
	s_nop 1
	v_add_f32_dpp v9, v9, v9 row_ror:1 row_mask:0xf bank_mask:0xf bound_ctrl:1
	ds_bpermute_b32 v10, v3, v9
	s_waitcnt lgkmcnt(0)
	v_add_f32_e32 v9, v9, v10
	v_mov_b32_e32 v10, v9
	s_nop 1
	v_permlane32_swap_b32_e32 v9, v10
	v_add_f32_e32 v9, v9, v10
	v_fmamk_f32 v9, v9, 0x3c000000, v177
	v_cmp_gt_f32_e32 vcc, s16, v9
	v_mul_f32_e32 v10, 0x4b800000, v9
	s_nop 0
	v_cndmask_b32_e32 v9, v9, v10, vcc
	v_rsq_f32_e32 v9, v9
	s_nop 0
	v_mul_f32_e32 v10, 0x45800000, v9
	v_cndmask_b32_e32 v9, v9, v10, vcc
	v_mul_f32_e32 v8, v8, v9
	v_cvt_pk_bf16_f32 v8, v8, v8
	v_add_u32_e32 v10, s5, v6
	v_mul_f32_e32 v7, v7, v9
	ds_write_b16 v10, v8
	s_add_i32 s5, s5, 2
	v_cvt_pk_bf16_f32 v7, v7, v7
	ds_write_b16 v10, v7 offset:272
	s_ashr_i32 s5, s4, 31
	s_lshl_b64 s[6:7], s[4:5], 15
	v_readlane_b32 s2, v253, 13
	v_ashrrev_i32_e32 v3, 31, v2
	s_add_u32 s6, s2, s6
	v_readlane_b32 s2, v253, 14
	v_lshlrev_b32_e32 v0, 7, v0
	s_addc_u32 s7, s2, s7
	v_lshlrev_b64 v[4:5], 8, v[2:3]
	v_and_b32_e32 v0, 0x80, v0
	v_lshl_add_u64 v[4:5], s[6:7], 0, v[4:5]
	v_mad_u64_u32 v[20:21], s[6:7], v2, s79, v[0:1]
	s_waitcnt lgkmcnt(0)
	s_barrier
	v_lshl_add_u64 v[18:19], v[4:5], 0, v[0:1]
	ds_read_b128 v[2:5], v20
	ds_read_b128 v[6:9], v20 offset:16
	ds_read_b128 v[10:13], v20 offset:32
	ds_read_b128 v[14:17], v20 offset:48
	s_waitcnt lgkmcnt(3)
	global_store_dwordx4 v[18:19], v[2:5], off
	s_waitcnt lgkmcnt(2)
	global_store_dwordx4 v[18:19], v[6:9], off offset:16
	s_waitcnt lgkmcnt(1)
	global_store_dwordx4 v[18:19], v[10:13], off offset:32
	s_waitcnt lgkmcnt(0)
	global_store_dwordx4 v[18:19], v[14:17], off offset:48
	ds_read_b128 v[2:5], v20 offset:64
	s_waitcnt lgkmcnt(0)
	global_store_dwordx4 v[18:19], v[2:5], off offset:64
	ds_read_b128 v[2:5], v20 offset:80
	s_waitcnt lgkmcnt(0)
	global_store_dwordx4 v[18:19], v[2:5], off offset:80
	ds_read_b128 v[2:5], v20 offset:96
	s_waitcnt lgkmcnt(0)
	global_store_dwordx4 v[18:19], v[2:5], off offset:96
	ds_read_b128 v[2:5], v20 offset:112
	s_waitcnt lgkmcnt(0)
	global_store_dwordx4 v[18:19], v[2:5], off offset:112
	s_barrier
	s_branch .LBB0_312

; DI bf16 f2bf(float f) { unsigned u = __float_as_uint(f); u += 0x7fffu + ((u >> 16) & 1u); return (bf16)(u >> 16); }
; DI u32x2 pk4(f32x4 v) { return u32x2{pk2(v[0], v[1]), pk2(v[2], v[3])}; }
; DI void gla_g3_item(const Ctx& c, int l, int item, bf16* lds) {
;     ...
;       qb[i] = qreg[i] * __expf(bv[i]);
;     ...
;       for (int j = 0; j < 4; ++j) {
;         f32x4 a = att[j];
; #pragma unroll
;         for (int r = 0; r < 4; ++r) { const int s_ = 16 * j + 4 * lq + r; if (dir == 0 ? (s_ > t) : (s_ < t)) a[r] = 0.f; }
;         *(u32x2*)(X1 + t * GL + 16 * j + 4 * lq) = pk4(a);
;       }
; #pragma unroll
;       for (int i = 0; i < 16; ++i) X2[(16 * tq + i) * GL + k] = f2bf(qb[i]);
; #pragma unroll
;       for (int i = 0; i < 4; ++i) { const int ci = tid + 256 * i; *(u32x4*)(STs + (ci >> 3) * GL + (ci & 7) * 8) = stg[i]; }
.LBB0_892:
	s_or_b64 exec, exec, vcc
	v_mul_f32_e32 v0, 0x3fb8aa3b, v90
	v_exp_f32_e32 v0, v0
	v_mul_f32_e32 v54, 0x3fb8aa3b, v91
	v_exp_f32_e32 v54, v54
	v_mul_f32_e32 v55, 0x3fb8aa3b, v88
	v_exp_f32_e32 v55, v55
	v_mul_f32_e32 v0, v93, v0
	v_cvt_pk_bf16_f32 v50, v50, v51
	v_cvt_pk_bf16_f32 v51, v52, v53
	v_mul_f32_e32 v56, 0x3fb8aa3b, v89
	ds_write_b64 v139, v[50:51] offset:96
	v_exp_f32_e32 v56, v56
	v_mul_f32_e32 v54, v96, v54
	v_cvt_pk_bf16_f32 v0, v0, v0
	v_mul_f32_e32 v57, 0x3fb8aa3b, v86
	ds_write_b16 v142, v0 offset:9216
	v_bfe_u32 v0, v54, 16, 1
	v_exp_f32_e32 v57, v57
	v_mul_f32_e32 v55, v99, v55
	v_add3_u32 v0, v54, v0, s83
	v_mul_f32_e32 v58, 0x3fb8aa3b, v87
	ds_write_b16_d16_hi v142, v0 offset:9360
	v_bfe_u32 v0, v55, 16, 1
	v_exp_f32_e32 v58, v58
	v_mul_f32_e32 v56, v102, v56
	v_add3_u32 v0, v55, v0, s83
	v_mul_f32_e32 v59, 0x3fb8aa3b, v84
	ds_write_b16_d16_hi v142, v0 offset:9504
	v_bfe_u32 v0, v56, 16, 1
	v_exp_f32_e32 v59, v59
	v_mul_f32_e32 v57, v105, v57
	v_add3_u32 v0, v56, v0, s83
	v_mul_f32_e32 v60, 0x3fb8aa3b, v85
	ds_write_b16_d16_hi v142, v0 offset:9648
	v_bfe_u32 v0, v57, 16, 1
	v_exp_f32_e32 v60, v60
	v_mul_f32_e32 v58, v108, v58
	v_add3_u32 v0, v57, v0, s83
	v_mul_f32_e32 v61, 0x3fb8aa3b, v82
	ds_write_b16_d16_hi v142, v0 offset:9792
	v_bfe_u32 v0, v58, 16, 1
	v_exp_f32_e32 v61, v61
	v_mul_f32_e32 v59, v111, v59
	v_add3_u32 v0, v58, v0, s83
	v_mul_f32_e32 v62, 0x3fb8aa3b, v83
	ds_write_b16_d16_hi v142, v0 offset:9936
	v_bfe_u32 v0, v59, 16, 1
	v_exp_f32_e32 v62, v62
	v_mul_f32_e32 v60, v114, v60
	v_add3_u32 v0, v59, v0, s83
	v_mul_f32_e32 v63, 0x3fb8aa3b, v80
	ds_write_b16_d16_hi v142, v0 offset:10080
	v_bfe_u32 v0, v60, 16, 1
	v_exp_f32_e32 v63, v63
	v_mul_f32_e32 v61, v117, v61
	v_add3_u32 v0, v60, v0, s83
	v_mul_f32_e32 v64, 0x3fb8aa3b, v81
	ds_write_b16_d16_hi v142, v0 offset:10224
	v_bfe_u32 v0, v61, 16, 1
	v_exp_f32_e32 v64, v64
	v_mul_f32_e32 v62, v120, v62
	v_add3_u32 v0, v61, v0, s83
	v_mul_f32_e32 v65, 0x3fb8aa3b, v78
	ds_write_b16_d16_hi v142, v0 offset:10368
	v_bfe_u32 v0, v62, 16, 1
	v_exp_f32_e32 v65, v65
	v_mul_f32_e32 v63, v122, v63
	v_add3_u32 v0, v62, v0, s83
	v_mul_f32_e32 v78, 0x3fb8aa3b, v79
	ds_write_b16_d16_hi v142, v0 offset:10512
	v_bfe_u32 v0, v63, 16, 1
	v_exp_f32_e32 v78, v78
	v_mul_f32_e32 v64, v124, v64
	v_add3_u32 v0, v63, v0, s83
	v_mul_f32_e32 v76, 0x3fb8aa3b, v76
	ds_write_b16_d16_hi v142, v0 offset:10656
	v_bfe_u32 v0, v64, 16, 1
	v_exp_f32_e32 v76, v76
	v_mul_f32_e32 v65, v126, v65
	v_add3_u32 v0, v64, v0, s83
	v_mul_f32_e32 v77, 0x3fb8aa3b, v77
	ds_write_b16_d16_hi v142, v0 offset:10800
	v_bfe_u32 v0, v65, 16, 1
	v_exp_f32_e32 v77, v77
	v_mul_f32_e32 v78, v128, v78
	v_add3_u32 v0, v65, v0, s83
	ds_write_b16_d16_hi v142, v0 offset:10944
	v_bfe_u32 v0, v78, 16, 1
	v_mul_f32_e32 v76, v130, v76
	v_add3_u32 v0, v78, v0, s83
	ds_write_b16_d16_hi v142, v0 offset:11088
	v_bfe_u32 v0, v76, 16, 1
	v_mul_f32_e32 v77, v133, v77
	v_add3_u32 v0, v76, v0, s83
	ds_write_b16_d16_hi v142, v0 offset:11232
	v_bfe_u32 v0, v77, 16, 1
	v_add3_u32 v0, v77, v0, s83
	ds_write_b16_d16_hi v143, v0 offset:9216
	ds_write_b128 v144, v[34:37] offset:36864
	ds_write_b128 v145, v[38:41] offset:36864
	ds_write_b128 v146, v[42:45] offset:36864
	ds_write_b128 v147, v[46:49] offset:36864
	s_waitcnt lgkmcnt(0)
	s_barrier
; #define MFMA16(a, b, c) __builtin_amdgcn_mfma_f32_16x16x32_bf16((a), (b), (c), 0, 0, 0)
; DI void gla_g3_item(const Ctx& c, int l, int item, bf16* lds) {
;     ...
; #pragma unroll
;     for (int kk = 0; kk < 2; ++kk) {
;       const bf16x8 a1 = ldfrag(X1, 16 * wave + l16, kk, lq), a2 = ldfrag(X2, 16 * wave + l16, kk, lq);
; #pragma unroll
;       for (int j = 0; j < 8; ++j) {
;         o[j] = MFMA16(ldfrag(VTs, 16 * j + l16, kk, lq), a1, o[j]);
;         o[j] = MFMA16(ldfrag(STs, 16 * j + l16, kk, lq), a2, o[j]);
;       }
;     }
	ds_read_b128 v[34:37], v140 offset:18432
	v_add_u32_e32 v0, v139, v137
	ds_read_b128 v[38:41], v0
	ds_read_b128 v[42:45], v140 offset:36864
	s_waitcnt lgkmcnt(1)
	v_mfma_f32_16x16x32_bf16 v[30:33], v[34:37], v[38:41], v[30:33]
	ds_read_b128 v[34:37], v0 offset:9216
	ds_read_b128 v[46:49], v141 offset:18432
	s_mov_b32 s76, 1
	s_and_b64 vcc, exec, s[70:71]
	s_waitcnt lgkmcnt(0)
	v_mfma_f32_16x16x32_bf16 v[26:29], v[46:49], v[38:41], v[26:29]
	ds_read_b128 v[46:49], v148 offset:23040
	s_mov_b64 s[70:71], 0
	v_mfma_f32_16x16x32_bf16 v[30:33], v[42:45], v[34:37], v[30:33]
	ds_read_b128 v[42:45], v141 offset:36864
	s_waitcnt lgkmcnt(1)
	v_mfma_f32_16x16x32_bf16 v[22:25], v[46:49], v[38:41], v[22:25]
	ds_read_b128 v[46:49], v148 offset:25344
	s_waitcnt lgkmcnt(0)
	v_mfma_f32_16x16x32_bf16 v[18:21], v[46:49], v[38:41], v[18:21]
	ds_read_b128 v[46:49], v140 offset:27648
	v_mfma_f32_16x16x32_bf16 v[26:29], v[42:45], v[34:37], v[26:29]
	ds_read_b128 v[42:45], v148 offset:41472
	s_waitcnt lgkmcnt(1)
	v_mfma_f32_16x16x32_bf16 v[14:17], v[46:49], v[38:41], v[14:17]
	ds_read_b128 v[46:49], v140 offset:29952
	s_waitcnt lgkmcnt(1)
	v_mfma_f32_16x16x32_bf16 v[22:25], v[42:45], v[34:37], v[22:25]
	ds_read_b128 v[42:45], v148 offset:43776
	s_waitcnt lgkmcnt(1)
	v_mfma_f32_16x16x32_bf16 v[10:13], v[46:49], v[38:41], v[10:13]
	ds_read_b128 v[46:49], v140 offset:32256
	s_waitcnt lgkmcnt(1)
	v_mfma_f32_16x16x32_bf16 v[18:21], v[42:45], v[34:37], v[18:21]
	ds_read_b128 v[42:45], v140 offset:46080
	s_waitcnt lgkmcnt(1)
	v_mfma_f32_16x16x32_bf16 v[6:9], v[46:49], v[38:41], v[6:9]
	ds_read_b128 v[46:49], v140 offset:34560
	s_waitcnt lgkmcnt(1)
	v_mfma_f32_16x16x32_bf16 v[14:17], v[42:45], v[34:37], v[14:17]
	ds_read_b128 v[42:45], v140 offset:48384
	s_waitcnt lgkmcnt(0)
	v_mfma_f32_16x16x32_bf16 v[10:13], v[42:45], v[34:37], v[10:13]
	ds_read_b128 v[42:45], v140 offset:50688
	s_waitcnt lgkmcnt(0)
	v_mfma_f32_16x16x32_bf16 v[6:9], v[42:45], v[34:37], v[6:9]
	ds_read_b128 v[42:45], v140 offset:52992
	v_mfma_f32_16x16x32_bf16 v[2:5], v[46:49], v[38:41], v[2:5]
	ds_read_b128 v[38:41], v140 offset:18496
	ds_read_b128 v[46:49], v0 offset:64
	s_waitcnt lgkmcnt(2)
	v_mfma_f32_16x16x32_bf16 v[2:5], v[42:45], v[34:37], v[2:5]
	ds_read_b128 v[34:37], v140 offset:36928
	s_waitcnt lgkmcnt(1)
	v_mfma_f32_16x16x32_bf16 v[30:33], v[38:41], v[46:49], v[30:33]
	ds_read_b128 v[38:41], v0 offset:9280
	s_waitcnt lgkmcnt(0)
	v_mfma_f32_16x16x32_bf16 v[30:33], v[34:37], v[38:41], v[30:33]
	ds_read_b128 v[34:37], v141 offset:18496
	s_waitcnt lgkmcnt(0)
	v_mfma_f32_16x16x32_bf16 v[26:29], v[34:37], v[46:49], v[26:29]
	ds_read_b128 v[34:37], v141 offset:36928
	s_waitcnt lgkmcnt(0)
	v_mfma_f32_16x16x32_bf16 v[26:29], v[34:37], v[38:41], v[26:29]
	ds_read_b128 v[34:37], v148 offset:23104
	s_waitcnt lgkmcnt(0)
	v_mfma_f32_16x16x32_bf16 v[22:25], v[34:37], v[46:49], v[22:25]
	ds_read_b128 v[34:37], v148 offset:41536
	s_waitcnt lgkmcnt(0)
	v_mfma_f32_16x16x32_bf16 v[22:25], v[34:37], v[38:41], v[22:25]
	ds_read_b128 v[34:37], v148 offset:25408
	s_waitcnt lgkmcnt(0)
	v_mfma_f32_16x16x32_bf16 v[18:21], v[34:37], v[46:49], v[18:21]
	ds_read_b128 v[34:37], v148 offset:43840
	s_waitcnt lgkmcnt(0)
	v_mfma_f32_16x16x32_bf16 v[18:21], v[34:37], v[38:41], v[18:21]
	ds_read_b128 v[34:37], v140 offset:27712
	s_waitcnt lgkmcnt(0)
	v_mfma_f32_16x16x32_bf16 v[14:17], v[34:37], v[46:49], v[14:17]
	ds_read_b128 v[34:37], v140 offset:46144
	s_waitcnt lgkmcnt(0)
	v_mfma_f32_16x16x32_bf16 v[14:17], v[34:37], v[38:41], v[14:17]
	ds_read_b128 v[34:37], v140 offset:30016
	s_waitcnt lgkmcnt(0)
	v_mfma_f32_16x16x32_bf16 v[10:13], v[34:37], v[46:49], v[10:13]
	ds_read_b128 v[34:37], v140 offset:48448
	s_waitcnt lgkmcnt(0)
	v_mfma_f32_16x16x32_bf16 v[10:13], v[34:37], v[38:41], v[10:13]
	ds_read_b128 v[34:37], v140 offset:32320
	s_waitcnt lgkmcnt(0)
	v_mfma_f32_16x16x32_bf16 v[6:9], v[34:37], v[46:49], v[6:9]
	ds_read_b128 v[34:37], v140 offset:50752
	s_waitcnt lgkmcnt(0)
	v_mfma_f32_16x16x32_bf16 v[6:9], v[34:37], v[38:41], v[6:9]
	ds_read_b128 v[34:37], v140 offset:34624
	s_waitcnt lgkmcnt(0)
	v_mfma_f32_16x16x32_bf16 v[2:5], v[34:37], v[46:49], v[2:5]
	ds_read_b128 v[34:37], v140 offset:53056
	s_waitcnt lgkmcnt(0)
	s_barrier
	v_mfma_f32_16x16x32_bf16 v[2:5], v[34:37], v[38:41], v[2:5]
	s_cbranch_vccz .LBB0_997

; DI bf16 f2bf(float f) { unsigned u = __float_as_uint(f); u += 0x7fffu + ((u >> 16) & 1u); return (bf16)(u >> 16); }
; DI void gla_g3_item(const Ctx& c, int l, int item, bf16* lds) {
;     ...
;     float qb[16];
; #pragma unroll
;     for (int i = 0; i < 16; ++i) {
;       X1[(16 * tq + i) * GL + k] = f2bf(qreg[i] * __expf(bv[i] - bmid));
;       X2[(16 * tq + i) * GL + k] = f2bf(kreg[i] * __expf(bmid - bv[i]));
;       qb[i] = qreg[i] * __expf(bv[i]);
;     }
;     __syncthreads();
.LBB0_901:
	s_nop 0
	v_pk_add_f32 v[90:91], v[86:87], v[50:51] op_sel_hi:[1,0]
	v_pk_add_f32 v[88:89], v[84:85], v[50:51] op_sel_hi:[1,0]
	v_sub_f32_e32 v0, v90, v51
	v_mul_f32_e32 v0, 0x3fb8aa3b, v0
	v_exp_f32_e32 v0, v0
	v_pk_add_f32 v[86:87], v[82:83], v[50:51] op_sel_hi:[1,0]
	v_pk_add_f32 v[84:85], v[60:61], v[50:51] op_sel_hi:[1,0]
	v_pk_add_f32 v[82:83], v[58:59], v[50:51] op_sel_hi:[1,0]
	v_mul_f32_e32 v0, v93, v0
	v_pk_add_f32 v[80:81], v[56:57], v[50:51] op_sel_hi:[1,0]
	v_pk_add_f32 v[78:79], v[54:55], v[50:51] op_sel_hi:[1,0]
	v_pk_add_f32 v[76:77], v[52:53], v[50:51] op_sel_hi:[1,0]
	v_cvt_pk_bf16_f32 v0, v0, v0
	s_waitcnt lgkmcnt(0)
	s_barrier
	ds_write_b16 v92, v0
	v_sub_f32_e32 v0, v51, v90
	v_mul_f32_e32 v0, 0x3fb8aa3b, v0
	v_exp_f32_e32 v0, v0
	s_and_b64 vcc, exec, s[76:77]
	v_mul_f32_e32 v0, v0, v94
	v_cvt_pk_bf16_f32 v0, v0, v0
	ds_write_b16 v92, v0 offset:9216
	v_sub_f32_e32 v0, v91, v51
	v_mul_f32_e32 v0, 0x3fb8aa3b, v0
	v_exp_f32_e32 v0, v0
	s_nop 0
	v_mul_f32_e32 v0, v96, v0
	v_cvt_pk_bf16_f32 v0, v0, v0
	ds_write_b16 v95, v0
	v_sub_f32_e32 v0, v51, v91
	v_mul_f32_e32 v0, 0x3fb8aa3b, v0
	v_exp_f32_e32 v0, v0
	s_nop 0
	v_mul_f32_e32 v0, v0, v97
	v_cvt_pk_bf16_f32 v0, v0, v0
	ds_write_b16 v95, v0 offset:9216
	v_sub_f32_e32 v0, v88, v51
	v_mul_f32_e32 v0, 0x3fb8aa3b, v0
	v_exp_f32_e32 v0, v0
	s_nop 0
	v_mul_f32_e32 v0, v99, v0
	v_cvt_pk_bf16_f32 v0, v0, v0
	ds_write_b16 v98, v0
	v_sub_f32_e32 v0, v51, v88
	v_mul_f32_e32 v0, 0x3fb8aa3b, v0
	v_exp_f32_e32 v0, v0
	s_nop 0
	v_mul_f32_e32 v0, v0, v100
	v_cvt_pk_bf16_f32 v0, v0, v0
	ds_write_b16 v98, v0 offset:9216
	v_sub_f32_e32 v0, v89, v51
	v_mul_f32_e32 v0, 0x3fb8aa3b, v0
	v_exp_f32_e32 v0, v0
	s_nop 0
	v_mul_f32_e32 v0, v102, v0
	v_cvt_pk_bf16_f32 v0, v0, v0
	ds_write_b16 v101, v0
	v_sub_f32_e32 v0, v51, v89
	v_mul_f32_e32 v0, 0x3fb8aa3b, v0
	v_exp_f32_e32 v0, v0
	s_nop 0
	v_mul_f32_e32 v0, v0, v103
	v_cvt_pk_bf16_f32 v0, v0, v0
	ds_write_b16 v101, v0 offset:9216
	v_sub_f32_e32 v0, v86, v51
	v_mul_f32_e32 v0, 0x3fb8aa3b, v0
	v_exp_f32_e32 v0, v0
	s_nop 0
	v_mul_f32_e32 v0, v105, v0
	v_cvt_pk_bf16_f32 v0, v0, v0
	ds_write_b16 v104, v0
	v_sub_f32_e32 v0, v51, v86
	v_mul_f32_e32 v0, 0x3fb8aa3b, v0
	v_exp_f32_e32 v0, v0
	s_nop 0
	v_mul_f32_e32 v0, v0, v106
	v_cvt_pk_bf16_f32 v0, v0, v0
	ds_write_b16 v104, v0 offset:9216
	v_sub_f32_e32 v0, v87, v51
	v_mul_f32_e32 v0, 0x3fb8aa3b, v0
	v_exp_f32_e32 v0, v0
	s_nop 0
	v_mul_f32_e32 v0, v108, v0
	v_cvt_pk_bf16_f32 v0, v0, v0
	ds_write_b16 v107, v0
	v_sub_f32_e32 v0, v51, v87
	v_mul_f32_e32 v0, 0x3fb8aa3b, v0
	v_exp_f32_e32 v0, v0
	s_nop 0
	v_mul_f32_e32 v0, v0, v109
	v_cvt_pk_bf16_f32 v0, v0, v0
	ds_write_b16 v107, v0 offset:9216
	v_sub_f32_e32 v0, v84, v51
	v_mul_f32_e32 v0, 0x3fb8aa3b, v0
	v_exp_f32_e32 v0, v0
	s_nop 0
	v_mul_f32_e32 v0, v111, v0
	v_cvt_pk_bf16_f32 v0, v0, v0
	ds_write_b16 v110, v0
	v_sub_f32_e32 v0, v51, v84
	v_mul_f32_e32 v0, 0x3fb8aa3b, v0
	v_exp_f32_e32 v0, v0
	s_nop 0
	v_mul_f32_e32 v0, v0, v112
	v_cvt_pk_bf16_f32 v0, v0, v0
	ds_write_b16 v110, v0 offset:9216
	v_sub_f32_e32 v0, v85, v51
	v_mul_f32_e32 v0, 0x3fb8aa3b, v0
	v_exp_f32_e32 v0, v0
	s_nop 0
	v_mul_f32_e32 v0, v114, v0
	v_cvt_pk_bf16_f32 v0, v0, v0
	ds_write_b16 v113, v0
	v_sub_f32_e32 v0, v51, v85
	v_mul_f32_e32 v0, 0x3fb8aa3b, v0
	v_exp_f32_e32 v0, v0
	s_nop 0
	v_mul_f32_e32 v0, v0, v115
	v_cvt_pk_bf16_f32 v0, v0, v0
	ds_write_b16 v113, v0 offset:9216
	v_sub_f32_e32 v0, v82, v51
	v_mul_f32_e32 v0, 0x3fb8aa3b, v0
	v_exp_f32_e32 v0, v0
	s_nop 0
	v_mul_f32_e32 v0, v117, v0
	v_cvt_pk_bf16_f32 v0, v0, v0
	ds_write_b16 v116, v0
	v_sub_f32_e32 v0, v51, v82
	v_mul_f32_e32 v0, 0x3fb8aa3b, v0
	v_exp_f32_e32 v0, v0
	s_nop 0
	v_mul_f32_e32 v0, v0, v118
	v_cvt_pk_bf16_f32 v0, v0, v0
	ds_write_b16 v116, v0 offset:9216
	v_sub_f32_e32 v0, v83, v51
	v_mul_f32_e32 v0, 0x3fb8aa3b, v0
	v_exp_f32_e32 v0, v0
	s_nop 0
	v_mul_f32_e32 v0, v120, v0
	v_cvt_pk_bf16_f32 v0, v0, v0
	ds_write_b16 v119, v0
	v_sub_f32_e32 v0, v51, v83
	v_mul_f32_e32 v0, 0x3fb8aa3b, v0
	v_exp_f32_e32 v0, v0
	s_nop 0
	v_mul_f32_e32 v0, v0, v121
	v_cvt_pk_bf16_f32 v0, v0, v0
	ds_write_b16 v119, v0 offset:9216
	v_sub_f32_e32 v0, v80, v51
	v_mul_f32_e32 v0, 0x3fb8aa3b, v0
	v_exp_f32_e32 v0, v0
	s_nop 0
	v_mul_f32_e32 v0, v122, v0
	v_cvt_pk_bf16_f32 v0, v0, v0
	ds_write_b16 v119, v0 offset:144
	v_sub_f32_e32 v0, v51, v80
	v_mul_f32_e32 v0, 0x3fb8aa3b, v0
	v_exp_f32_e32 v0, v0
	s_nop 0
	v_mul_f32_e32 v0, v0, v123
	v_cvt_pk_bf16_f32 v0, v0, v0
	ds_write_b16 v119, v0 offset:9360
	v_sub_f32_e32 v0, v81, v51
	v_mul_f32_e32 v0, 0x3fb8aa3b, v0
	v_exp_f32_e32 v0, v0
	s_nop 0
	v_mul_f32_e32 v0, v124, v0
	v_cvt_pk_bf16_f32 v0, v0, v0
	ds_write_b16 v119, v0 offset:288
	v_sub_f32_e32 v0, v51, v81
	v_mul_f32_e32 v0, 0x3fb8aa3b, v0
	v_exp_f32_e32 v0, v0
	s_nop 0
	v_mul_f32_e32 v0, v0, v125
	v_cvt_pk_bf16_f32 v0, v0, v0
	ds_write_b16 v119, v0 offset:9504
	v_sub_f32_e32 v0, v78, v51
	v_mul_f32_e32 v0, 0x3fb8aa3b, v0
	v_exp_f32_e32 v0, v0
	s_nop 0
	v_mul_f32_e32 v0, v126, v0
	v_cvt_pk_bf16_f32 v0, v0, v0
	ds_write_b16 v119, v0 offset:432
	v_sub_f32_e32 v0, v51, v78
	v_mul_f32_e32 v0, 0x3fb8aa3b, v0
	v_exp_f32_e32 v0, v0
	s_nop 0
	v_mul_f32_e32 v0, v0, v127
	v_cvt_pk_bf16_f32 v0, v0, v0
	ds_write_b16 v119, v0 offset:9648
	v_sub_f32_e32 v0, v79, v51
	v_mul_f32_e32 v0, 0x3fb8aa3b, v0
	v_exp_f32_e32 v0, v0
	s_nop 0
	v_mul_f32_e32 v0, v128, v0
	v_cvt_pk_bf16_f32 v0, v0, v0
	ds_write_b16 v119, v0 offset:576
	v_sub_f32_e32 v0, v51, v79
	v_mul_f32_e32 v0, 0x3fb8aa3b, v0
	v_exp_f32_e32 v0, v0
	s_nop 0
	v_mul_f32_e32 v0, v0, v129
	v_cvt_pk_bf16_f32 v0, v0, v0
	ds_write_b16 v119, v0 offset:9792
	v_sub_f32_e32 v0, v76, v51
	v_mul_f32_e32 v0, 0x3fb8aa3b, v0
	v_exp_f32_e32 v0, v0
	s_nop 0
	v_mul_f32_e32 v0, v130, v0
	v_cvt_pk_bf16_f32 v0, v0, v0
	ds_write_b16 v119, v0 offset:720
	v_sub_f32_e32 v0, v51, v76
	v_mul_f32_e32 v0, 0x3fb8aa3b, v0
	v_exp_f32_e32 v0, v0
	s_nop 0
	v_mul_f32_e32 v0, v0, v131
	v_cvt_pk_bf16_f32 v0, v0, v0
	ds_write_b16 v119, v0 offset:9936
	v_sub_f32_e32 v0, v77, v51
	v_mul_f32_e32 v0, 0x3fb8aa3b, v0
	v_exp_f32_e32 v0, v0
	s_nop 0
	v_mul_f32_e32 v0, v133, v0
	v_cvt_pk_bf16_f32 v0, v0, v0
	ds_write_b16 v132, v0
	v_sub_f32_e32 v0, v51, v77
	v_mul_f32_e32 v0, 0x3fb8aa3b, v0
	v_exp_f32_e32 v0, v0
	s_nop 0
	v_mul_f32_e32 v0, v0, v134
	v_bfe_u32 v50, v0, 16, 1
	v_add3_u32 v0, v0, v50, s83
	ds_write_b16_d16_hi v132, v0 offset:9216
	s_waitcnt lgkmcnt(0)
	s_barrier
; #define MFMA16(a, b, c) __builtin_amdgcn_mfma_f32_16x16x32_bf16((a), (b), (c), 0, 0, 0)
; DI void gla_g3_item(const Ctx& c, int l, int item, bf16* lds) {
;     ...
;     f32x4 att[4];
; #pragma unroll
;     for (int j = 0; j < 4; ++j) att[j] = f32x4{0.f, 0.f, 0.f, 0.f};
; #pragma unroll
;     for (int kk = 0; kk < 2; ++kk) {
;       const bf16x8 af = ldfrag(X1, 16 * wave + l16, kk, lq);
; #pragma unroll
;       for (int j = 0; j < 4; ++j) att[j] = MFMA16(ldfrag(X2, 16 * j + l16, kk, lq), af, att[j]);
;     }
	ds_read_b128 v[50:53], v138
	ds_read_b128 v[54:57], v148 offset:9216
	ds_read_b128 v[58:61], v148 offset:11520
	ds_read_b128 v[62:65], v148 offset:13824
	s_waitcnt lgkmcnt(0)
	v_mfma_f32_16x16x32_bf16 v[150:153], v[62:65], v[50:53], 0
	ds_read_b128 v[62:65], v148 offset:16128
	v_mfma_f32_16x16x32_bf16 v[54:57], v[54:57], v[50:53], 0
	v_mfma_f32_16x16x32_bf16 v[58:61], v[58:61], v[50:53], 0
	s_waitcnt lgkmcnt(0)
	v_mfma_f32_16x16x32_bf16 v[50:53], v[62:65], v[50:53], 0
	ds_read_b128 v[154:157], v138 offset:64
	ds_read_b128 v[62:65], v148 offset:9280
	s_waitcnt lgkmcnt(0)
	v_mfma_f32_16x16x32_bf16 v[62:65], v[62:65], v[154:157], v[54:57]
	s_nop 2
	ds_read_b128 v[54:57], v148 offset:11584
	s_waitcnt lgkmcnt(0)
	v_mfma_f32_16x16x32_bf16 v[58:61], v[54:57], v[154:157], v[58:61]
	ds_read_b128 v[54:57], v148 offset:13888
	s_waitcnt lgkmcnt(0)
	v_mfma_f32_16x16x32_bf16 v[54:57], v[54:57], v[154:157], v[150:153]
	s_nop 2
	ds_read_b128 v[150:153], v148 offset:16192
	s_waitcnt lgkmcnt(0)
	s_barrier
	v_mfma_f32_16x16x32_bf16 v[50:53], v[150:153], v[154:157], v[50:53]
	s_cbranch_vccz .LBB0_903
	s_and_b64 s[70:71], s[90:91], exec
	s_cbranch_execz .LBB0_904
	s_branch .LBB0_905
